# LDS-DMA loads in the K-loops use SGPR base + 32-bit VGPR offset (no 64-bit VALU address adds); on top of interleaved accumulate pairs
# speedup vs baseline: 1.0176x; 1.0038x over previous
.LBB0_296:
	s_ashr_i32 s23, s22, 31
	s_lshl_b64 s[56:57], s[22:23], 21
	s_add_u32 s72, s2, s56
	s_addc_u32 s73, s3, s57
	s_and_b64 s[56:57], s[4:5], exec
	s_cselect_b32 s23, s73, s81
	s_cselect_b32 s56, s72, s80
	s_ashr_i32 s21, s20, 31
	s_lshl_b64 s[60:61], s[20:21], 20
	s_add_u32 s74, s14, s60
	s_addc_u32 s75, s15, s61
	s_and_b64 s[60:61], s[4:5], exec
	s_cselect_b32 s21, s75, s83
	s_cselect_b32 s57, s74, s82
	s_add_u32 s80, s80, 0x100080
	s_addc_u32 s81, s81, 0
	s_add_u32 s60, s82, 0x100
	s_addc_u32 s61, s83, 0
	s_mov_b32 s68, -2
	s_add_u32 s67, s80, 0xfff00080
	s_addc_u32 s69, s81, -1
	s_add_i32 s70, 0, 0x10000
	s_cmp_eq_u32 s68, 28
	s_cselect_b32 s85, s23, s69
	s_cselect_b32 s84, s56, s67
	s_cselect_b32 s83, s21, s61
	s_cselect_b32 s82, s57, s60
	s_add_i32 s67, 0, 0x14000
	v_add_u32_e32 v140, s70, v168
	v_add_u32_e32 v166, s67, v168
	ds_read_b128 v[80:83], v140
	ds_read_b128 v[116:119], v140 offset:1024
	ds_read_b128 v[136:139], v140 offset:2048
	ds_read_b128 v[140:143], v140 offset:3072
	ds_read_b128 v[158:161], v166
	ds_read_b128 v[162:165], v166 offset:1024
	ds_read_b128 v[170:173], v166 offset:2048
	ds_read_b128 v[174:177], v166 offset:3072
	s_add_i32 m0, s26, 0xc000
	ds_read_b128 v[178:181], v169
	ds_read_b128 v[182:185], v169 offset:1024
	ds_read_b128 v[186:189], v169 offset:2048
	ds_read_b128 v[190:193], v169 offset:3072
	ds_read_b128 v[194:197], v169 offset:4096
	ds_read_b128 v[198:201], v169 offset:5120
	ds_read_b128 v[202:205], v169 offset:6144
	ds_read_b128 v[206:209], v169 offset:7168
	global_load_lds_dwordx4 v154, s[80:81]
	s_add_i32 m0, s26, 0xe000
	s_nop 0
	global_load_lds_dwordx4 v156, s[80:81]
	s_waitcnt vmcnt(8)
	s_waitcnt lgkmcnt(0)
	s_barrier
	s_waitcnt lgkmcnt(0)
	v_mfma_f32_16x16x32_bf16 v[132:135], v[80:83], v[178:181], 0
	v_mfma_f32_16x16x32_bf16 v[132:135], v[116:119], v[182:185], v[132:135]
	v_mfma_f32_16x16x32_bf16 v[124:127], v[158:161], v[178:181], 0
	v_mfma_f32_16x16x32_bf16 v[124:127], v[162:165], v[182:185], v[124:127]
	v_mfma_f32_16x16x32_bf16 v[128:131], v[136:139], v[178:181], 0
	v_mfma_f32_16x16x32_bf16 v[128:131], v[140:143], v[182:185], v[128:131]
	v_mfma_f32_16x16x32_bf16 v[120:123], v[170:173], v[178:181], 0
	v_mfma_f32_16x16x32_bf16 v[120:123], v[174:177], v[182:185], v[120:123]
	v_mfma_f32_16x16x32_bf16 v[112:115], v[80:83], v[186:189], 0
	v_mfma_f32_16x16x32_bf16 v[112:115], v[116:119], v[190:193], v[112:115]
	v_mfma_f32_16x16x32_bf16 v[104:107], v[158:161], v[186:189], 0
	v_mfma_f32_16x16x32_bf16 v[104:107], v[162:165], v[190:193], v[104:107]
	v_mfma_f32_16x16x32_bf16 v[108:111], v[136:139], v[186:189], 0
	v_mfma_f32_16x16x32_bf16 v[108:111], v[140:143], v[190:193], v[108:111]
	v_mfma_f32_16x16x32_bf16 v[100:103], v[170:173], v[186:189], 0
	v_mfma_f32_16x16x32_bf16 v[100:103], v[174:177], v[190:193], v[100:103]
	v_mfma_f32_16x16x32_bf16 v[96:99], v[80:83], v[194:197], 0
	v_mfma_f32_16x16x32_bf16 v[96:99], v[116:119], v[198:201], v[96:99]
	v_mfma_f32_16x16x32_bf16 v[88:91], v[158:161], v[194:197], 0
	v_mfma_f32_16x16x32_bf16 v[88:91], v[162:165], v[198:201], v[88:91]
	v_mfma_f32_16x16x32_bf16 v[92:95], v[136:139], v[194:197], 0
	v_mfma_f32_16x16x32_bf16 v[92:95], v[140:143], v[198:201], v[92:95]
	v_mfma_f32_16x16x32_bf16 v[84:87], v[170:173], v[194:197], 0
	v_mfma_f32_16x16x32_bf16 v[84:87], v[174:177], v[198:201], v[84:87]
	v_mfma_f32_16x16x32_bf16 v[76:79], v[80:83], v[202:205], 0
	v_mfma_f32_16x16x32_bf16 v[76:79], v[116:119], v[206:209], v[76:79]
	v_mfma_f32_16x16x32_bf16 v[68:71], v[158:161], v[202:205], 0
	v_mfma_f32_16x16x32_bf16 v[68:71], v[162:165], v[206:209], v[68:71]
	v_mfma_f32_16x16x32_bf16 v[72:75], v[136:139], v[202:205], 0
	v_mfma_f32_16x16x32_bf16 v[72:75], v[140:143], v[206:209], v[72:75]
	v_mfma_f32_16x16x32_bf16 v[64:67], v[170:173], v[202:205], 0
	v_mfma_f32_16x16x32_bf16 v[64:67], v[174:177], v[206:209], v[64:67]
	s_barrier
	s_add_i32 s69, s70, s24
	s_mov_b32 m0, s69
	ds_read_b128 v[178:181], v169 offset:16384
	ds_read_b128 v[182:185], v169 offset:17408
	ds_read_b128 v[186:189], v169 offset:18432
	ds_read_b128 v[190:193], v169 offset:19456
	ds_read_b128 v[194:197], v169 offset:20480
	ds_read_b128 v[198:201], v169 offset:21504
	ds_read_b128 v[202:205], v169 offset:22528
	ds_read_b128 v[206:209], v169 offset:23552
	global_load_lds_dwordx4 v146, s[82:83]
	s_add_i32 m0, s69, 0x2000
	s_add_u32 s70, s82, 0x80000
	s_addc_u32 s71, s83, 0
	s_add_i32 s67, s67, s24
	global_load_lds_dwordx4 v150, s[82:83]
	s_mov_b32 m0, s67
	s_nop 0
	global_load_lds_dwordx4 v146, s[70:71]
	s_add_i32 m0, s67, 0x2000
	s_nop 0
	global_load_lds_dwordx4 v150, s[70:71]
	s_mov_b32 m0, s26
	s_nop 0
	global_load_lds_dwordx4 v144, s[84:85]
	s_mov_b32 m0, s28
	s_nop 0
	global_load_lds_dwordx4 v148, s[84:85]
	s_waitcnt vmcnt(8)
	s_waitcnt lgkmcnt(0)
	s_barrier
	s_waitcnt lgkmcnt(0)
	v_mfma_f32_16x16x32_bf16 v[60:63], v[80:83], v[178:181], 0
	v_mfma_f32_16x16x32_bf16 v[60:63], v[116:119], v[182:185], v[60:63]
	v_mfma_f32_16x16x32_bf16 v[52:55], v[158:161], v[178:181], 0
	v_mfma_f32_16x16x32_bf16 v[52:55], v[162:165], v[182:185], v[52:55]
	v_mfma_f32_16x16x32_bf16 v[56:59], v[136:139], v[178:181], 0
	v_mfma_f32_16x16x32_bf16 v[56:59], v[140:143], v[182:185], v[56:59]
	v_mfma_f32_16x16x32_bf16 v[48:51], v[170:173], v[178:181], 0
	v_mfma_f32_16x16x32_bf16 v[48:51], v[174:177], v[182:185], v[48:51]
	v_mfma_f32_16x16x32_bf16 v[44:47], v[80:83], v[186:189], 0
	v_mfma_f32_16x16x32_bf16 v[44:47], v[116:119], v[190:193], v[44:47]
	v_mfma_f32_16x16x32_bf16 v[36:39], v[158:161], v[186:189], 0
	v_mfma_f32_16x16x32_bf16 v[36:39], v[162:165], v[190:193], v[36:39]
	v_mfma_f32_16x16x32_bf16 v[40:43], v[136:139], v[186:189], 0
	v_mfma_f32_16x16x32_bf16 v[40:43], v[140:143], v[190:193], v[40:43]
	v_mfma_f32_16x16x32_bf16 v[32:35], v[170:173], v[186:189], 0
	v_mfma_f32_16x16x32_bf16 v[32:35], v[174:177], v[190:193], v[32:35]
	v_mfma_f32_16x16x32_bf16 v[28:31], v[80:83], v[194:197], 0
	v_mfma_f32_16x16x32_bf16 v[28:31], v[116:119], v[198:201], v[28:31]
	v_mfma_f32_16x16x32_bf16 v[20:23], v[158:161], v[194:197], 0
	v_mfma_f32_16x16x32_bf16 v[20:23], v[162:165], v[198:201], v[20:23]
	v_mfma_f32_16x16x32_bf16 v[24:27], v[136:139], v[194:197], 0
	v_mfma_f32_16x16x32_bf16 v[24:27], v[140:143], v[198:201], v[24:27]
	v_mfma_f32_16x16x32_bf16 v[16:19], v[170:173], v[194:197], 0
	v_mfma_f32_16x16x32_bf16 v[16:19], v[174:177], v[198:201], v[16:19]
	v_mfma_f32_16x16x32_bf16 v[12:15], v[80:83], v[202:205], 0
	v_mfma_f32_16x16x32_bf16 v[12:15], v[116:119], v[206:209], v[12:15]
	v_mfma_f32_16x16x32_bf16 v[4:7], v[158:161], v[202:205], 0
	v_mfma_f32_16x16x32_bf16 v[4:7], v[162:165], v[206:209], v[4:7]
	v_mfma_f32_16x16x32_bf16 v[8:11], v[136:139], v[202:205], 0
	v_mfma_f32_16x16x32_bf16 v[8:11], v[140:143], v[206:209], v[8:11]
	v_mfma_f32_16x16x32_bf16 v[0:3], v[170:173], v[202:205], 0
	v_mfma_f32_16x16x32_bf16 v[0:3], v[174:177], v[206:209], v[0:3]
	s_barrier
	s_add_i32 s67, 0, 0x18000
	s_add_i32 s69, 0, 0x1c000
	v_add_u32_e32 v140, s67, v168
	v_add_u32_e32 v174, s69, v168
	ds_read_b128 v[80:83], v140
	ds_read_b128 v[116:119], v140 offset:1024
	ds_read_b128 v[136:139], v140 offset:2048
	ds_read_b128 v[140:143], v140 offset:3072
	ds_read_b128 v[158:161], v174
	ds_read_b128 v[162:165], v174 offset:1024
	ds_read_b128 v[170:173], v174 offset:2048
	ds_read_b128 v[174:177], v174 offset:3072
	s_add_u32 s70, s84, 0x100000
	s_addc_u32 s71, s85, 0
	s_mov_b32 m0, s29
	ds_read_b128 v[178:181], v169 offset:32768
	ds_read_b128 v[182:185], v169 offset:33792
	ds_read_b128 v[186:189], v169 offset:34816
	ds_read_b128 v[190:193], v169 offset:35840
	ds_read_b128 v[194:197], v169 offset:36864
	ds_read_b128 v[198:201], v169 offset:37888
	ds_read_b128 v[202:205], v169 offset:38912
	ds_read_b128 v[206:209], v169 offset:39936
	global_load_lds_dwordx4 v144, s[70:71]
	s_mov_b32 m0, s34
	s_nop 0
	global_load_lds_dwordx4 v148, s[70:71]
	s_waitcnt vmcnt(8)
	s_waitcnt lgkmcnt(0)
	s_barrier
	s_waitcnt lgkmcnt(0)
	v_mfma_f32_16x16x32_bf16 v[132:135], v[80:83], v[178:181], v[132:135]
	v_mfma_f32_16x16x32_bf16 v[132:135], v[116:119], v[182:185], v[132:135]
	v_mfma_f32_16x16x32_bf16 v[124:127], v[158:161], v[178:181], v[124:127]
	v_mfma_f32_16x16x32_bf16 v[124:127], v[162:165], v[182:185], v[124:127]
	v_mfma_f32_16x16x32_bf16 v[128:131], v[136:139], v[178:181], v[128:131]
	v_mfma_f32_16x16x32_bf16 v[128:131], v[140:143], v[182:185], v[128:131]
	v_mfma_f32_16x16x32_bf16 v[120:123], v[170:173], v[178:181], v[120:123]
	v_mfma_f32_16x16x32_bf16 v[120:123], v[174:177], v[182:185], v[120:123]
	v_mfma_f32_16x16x32_bf16 v[112:115], v[80:83], v[186:189], v[112:115]
	v_mfma_f32_16x16x32_bf16 v[112:115], v[116:119], v[190:193], v[112:115]
	v_mfma_f32_16x16x32_bf16 v[104:107], v[158:161], v[186:189], v[104:107]
	v_mfma_f32_16x16x32_bf16 v[104:107], v[162:165], v[190:193], v[104:107]
	v_mfma_f32_16x16x32_bf16 v[108:111], v[136:139], v[186:189], v[108:111]
	v_mfma_f32_16x16x32_bf16 v[108:111], v[140:143], v[190:193], v[108:111]
	v_mfma_f32_16x16x32_bf16 v[100:103], v[170:173], v[186:189], v[100:103]
	v_mfma_f32_16x16x32_bf16 v[100:103], v[174:177], v[190:193], v[100:103]
	v_mfma_f32_16x16x32_bf16 v[96:99], v[80:83], v[194:197], v[96:99]
	v_mfma_f32_16x16x32_bf16 v[96:99], v[116:119], v[198:201], v[96:99]
	v_mfma_f32_16x16x32_bf16 v[88:91], v[158:161], v[194:197], v[88:91]
	v_mfma_f32_16x16x32_bf16 v[88:91], v[162:165], v[198:201], v[88:91]
	v_mfma_f32_16x16x32_bf16 v[92:95], v[136:139], v[194:197], v[92:95]
	v_mfma_f32_16x16x32_bf16 v[92:95], v[140:143], v[198:201], v[92:95]
	v_mfma_f32_16x16x32_bf16 v[84:87], v[170:173], v[194:197], v[84:87]
	v_mfma_f32_16x16x32_bf16 v[84:87], v[174:177], v[198:201], v[84:87]
	v_mfma_f32_16x16x32_bf16 v[76:79], v[80:83], v[202:205], v[76:79]
	v_mfma_f32_16x16x32_bf16 v[76:79], v[116:119], v[206:209], v[76:79]
	v_mfma_f32_16x16x32_bf16 v[68:71], v[158:161], v[202:205], v[68:71]
	v_mfma_f32_16x16x32_bf16 v[68:71], v[162:165], v[206:209], v[68:71]
	v_mfma_f32_16x16x32_bf16 v[72:75], v[136:139], v[202:205], v[72:75]
	v_mfma_f32_16x16x32_bf16 v[72:75], v[140:143], v[206:209], v[72:75]
	v_mfma_f32_16x16x32_bf16 v[64:67], v[170:173], v[202:205], v[64:67]
	v_mfma_f32_16x16x32_bf16 v[64:67], v[174:177], v[206:209], v[64:67]
	s_barrier
	s_add_i32 s67, s67, s24
	s_add_u32 s98, s82, 0x80
	s_addc_u32 s99, s83, 0
	s_mov_b32 m0, s67
	ds_read_b128 v[178:181], v169 offset:49152
	ds_read_b128 v[182:185], v169 offset:50176
	ds_read_b128 v[186:189], v169 offset:51200
	ds_read_b128 v[190:193], v169 offset:52224
	ds_read_b128 v[194:197], v169 offset:53248
	ds_read_b128 v[198:201], v169 offset:54272
	ds_read_b128 v[202:205], v169 offset:55296
	ds_read_b128 v[206:209], v169 offset:56320
	global_load_lds_dwordx4 v146, s[98:99]
	s_add_i32 m0, s67, 0x2000
	s_add_u32 s70, s82, 0x80080
	s_addc_u32 s71, s83, 0
	s_add_i32 s67, s69, s24
	global_load_lds_dwordx4 v150, s[98:99]
	s_mov_b32 m0, s67
	s_nop 0
	global_load_lds_dwordx4 v146, s[70:71]
	s_add_i32 m0, s67, 0x2000
	s_nop 0
	global_load_lds_dwordx4 v150, s[70:71]
	s_add_u32 s98, s84, 0x80
	s_addc_u32 s99, s85, 0
	s_mov_b32 m0, s39
	s_nop 0
	global_load_lds_dwordx4 v144, s[98:99]
	s_mov_b32 m0, s40
	s_nop 0
	global_load_lds_dwordx4 v148, s[98:99]
	s_waitcnt vmcnt(8)
	s_waitcnt lgkmcnt(0)
	s_barrier
	s_waitcnt lgkmcnt(0)
	v_mfma_f32_16x16x32_bf16 v[60:63], v[80:83], v[178:181], v[60:63]
	v_mfma_f32_16x16x32_bf16 v[60:63], v[116:119], v[182:185], v[60:63]
	v_mfma_f32_16x16x32_bf16 v[52:55], v[158:161], v[178:181], v[52:55]
	v_mfma_f32_16x16x32_bf16 v[52:55], v[162:165], v[182:185], v[52:55]
	v_mfma_f32_16x16x32_bf16 v[56:59], v[136:139], v[178:181], v[56:59]
	v_mfma_f32_16x16x32_bf16 v[56:59], v[140:143], v[182:185], v[56:59]
	v_mfma_f32_16x16x32_bf16 v[48:51], v[170:173], v[178:181], v[48:51]
	v_mfma_f32_16x16x32_bf16 v[48:51], v[174:177], v[182:185], v[48:51]
	v_mfma_f32_16x16x32_bf16 v[44:47], v[80:83], v[186:189], v[44:47]
	v_mfma_f32_16x16x32_bf16 v[44:47], v[116:119], v[190:193], v[44:47]
	v_mfma_f32_16x16x32_bf16 v[36:39], v[158:161], v[186:189], v[36:39]
	v_mfma_f32_16x16x32_bf16 v[36:39], v[162:165], v[190:193], v[36:39]
	v_mfma_f32_16x16x32_bf16 v[40:43], v[136:139], v[186:189], v[40:43]
	v_mfma_f32_16x16x32_bf16 v[40:43], v[140:143], v[190:193], v[40:43]
	v_mfma_f32_16x16x32_bf16 v[32:35], v[170:173], v[186:189], v[32:35]
	v_mfma_f32_16x16x32_bf16 v[32:35], v[174:177], v[190:193], v[32:35]
	v_mfma_f32_16x16x32_bf16 v[28:31], v[80:83], v[194:197], v[28:31]
	v_mfma_f32_16x16x32_bf16 v[28:31], v[116:119], v[198:201], v[28:31]
	v_mfma_f32_16x16x32_bf16 v[20:23], v[158:161], v[194:197], v[20:23]
	v_mfma_f32_16x16x32_bf16 v[20:23], v[162:165], v[198:201], v[20:23]
	v_mfma_f32_16x16x32_bf16 v[24:27], v[136:139], v[194:197], v[24:27]
	v_mfma_f32_16x16x32_bf16 v[24:27], v[140:143], v[198:201], v[24:27]
	v_mfma_f32_16x16x32_bf16 v[16:19], v[170:173], v[194:197], v[16:19]
	v_mfma_f32_16x16x32_bf16 v[16:19], v[174:177], v[198:201], v[16:19]
	v_mfma_f32_16x16x32_bf16 v[12:15], v[80:83], v[202:205], v[12:15]
	v_mfma_f32_16x16x32_bf16 v[12:15], v[116:119], v[206:209], v[12:15]
	v_mfma_f32_16x16x32_bf16 v[4:7], v[158:161], v[202:205], v[4:7]
	v_mfma_f32_16x16x32_bf16 v[4:7], v[162:165], v[206:209], v[4:7]
	v_mfma_f32_16x16x32_bf16 v[8:11], v[136:139], v[202:205], v[8:11]
	v_mfma_f32_16x16x32_bf16 v[8:11], v[140:143], v[206:209], v[8:11]
	v_mfma_f32_16x16x32_bf16 v[0:3], v[170:173], v[202:205], v[0:3]
	v_mfma_f32_16x16x32_bf16 v[0:3], v[174:177], v[206:209], v[0:3]
	s_barrier
	s_add_i32 s68, s68, 2
	s_add_u32 s80, s80, 0x100
	s_addc_u32 s81, s81, 0
	s_add_u32 s60, s60, 0x100
	s_addc_u32 s61, s61, 0
.LBB0_297:
	s_add_u32 s67, s80, 0xfff00080
	s_addc_u32 s69, s81, -1
	s_add_i32 s70, 0, 0x10000
	s_cmp_eq_u32 s68, 28
	s_cselect_b32 s85, s23, s69
	s_cselect_b32 s84, s56, s67
	s_cselect_b32 s83, s21, s61
	s_cselect_b32 s82, s57, s60
	s_add_i32 s67, 0, 0x14000
	v_add_u32_e32 v140, s70, v168
	v_add_u32_e32 v166, s67, v168
	ds_read_b128 v[80:83], v140
	ds_read_b128 v[116:119], v140 offset:1024
	ds_read_b128 v[136:139], v140 offset:2048
	ds_read_b128 v[140:143], v140 offset:3072
	ds_read_b128 v[158:161], v166
	ds_read_b128 v[162:165], v166 offset:1024
	ds_read_b128 v[170:173], v166 offset:2048
	ds_read_b128 v[174:177], v166 offset:3072
	s_add_i32 m0, s26, 0xc000
	ds_read_b128 v[178:181], v169
	ds_read_b128 v[182:185], v169 offset:1024
	ds_read_b128 v[186:189], v169 offset:2048
	ds_read_b128 v[190:193], v169 offset:3072
	ds_read_b128 v[194:197], v169 offset:4096
	ds_read_b128 v[198:201], v169 offset:5120
	ds_read_b128 v[202:205], v169 offset:6144
	ds_read_b128 v[206:209], v169 offset:7168
	global_load_lds_dwordx4 v154, s[80:81]
	s_add_i32 m0, s26, 0xe000
	s_nop 0
	global_load_lds_dwordx4 v156, s[80:81]
	s_waitcnt vmcnt(8)
	s_waitcnt lgkmcnt(0)
	s_barrier
	s_waitcnt lgkmcnt(0)
	v_mfma_f32_16x16x32_bf16 v[132:135], v[80:83], v[178:181], v[132:135]
	v_mfma_f32_16x16x32_bf16 v[132:135], v[116:119], v[182:185], v[132:135]
	v_mfma_f32_16x16x32_bf16 v[124:127], v[158:161], v[178:181], v[124:127]
	v_mfma_f32_16x16x32_bf16 v[124:127], v[162:165], v[182:185], v[124:127]
	v_mfma_f32_16x16x32_bf16 v[128:131], v[136:139], v[178:181], v[128:131]
	v_mfma_f32_16x16x32_bf16 v[128:131], v[140:143], v[182:185], v[128:131]
	v_mfma_f32_16x16x32_bf16 v[120:123], v[170:173], v[178:181], v[120:123]
	v_mfma_f32_16x16x32_bf16 v[120:123], v[174:177], v[182:185], v[120:123]
	v_mfma_f32_16x16x32_bf16 v[112:115], v[80:83], v[186:189], v[112:115]
	v_mfma_f32_16x16x32_bf16 v[112:115], v[116:119], v[190:193], v[112:115]
	v_mfma_f32_16x16x32_bf16 v[104:107], v[158:161], v[186:189], v[104:107]
	v_mfma_f32_16x16x32_bf16 v[104:107], v[162:165], v[190:193], v[104:107]
	v_mfma_f32_16x16x32_bf16 v[108:111], v[136:139], v[186:189], v[108:111]
	v_mfma_f32_16x16x32_bf16 v[108:111], v[140:143], v[190:193], v[108:111]
	v_mfma_f32_16x16x32_bf16 v[100:103], v[170:173], v[186:189], v[100:103]
	v_mfma_f32_16x16x32_bf16 v[100:103], v[174:177], v[190:193], v[100:103]
	v_mfma_f32_16x16x32_bf16 v[96:99], v[80:83], v[194:197], v[96:99]
	v_mfma_f32_16x16x32_bf16 v[96:99], v[116:119], v[198:201], v[96:99]
	v_mfma_f32_16x16x32_bf16 v[88:91], v[158:161], v[194:197], v[88:91]
	v_mfma_f32_16x16x32_bf16 v[88:91], v[162:165], v[198:201], v[88:91]
	v_mfma_f32_16x16x32_bf16 v[92:95], v[136:139], v[194:197], v[92:95]
	v_mfma_f32_16x16x32_bf16 v[92:95], v[140:143], v[198:201], v[92:95]
	v_mfma_f32_16x16x32_bf16 v[84:87], v[170:173], v[194:197], v[84:87]
	v_mfma_f32_16x16x32_bf16 v[84:87], v[174:177], v[198:201], v[84:87]
	v_mfma_f32_16x16x32_bf16 v[76:79], v[80:83], v[202:205], v[76:79]
	v_mfma_f32_16x16x32_bf16 v[76:79], v[116:119], v[206:209], v[76:79]
	v_mfma_f32_16x16x32_bf16 v[68:71], v[158:161], v[202:205], v[68:71]
	v_mfma_f32_16x16x32_bf16 v[68:71], v[162:165], v[206:209], v[68:71]
	v_mfma_f32_16x16x32_bf16 v[72:75], v[136:139], v[202:205], v[72:75]
	v_mfma_f32_16x16x32_bf16 v[72:75], v[140:143], v[206:209], v[72:75]
	v_mfma_f32_16x16x32_bf16 v[64:67], v[170:173], v[202:205], v[64:67]
	v_mfma_f32_16x16x32_bf16 v[64:67], v[174:177], v[206:209], v[64:67]
	s_barrier
	s_add_i32 s69, s70, s24
	s_mov_b32 m0, s69
	ds_read_b128 v[178:181], v169 offset:16384
	ds_read_b128 v[182:185], v169 offset:17408
	ds_read_b128 v[186:189], v169 offset:18432
	ds_read_b128 v[190:193], v169 offset:19456
	ds_read_b128 v[194:197], v169 offset:20480
	ds_read_b128 v[198:201], v169 offset:21504
	ds_read_b128 v[202:205], v169 offset:22528
	ds_read_b128 v[206:209], v169 offset:23552
	global_load_lds_dwordx4 v146, s[82:83]
	s_add_i32 m0, s69, 0x2000
	s_add_u32 s70, s82, 0x80000
	s_addc_u32 s71, s83, 0
	s_add_i32 s67, s67, s24
	global_load_lds_dwordx4 v150, s[82:83]
	s_mov_b32 m0, s67
	s_nop 0
	global_load_lds_dwordx4 v146, s[70:71]
	s_add_i32 m0, s67, 0x2000
	s_nop 0
	global_load_lds_dwordx4 v150, s[70:71]
	s_mov_b32 m0, s26
	s_nop 0
	global_load_lds_dwordx4 v144, s[84:85]
	s_mov_b32 m0, s28
	s_nop 0
	global_load_lds_dwordx4 v148, s[84:85]
	s_waitcnt vmcnt(8)
	s_waitcnt lgkmcnt(0)
	s_barrier
	s_waitcnt lgkmcnt(0)
	v_mfma_f32_16x16x32_bf16 v[60:63], v[80:83], v[178:181], v[60:63]
	v_mfma_f32_16x16x32_bf16 v[60:63], v[116:119], v[182:185], v[60:63]
	v_mfma_f32_16x16x32_bf16 v[52:55], v[158:161], v[178:181], v[52:55]
	v_mfma_f32_16x16x32_bf16 v[52:55], v[162:165], v[182:185], v[52:55]
	v_mfma_f32_16x16x32_bf16 v[56:59], v[136:139], v[178:181], v[56:59]
	v_mfma_f32_16x16x32_bf16 v[56:59], v[140:143], v[182:185], v[56:59]
	v_mfma_f32_16x16x32_bf16 v[48:51], v[170:173], v[178:181], v[48:51]
	v_mfma_f32_16x16x32_bf16 v[48:51], v[174:177], v[182:185], v[48:51]
	v_mfma_f32_16x16x32_bf16 v[44:47], v[80:83], v[186:189], v[44:47]
	v_mfma_f32_16x16x32_bf16 v[44:47], v[116:119], v[190:193], v[44:47]
	v_mfma_f32_16x16x32_bf16 v[36:39], v[158:161], v[186:189], v[36:39]
	v_mfma_f32_16x16x32_bf16 v[36:39], v[162:165], v[190:193], v[36:39]
	v_mfma_f32_16x16x32_bf16 v[40:43], v[136:139], v[186:189], v[40:43]
	v_mfma_f32_16x16x32_bf16 v[40:43], v[140:143], v[190:193], v[40:43]
	v_mfma_f32_16x16x32_bf16 v[32:35], v[170:173], v[186:189], v[32:35]
	v_mfma_f32_16x16x32_bf16 v[32:35], v[174:177], v[190:193], v[32:35]
	v_mfma_f32_16x16x32_bf16 v[28:31], v[80:83], v[194:197], v[28:31]
	v_mfma_f32_16x16x32_bf16 v[28:31], v[116:119], v[198:201], v[28:31]
	v_mfma_f32_16x16x32_bf16 v[20:23], v[158:161], v[194:197], v[20:23]
	v_mfma_f32_16x16x32_bf16 v[20:23], v[162:165], v[198:201], v[20:23]
	v_mfma_f32_16x16x32_bf16 v[24:27], v[136:139], v[194:197], v[24:27]
	v_mfma_f32_16x16x32_bf16 v[24:27], v[140:143], v[198:201], v[24:27]
	v_mfma_f32_16x16x32_bf16 v[16:19], v[170:173], v[194:197], v[16:19]
	v_mfma_f32_16x16x32_bf16 v[16:19], v[174:177], v[198:201], v[16:19]
	v_mfma_f32_16x16x32_bf16 v[12:15], v[80:83], v[202:205], v[12:15]
	v_mfma_f32_16x16x32_bf16 v[12:15], v[116:119], v[206:209], v[12:15]
	v_mfma_f32_16x16x32_bf16 v[4:7], v[158:161], v[202:205], v[4:7]
	v_mfma_f32_16x16x32_bf16 v[4:7], v[162:165], v[206:209], v[4:7]
	v_mfma_f32_16x16x32_bf16 v[8:11], v[136:139], v[202:205], v[8:11]
	v_mfma_f32_16x16x32_bf16 v[8:11], v[140:143], v[206:209], v[8:11]
	v_mfma_f32_16x16x32_bf16 v[0:3], v[170:173], v[202:205], v[0:3]
	v_mfma_f32_16x16x32_bf16 v[0:3], v[174:177], v[206:209], v[0:3]
	s_barrier
	s_add_i32 s67, 0, 0x18000
	s_add_i32 s69, 0, 0x1c000
	v_add_u32_e32 v140, s67, v168
	v_add_u32_e32 v174, s69, v168
	ds_read_b128 v[80:83], v140
	ds_read_b128 v[116:119], v140 offset:1024
	ds_read_b128 v[136:139], v140 offset:2048
	ds_read_b128 v[140:143], v140 offset:3072
	ds_read_b128 v[158:161], v174
	ds_read_b128 v[162:165], v174 offset:1024
	ds_read_b128 v[170:173], v174 offset:2048
	ds_read_b128 v[174:177], v174 offset:3072
	s_add_u32 s70, s84, 0x100000
	s_addc_u32 s71, s85, 0
	s_mov_b32 m0, s29
	ds_read_b128 v[178:181], v169 offset:32768
	ds_read_b128 v[182:185], v169 offset:33792
	ds_read_b128 v[186:189], v169 offset:34816
	ds_read_b128 v[190:193], v169 offset:35840
	ds_read_b128 v[194:197], v169 offset:36864
	ds_read_b128 v[198:201], v169 offset:37888
	ds_read_b128 v[202:205], v169 offset:38912
	ds_read_b128 v[206:209], v169 offset:39936
	global_load_lds_dwordx4 v144, s[70:71]
	s_mov_b32 m0, s34
	s_nop 0
	global_load_lds_dwordx4 v148, s[70:71]
	s_waitcnt vmcnt(8)
	s_waitcnt lgkmcnt(0)
	s_barrier
	s_waitcnt lgkmcnt(0)
	v_mfma_f32_16x16x32_bf16 v[132:135], v[80:83], v[178:181], v[132:135]
	v_mfma_f32_16x16x32_bf16 v[132:135], v[116:119], v[182:185], v[132:135]
	v_mfma_f32_16x16x32_bf16 v[124:127], v[158:161], v[178:181], v[124:127]
	v_mfma_f32_16x16x32_bf16 v[124:127], v[162:165], v[182:185], v[124:127]
	v_mfma_f32_16x16x32_bf16 v[128:131], v[136:139], v[178:181], v[128:131]
	v_mfma_f32_16x16x32_bf16 v[128:131], v[140:143], v[182:185], v[128:131]
	v_mfma_f32_16x16x32_bf16 v[120:123], v[170:173], v[178:181], v[120:123]
	v_mfma_f32_16x16x32_bf16 v[120:123], v[174:177], v[182:185], v[120:123]
	v_mfma_f32_16x16x32_bf16 v[112:115], v[80:83], v[186:189], v[112:115]
	v_mfma_f32_16x16x32_bf16 v[112:115], v[116:119], v[190:193], v[112:115]
	v_mfma_f32_16x16x32_bf16 v[104:107], v[158:161], v[186:189], v[104:107]
	v_mfma_f32_16x16x32_bf16 v[104:107], v[162:165], v[190:193], v[104:107]
	v_mfma_f32_16x16x32_bf16 v[108:111], v[136:139], v[186:189], v[108:111]
	v_mfma_f32_16x16x32_bf16 v[108:111], v[140:143], v[190:193], v[108:111]
	v_mfma_f32_16x16x32_bf16 v[100:103], v[170:173], v[186:189], v[100:103]
	v_mfma_f32_16x16x32_bf16 v[100:103], v[174:177], v[190:193], v[100:103]
	v_mfma_f32_16x16x32_bf16 v[96:99], v[80:83], v[194:197], v[96:99]
	v_mfma_f32_16x16x32_bf16 v[96:99], v[116:119], v[198:201], v[96:99]
	v_mfma_f32_16x16x32_bf16 v[88:91], v[158:161], v[194:197], v[88:91]
	v_mfma_f32_16x16x32_bf16 v[88:91], v[162:165], v[198:201], v[88:91]
	v_mfma_f32_16x16x32_bf16 v[92:95], v[136:139], v[194:197], v[92:95]
	v_mfma_f32_16x16x32_bf16 v[92:95], v[140:143], v[198:201], v[92:95]
	v_mfma_f32_16x16x32_bf16 v[84:87], v[170:173], v[194:197], v[84:87]
	v_mfma_f32_16x16x32_bf16 v[84:87], v[174:177], v[198:201], v[84:87]
	v_mfma_f32_16x16x32_bf16 v[76:79], v[80:83], v[202:205], v[76:79]
	v_mfma_f32_16x16x32_bf16 v[76:79], v[116:119], v[206:209], v[76:79]
	v_mfma_f32_16x16x32_bf16 v[68:71], v[158:161], v[202:205], v[68:71]
	v_mfma_f32_16x16x32_bf16 v[68:71], v[162:165], v[206:209], v[68:71]
	v_mfma_f32_16x16x32_bf16 v[72:75], v[136:139], v[202:205], v[72:75]
	v_mfma_f32_16x16x32_bf16 v[72:75], v[140:143], v[206:209], v[72:75]
	v_mfma_f32_16x16x32_bf16 v[64:67], v[170:173], v[202:205], v[64:67]
	v_mfma_f32_16x16x32_bf16 v[64:67], v[174:177], v[206:209], v[64:67]
	s_barrier
	s_add_i32 s67, s67, s24
	s_add_u32 s98, s82, 0x80
	s_addc_u32 s99, s83, 0
	s_mov_b32 m0, s67
	ds_read_b128 v[178:181], v169 offset:49152
	ds_read_b128 v[182:185], v169 offset:50176
	ds_read_b128 v[186:189], v169 offset:51200
	ds_read_b128 v[190:193], v169 offset:52224
	ds_read_b128 v[194:197], v169 offset:53248
	ds_read_b128 v[198:201], v169 offset:54272
	ds_read_b128 v[202:205], v169 offset:55296
	ds_read_b128 v[206:209], v169 offset:56320
	global_load_lds_dwordx4 v146, s[98:99]
	s_add_i32 m0, s67, 0x2000
	s_add_u32 s70, s82, 0x80080
	s_addc_u32 s71, s83, 0
	s_add_i32 s67, s69, s24
	global_load_lds_dwordx4 v150, s[98:99]
	s_mov_b32 m0, s67
	s_nop 0
	global_load_lds_dwordx4 v146, s[70:71]
	s_add_i32 m0, s67, 0x2000
	s_nop 0
	global_load_lds_dwordx4 v150, s[70:71]
	s_add_u32 s98, s84, 0x80
	s_addc_u32 s99, s85, 0
	s_mov_b32 m0, s39
	s_nop 0
	global_load_lds_dwordx4 v144, s[98:99]
	s_mov_b32 m0, s40
	s_nop 0
	global_load_lds_dwordx4 v148, s[98:99]
	s_waitcnt vmcnt(8)
	s_waitcnt lgkmcnt(0)
	s_barrier
	s_waitcnt lgkmcnt(0)
	v_mfma_f32_16x16x32_bf16 v[60:63], v[80:83], v[178:181], v[60:63]
	v_mfma_f32_16x16x32_bf16 v[60:63], v[116:119], v[182:185], v[60:63]
	v_mfma_f32_16x16x32_bf16 v[52:55], v[158:161], v[178:181], v[52:55]
	v_mfma_f32_16x16x32_bf16 v[52:55], v[162:165], v[182:185], v[52:55]
	v_mfma_f32_16x16x32_bf16 v[56:59], v[136:139], v[178:181], v[56:59]
	v_mfma_f32_16x16x32_bf16 v[56:59], v[140:143], v[182:185], v[56:59]
	v_mfma_f32_16x16x32_bf16 v[48:51], v[170:173], v[178:181], v[48:51]
	v_mfma_f32_16x16x32_bf16 v[48:51], v[174:177], v[182:185], v[48:51]
	v_mfma_f32_16x16x32_bf16 v[44:47], v[80:83], v[186:189], v[44:47]
	v_mfma_f32_16x16x32_bf16 v[44:47], v[116:119], v[190:193], v[44:47]
	v_mfma_f32_16x16x32_bf16 v[36:39], v[158:161], v[186:189], v[36:39]
	v_mfma_f32_16x16x32_bf16 v[36:39], v[162:165], v[190:193], v[36:39]
	v_mfma_f32_16x16x32_bf16 v[40:43], v[136:139], v[186:189], v[40:43]
	v_mfma_f32_16x16x32_bf16 v[40:43], v[140:143], v[190:193], v[40:43]
	v_mfma_f32_16x16x32_bf16 v[32:35], v[170:173], v[186:189], v[32:35]
	v_mfma_f32_16x16x32_bf16 v[32:35], v[174:177], v[190:193], v[32:35]
	v_mfma_f32_16x16x32_bf16 v[28:31], v[80:83], v[194:197], v[28:31]
	v_mfma_f32_16x16x32_bf16 v[28:31], v[116:119], v[198:201], v[28:31]
	v_mfma_f32_16x16x32_bf16 v[20:23], v[158:161], v[194:197], v[20:23]
	v_mfma_f32_16x16x32_bf16 v[20:23], v[162:165], v[198:201], v[20:23]
	v_mfma_f32_16x16x32_bf16 v[24:27], v[136:139], v[194:197], v[24:27]
	v_mfma_f32_16x16x32_bf16 v[24:27], v[140:143], v[198:201], v[24:27]
	v_mfma_f32_16x16x32_bf16 v[16:19], v[170:173], v[194:197], v[16:19]
	v_mfma_f32_16x16x32_bf16 v[16:19], v[174:177], v[198:201], v[16:19]
	v_mfma_f32_16x16x32_bf16 v[12:15], v[80:83], v[202:205], v[12:15]
	v_mfma_f32_16x16x32_bf16 v[12:15], v[116:119], v[206:209], v[12:15]
	v_mfma_f32_16x16x32_bf16 v[4:7], v[158:161], v[202:205], v[4:7]
	v_mfma_f32_16x16x32_bf16 v[4:7], v[162:165], v[206:209], v[4:7]
	v_mfma_f32_16x16x32_bf16 v[8:11], v[136:139], v[202:205], v[8:11]
	v_mfma_f32_16x16x32_bf16 v[8:11], v[140:143], v[206:209], v[8:11]
	v_mfma_f32_16x16x32_bf16 v[0:3], v[170:173], v[202:205], v[0:3]
	v_mfma_f32_16x16x32_bf16 v[0:3], v[174:177], v[206:209], v[0:3]
	s_barrier
	s_add_i32 s68, s68, 2
	s_add_u32 s80, s80, 0x100
	s_addc_u32 s81, s81, 0
	s_add_u32 s60, s60, 0x100
	s_addc_u32 s61, s61, 0
	s_cmp_gt_u32 s68, 29
	s_cbranch_scc0 .LBB0_297
	s_and_b64 vcc, exec, s[18:19]
	s_cbranch_vccz .LBB0_300
	s_barrier

.LBB0_384:
	s_ashr_i32 s73, s72, 31
	s_lshl_b64 s[74:75], s[72:73], 20
	s_add_u32 s74, s2, s74
	s_addc_u32 s75, s3, s75
	s_and_b64 s[76:77], s[4:5], exec
	s_cselect_b32 s73, s75, s81
	s_cselect_b32 s79, s74, s80
	s_ashr_i32 s23, s22, 31
	s_lshl_b64 s[76:77], s[22:23], 20
	s_add_u32 s76, s14, s76
	s_addc_u32 s77, s15, s77
	s_and_b64 s[84:85], s[4:5], exec
	s_cselect_b32 s23, s77, s83
	s_cselect_b32 s86, s76, s82
	s_add_u32 s80, s80, 0x80080
	s_addc_u32 s81, s81, 0
	s_add_u32 s87, s82, 0x100
	s_addc_u32 s88, s83, 0
	s_mov_b32 s89, -2
	s_add_u32 s67, s80, 0xfff80080
	s_addc_u32 s82, s81, -1
	s_add_i32 s90, 0, 0x10000
	s_cmp_eq_u32 s89, 28
	s_cselect_b32 s85, s73, s82
	s_cselect_b32 s84, s79, s67
	s_cselect_b32 s83, s23, s88
	s_cselect_b32 s82, s86, s87
	s_add_i32 s67, 0, 0x14000
	v_add_u32_e32 v140, s90, v186
	v_add_u32_e32 v156, s67, v186
	ds_read_b128 v[128:131], v140
	ds_read_b128 v[132:135], v140 offset:1024
	ds_read_b128 v[136:139], v140 offset:2048
	ds_read_b128 v[140:143], v140 offset:3072
	ds_read_b128 v[144:147], v156
	ds_read_b128 v[148:151], v156 offset:1024
	ds_read_b128 v[152:155], v156 offset:2048
	ds_read_b128 v[156:159], v156 offset:3072
	s_add_i32 m0, s29, 0xc000
	ds_read_b128 v[160:163], v187
	ds_read_b128 v[164:167], v187 offset:1024
	ds_read_b128 v[182:185], v187 offset:2048
	ds_read_b128 v[188:191], v187 offset:3072
	ds_read_b128 v[192:195], v187 offset:4096
	ds_read_b128 v[196:199], v187 offset:5120
	ds_read_b128 v[200:203], v187 offset:6144
	ds_read_b128 v[204:207], v187 offset:7168
	global_load_lds_dwordx4 v178, s[80:81]
	s_add_i32 m0, s29, 0xe000
	s_nop 0
	global_load_lds_dwordx4 v180, s[80:81]
	s_waitcnt vmcnt(8)
	s_waitcnt lgkmcnt(0)
	s_barrier
	s_waitcnt lgkmcnt(0)
	v_mfma_f32_16x16x32_bf16 v[124:127], v[128:131], v[160:163], 0
	v_mfma_f32_16x16x32_bf16 v[124:127], v[132:135], v[164:167], v[124:127]
	v_mfma_f32_16x16x32_bf16 v[116:119], v[144:147], v[160:163], 0
	v_mfma_f32_16x16x32_bf16 v[116:119], v[148:151], v[164:167], v[116:119]
	v_mfma_f32_16x16x32_bf16 v[120:123], v[136:139], v[160:163], 0
	v_mfma_f32_16x16x32_bf16 v[120:123], v[140:143], v[164:167], v[120:123]
	v_mfma_f32_16x16x32_bf16 v[112:115], v[152:155], v[160:163], 0
	v_mfma_f32_16x16x32_bf16 v[112:115], v[156:159], v[164:167], v[112:115]
	v_mfma_f32_16x16x32_bf16 v[108:111], v[128:131], v[182:185], 0
	v_mfma_f32_16x16x32_bf16 v[108:111], v[132:135], v[188:191], v[108:111]
	v_mfma_f32_16x16x32_bf16 v[100:103], v[144:147], v[182:185], 0
	v_mfma_f32_16x16x32_bf16 v[100:103], v[148:151], v[188:191], v[100:103]
	v_mfma_f32_16x16x32_bf16 v[104:107], v[136:139], v[182:185], 0
	v_mfma_f32_16x16x32_bf16 v[104:107], v[140:143], v[188:191], v[104:107]
	v_mfma_f32_16x16x32_bf16 v[96:99], v[152:155], v[182:185], 0
	v_mfma_f32_16x16x32_bf16 v[96:99], v[156:159], v[188:191], v[96:99]
	v_mfma_f32_16x16x32_bf16 v[92:95], v[128:131], v[192:195], 0
	v_mfma_f32_16x16x32_bf16 v[92:95], v[132:135], v[196:199], v[92:95]
	v_mfma_f32_16x16x32_bf16 v[84:87], v[144:147], v[192:195], 0
	v_mfma_f32_16x16x32_bf16 v[84:87], v[148:151], v[196:199], v[84:87]
	v_mfma_f32_16x16x32_bf16 v[88:91], v[136:139], v[192:195], 0
	v_mfma_f32_16x16x32_bf16 v[88:91], v[140:143], v[196:199], v[88:91]
	v_mfma_f32_16x16x32_bf16 v[80:83], v[152:155], v[192:195], 0
	v_mfma_f32_16x16x32_bf16 v[80:83], v[156:159], v[196:199], v[80:83]
	v_mfma_f32_16x16x32_bf16 v[76:79], v[128:131], v[200:203], 0
	v_mfma_f32_16x16x32_bf16 v[76:79], v[132:135], v[204:207], v[76:79]
	v_mfma_f32_16x16x32_bf16 v[68:71], v[144:147], v[200:203], 0
	v_mfma_f32_16x16x32_bf16 v[68:71], v[148:151], v[204:207], v[68:71]
	v_mfma_f32_16x16x32_bf16 v[72:75], v[136:139], v[200:203], 0
	v_mfma_f32_16x16x32_bf16 v[72:75], v[140:143], v[204:207], v[72:75]
	v_mfma_f32_16x16x32_bf16 v[64:67], v[152:155], v[200:203], 0
	v_mfma_f32_16x16x32_bf16 v[64:67], v[156:159], v[204:207], v[64:67]
	s_barrier
	s_add_i32 s90, s90, s24
	s_mov_b32 m0, s90
	ds_read_b128 v[160:163], v187 offset:16384
	ds_read_b128 v[164:167], v187 offset:17408
	ds_read_b128 v[182:185], v187 offset:18432
	ds_read_b128 v[188:191], v187 offset:19456
	ds_read_b128 v[192:195], v187 offset:20480
	ds_read_b128 v[196:199], v187 offset:21504
	ds_read_b128 v[200:203], v187 offset:22528
	ds_read_b128 v[204:207], v187 offset:23552
	global_load_lds_dwordx4 v172, s[82:83]
	s_add_i32 m0, s90, 0x2000
	s_add_u32 s90, s82, 0x80000
	s_addc_u32 s91, s83, 0
	s_add_i32 s67, s67, s24
	global_load_lds_dwordx4 v168, s[82:83]
	s_mov_b32 m0, s67
	s_nop 0
	global_load_lds_dwordx4 v172, s[90:91]
	s_add_i32 m0, s67, 0x2000
	s_nop 0
	global_load_lds_dwordx4 v168, s[90:91]
	s_mov_b32 m0, s29
	s_nop 0
	global_load_lds_dwordx4 v174, s[84:85]
	s_mov_b32 m0, s34
	s_nop 0
	global_load_lds_dwordx4 v170, s[84:85]
	s_waitcnt vmcnt(8)
	s_waitcnt lgkmcnt(0)
	s_barrier
	s_waitcnt lgkmcnt(0)
	v_mfma_f32_16x16x32_bf16 v[60:63], v[128:131], v[160:163], 0
	v_mfma_f32_16x16x32_bf16 v[60:63], v[132:135], v[164:167], v[60:63]
	v_mfma_f32_16x16x32_bf16 v[52:55], v[144:147], v[160:163], 0
	v_mfma_f32_16x16x32_bf16 v[52:55], v[148:151], v[164:167], v[52:55]
	v_mfma_f32_16x16x32_bf16 v[56:59], v[136:139], v[160:163], 0
	v_mfma_f32_16x16x32_bf16 v[56:59], v[140:143], v[164:167], v[56:59]
	v_mfma_f32_16x16x32_bf16 v[48:51], v[152:155], v[160:163], 0
	v_mfma_f32_16x16x32_bf16 v[48:51], v[156:159], v[164:167], v[48:51]
	v_mfma_f32_16x16x32_bf16 v[44:47], v[128:131], v[182:185], 0
	v_mfma_f32_16x16x32_bf16 v[44:47], v[132:135], v[188:191], v[44:47]
	v_mfma_f32_16x16x32_bf16 v[36:39], v[144:147], v[182:185], 0
	v_mfma_f32_16x16x32_bf16 v[36:39], v[148:151], v[188:191], v[36:39]
	v_mfma_f32_16x16x32_bf16 v[40:43], v[136:139], v[182:185], 0
	v_mfma_f32_16x16x32_bf16 v[40:43], v[140:143], v[188:191], v[40:43]
	v_mfma_f32_16x16x32_bf16 v[32:35], v[152:155], v[182:185], 0
	v_mfma_f32_16x16x32_bf16 v[32:35], v[156:159], v[188:191], v[32:35]
	v_mfma_f32_16x16x32_bf16 v[28:31], v[128:131], v[192:195], 0
	v_mfma_f32_16x16x32_bf16 v[28:31], v[132:135], v[196:199], v[28:31]
	v_mfma_f32_16x16x32_bf16 v[20:23], v[144:147], v[192:195], 0
	v_mfma_f32_16x16x32_bf16 v[20:23], v[148:151], v[196:199], v[20:23]
	v_mfma_f32_16x16x32_bf16 v[24:27], v[136:139], v[192:195], 0
	v_mfma_f32_16x16x32_bf16 v[24:27], v[140:143], v[196:199], v[24:27]
	v_mfma_f32_16x16x32_bf16 v[16:19], v[152:155], v[192:195], 0
	v_mfma_f32_16x16x32_bf16 v[16:19], v[156:159], v[196:199], v[16:19]
	v_mfma_f32_16x16x32_bf16 v[12:15], v[128:131], v[200:203], 0
	v_mfma_f32_16x16x32_bf16 v[12:15], v[132:135], v[204:207], v[12:15]
	v_mfma_f32_16x16x32_bf16 v[4:7], v[144:147], v[200:203], 0
	v_mfma_f32_16x16x32_bf16 v[4:7], v[148:151], v[204:207], v[4:7]
	v_mfma_f32_16x16x32_bf16 v[8:11], v[136:139], v[200:203], 0
	v_mfma_f32_16x16x32_bf16 v[8:11], v[140:143], v[204:207], v[8:11]
	v_mfma_f32_16x16x32_bf16 v[0:3], v[152:155], v[200:203], 0
	v_mfma_f32_16x16x32_bf16 v[0:3], v[156:159], v[204:207], v[0:3]
	s_barrier
	s_add_i32 s67, 0, 0x18000
	s_add_i32 s90, 0, 0x1c000
	v_add_u32_e32 v140, s67, v186
	v_add_u32_e32 v156, s90, v186
	ds_read_b128 v[128:131], v140
	ds_read_b128 v[132:135], v140 offset:1024
	ds_read_b128 v[136:139], v140 offset:2048
	ds_read_b128 v[140:143], v140 offset:3072
	ds_read_b128 v[144:147], v156
	ds_read_b128 v[148:151], v156 offset:1024
	ds_read_b128 v[152:155], v156 offset:2048
	ds_read_b128 v[156:159], v156 offset:3072
	s_add_u32 s84, s84, 0x80000
	s_addc_u32 s85, s85, 0
	s_mov_b32 m0, s35
	ds_read_b128 v[160:163], v187 offset:32768
	ds_read_b128 v[164:167], v187 offset:33792
	ds_read_b128 v[182:185], v187 offset:34816
	ds_read_b128 v[188:191], v187 offset:35840
	ds_read_b128 v[192:195], v187 offset:36864
	ds_read_b128 v[196:199], v187 offset:37888
	ds_read_b128 v[200:203], v187 offset:38912
	ds_read_b128 v[204:207], v187 offset:39936
	global_load_lds_dwordx4 v174, s[84:85]
	s_mov_b32 m0, s38
	s_nop 0
	global_load_lds_dwordx4 v170, s[84:85]
	s_waitcnt vmcnt(8)
	s_waitcnt lgkmcnt(0)
	s_barrier
	s_waitcnt lgkmcnt(0)
	v_mfma_f32_16x16x32_bf16 v[124:127], v[128:131], v[160:163], v[124:127]
	v_mfma_f32_16x16x32_bf16 v[124:127], v[132:135], v[164:167], v[124:127]
	v_mfma_f32_16x16x32_bf16 v[116:119], v[144:147], v[160:163], v[116:119]
	v_mfma_f32_16x16x32_bf16 v[116:119], v[148:151], v[164:167], v[116:119]
	v_mfma_f32_16x16x32_bf16 v[120:123], v[136:139], v[160:163], v[120:123]
	v_mfma_f32_16x16x32_bf16 v[120:123], v[140:143], v[164:167], v[120:123]
	v_mfma_f32_16x16x32_bf16 v[112:115], v[152:155], v[160:163], v[112:115]
	v_mfma_f32_16x16x32_bf16 v[112:115], v[156:159], v[164:167], v[112:115]
	v_mfma_f32_16x16x32_bf16 v[108:111], v[128:131], v[182:185], v[108:111]
	v_mfma_f32_16x16x32_bf16 v[108:111], v[132:135], v[188:191], v[108:111]
	v_mfma_f32_16x16x32_bf16 v[100:103], v[144:147], v[182:185], v[100:103]
	v_mfma_f32_16x16x32_bf16 v[100:103], v[148:151], v[188:191], v[100:103]
	v_mfma_f32_16x16x32_bf16 v[104:107], v[136:139], v[182:185], v[104:107]
	v_mfma_f32_16x16x32_bf16 v[104:107], v[140:143], v[188:191], v[104:107]
	v_mfma_f32_16x16x32_bf16 v[96:99], v[152:155], v[182:185], v[96:99]
	v_mfma_f32_16x16x32_bf16 v[96:99], v[156:159], v[188:191], v[96:99]
	v_mfma_f32_16x16x32_bf16 v[92:95], v[128:131], v[192:195], v[92:95]
	v_mfma_f32_16x16x32_bf16 v[92:95], v[132:135], v[196:199], v[92:95]
	v_mfma_f32_16x16x32_bf16 v[84:87], v[144:147], v[192:195], v[84:87]
	v_mfma_f32_16x16x32_bf16 v[84:87], v[148:151], v[196:199], v[84:87]
	v_mfma_f32_16x16x32_bf16 v[88:91], v[136:139], v[192:195], v[88:91]
	v_mfma_f32_16x16x32_bf16 v[88:91], v[140:143], v[196:199], v[88:91]
	v_mfma_f32_16x16x32_bf16 v[80:83], v[152:155], v[192:195], v[80:83]
	v_mfma_f32_16x16x32_bf16 v[80:83], v[156:159], v[196:199], v[80:83]
	v_mfma_f32_16x16x32_bf16 v[76:79], v[128:131], v[200:203], v[76:79]
	v_mfma_f32_16x16x32_bf16 v[76:79], v[132:135], v[204:207], v[76:79]
	v_mfma_f32_16x16x32_bf16 v[68:71], v[144:147], v[200:203], v[68:71]
	v_mfma_f32_16x16x32_bf16 v[68:71], v[148:151], v[204:207], v[68:71]
	v_mfma_f32_16x16x32_bf16 v[72:75], v[136:139], v[200:203], v[72:75]
	v_mfma_f32_16x16x32_bf16 v[72:75], v[140:143], v[204:207], v[72:75]
	v_mfma_f32_16x16x32_bf16 v[64:67], v[152:155], v[200:203], v[64:67]
	v_mfma_f32_16x16x32_bf16 v[64:67], v[156:159], v[204:207], v[64:67]
	s_barrier
	s_add_i32 s67, s67, s24
	s_add_u32 s98, s82, 0x80
	s_addc_u32 s99, s83, 0
	s_mov_b32 m0, s67
	ds_read_b128 v[160:163], v187 offset:49152
	ds_read_b128 v[164:167], v187 offset:50176
	ds_read_b128 v[182:185], v187 offset:51200
	ds_read_b128 v[188:191], v187 offset:52224
	ds_read_b128 v[192:195], v187 offset:53248
	ds_read_b128 v[196:199], v187 offset:54272
	ds_read_b128 v[200:203], v187 offset:55296
	ds_read_b128 v[204:207], v187 offset:56320
	global_load_lds_dwordx4 v172, s[98:99]
	s_add_i32 m0, s67, 0x2000
	s_add_u32 s82, s82, 0x80080
	s_addc_u32 s83, s83, 0
	s_add_i32 s67, s90, s24
	global_load_lds_dwordx4 v168, s[98:99]
	s_mov_b32 m0, s67
	s_nop 0
	global_load_lds_dwordx4 v172, s[82:83]
	s_add_i32 m0, s67, 0x2000
	s_nop 0
	global_load_lds_dwordx4 v168, s[82:83]
	s_add_u32 s98, s84, 0xfff80080
	s_addc_u32 s99, s85, -1
	s_mov_b32 m0, s54
	s_nop 0
	global_load_lds_dwordx4 v174, s[98:99]
	s_mov_b32 m0, s55
	s_nop 0
	global_load_lds_dwordx4 v170, s[98:99]
	s_waitcnt vmcnt(8)
	s_waitcnt lgkmcnt(0)
	s_barrier
	s_waitcnt lgkmcnt(0)
	v_mfma_f32_16x16x32_bf16 v[60:63], v[128:131], v[160:163], v[60:63]
	v_mfma_f32_16x16x32_bf16 v[60:63], v[132:135], v[164:167], v[60:63]
	v_mfma_f32_16x16x32_bf16 v[52:55], v[144:147], v[160:163], v[52:55]
	v_mfma_f32_16x16x32_bf16 v[52:55], v[148:151], v[164:167], v[52:55]
	v_mfma_f32_16x16x32_bf16 v[56:59], v[136:139], v[160:163], v[56:59]
	v_mfma_f32_16x16x32_bf16 v[56:59], v[140:143], v[164:167], v[56:59]
	v_mfma_f32_16x16x32_bf16 v[48:51], v[152:155], v[160:163], v[48:51]
	v_mfma_f32_16x16x32_bf16 v[48:51], v[156:159], v[164:167], v[48:51]
	v_mfma_f32_16x16x32_bf16 v[44:47], v[128:131], v[182:185], v[44:47]
	v_mfma_f32_16x16x32_bf16 v[44:47], v[132:135], v[188:191], v[44:47]
	v_mfma_f32_16x16x32_bf16 v[36:39], v[144:147], v[182:185], v[36:39]
	v_mfma_f32_16x16x32_bf16 v[36:39], v[148:151], v[188:191], v[36:39]
	v_mfma_f32_16x16x32_bf16 v[40:43], v[136:139], v[182:185], v[40:43]
	v_mfma_f32_16x16x32_bf16 v[40:43], v[140:143], v[188:191], v[40:43]
	v_mfma_f32_16x16x32_bf16 v[32:35], v[152:155], v[182:185], v[32:35]
	v_mfma_f32_16x16x32_bf16 v[32:35], v[156:159], v[188:191], v[32:35]
	v_mfma_f32_16x16x32_bf16 v[28:31], v[128:131], v[192:195], v[28:31]
	v_mfma_f32_16x16x32_bf16 v[28:31], v[132:135], v[196:199], v[28:31]
	v_mfma_f32_16x16x32_bf16 v[20:23], v[144:147], v[192:195], v[20:23]
	v_mfma_f32_16x16x32_bf16 v[20:23], v[148:151], v[196:199], v[20:23]
	v_mfma_f32_16x16x32_bf16 v[24:27], v[136:139], v[192:195], v[24:27]
	v_mfma_f32_16x16x32_bf16 v[24:27], v[140:143], v[196:199], v[24:27]
	v_mfma_f32_16x16x32_bf16 v[16:19], v[152:155], v[192:195], v[16:19]
	v_mfma_f32_16x16x32_bf16 v[16:19], v[156:159], v[196:199], v[16:19]
	v_mfma_f32_16x16x32_bf16 v[12:15], v[128:131], v[200:203], v[12:15]
	v_mfma_f32_16x16x32_bf16 v[12:15], v[132:135], v[204:207], v[12:15]
	v_mfma_f32_16x16x32_bf16 v[4:7], v[144:147], v[200:203], v[4:7]
	v_mfma_f32_16x16x32_bf16 v[4:7], v[148:151], v[204:207], v[4:7]
	v_mfma_f32_16x16x32_bf16 v[8:11], v[136:139], v[200:203], v[8:11]
	v_mfma_f32_16x16x32_bf16 v[8:11], v[140:143], v[204:207], v[8:11]
	v_mfma_f32_16x16x32_bf16 v[0:3], v[152:155], v[200:203], v[0:3]
	v_mfma_f32_16x16x32_bf16 v[0:3], v[156:159], v[204:207], v[0:3]
	s_barrier
	s_add_i32 s89, s89, 2
	s_add_u32 s80, s80, 0x100
	s_addc_u32 s81, s81, 0
	s_add_u32 s87, s87, 0x100
	s_addc_u32 s88, s88, 0
.LBB0_385:
	s_add_u32 s67, s80, 0xfff80080
	s_addc_u32 s82, s81, -1
	s_add_i32 s90, 0, 0x10000
	s_cmp_eq_u32 s89, 28
	s_cselect_b32 s85, s73, s82
	s_cselect_b32 s84, s79, s67
	s_cselect_b32 s83, s23, s88
	s_cselect_b32 s82, s86, s87
	s_add_i32 s67, 0, 0x14000
	v_add_u32_e32 v140, s90, v186
	v_add_u32_e32 v156, s67, v186
	ds_read_b128 v[128:131], v140
	ds_read_b128 v[132:135], v140 offset:1024
	ds_read_b128 v[136:139], v140 offset:2048
	ds_read_b128 v[140:143], v140 offset:3072
	ds_read_b128 v[144:147], v156
	ds_read_b128 v[148:151], v156 offset:1024
	ds_read_b128 v[152:155], v156 offset:2048
	ds_read_b128 v[156:159], v156 offset:3072
	s_add_i32 m0, s29, 0xc000
	ds_read_b128 v[160:163], v187
	ds_read_b128 v[164:167], v187 offset:1024
	ds_read_b128 v[182:185], v187 offset:2048
	ds_read_b128 v[188:191], v187 offset:3072
	ds_read_b128 v[192:195], v187 offset:4096
	ds_read_b128 v[196:199], v187 offset:5120
	ds_read_b128 v[200:203], v187 offset:6144
	ds_read_b128 v[204:207], v187 offset:7168
	global_load_lds_dwordx4 v178, s[80:81]
	s_add_i32 m0, s29, 0xe000
	s_nop 0
	global_load_lds_dwordx4 v180, s[80:81]
	s_waitcnt vmcnt(8)
	s_waitcnt lgkmcnt(0)
	s_barrier
	s_waitcnt lgkmcnt(0)
	v_mfma_f32_16x16x32_bf16 v[124:127], v[128:131], v[160:163], v[124:127]
	v_mfma_f32_16x16x32_bf16 v[124:127], v[132:135], v[164:167], v[124:127]
	v_mfma_f32_16x16x32_bf16 v[116:119], v[144:147], v[160:163], v[116:119]
	v_mfma_f32_16x16x32_bf16 v[116:119], v[148:151], v[164:167], v[116:119]
	v_mfma_f32_16x16x32_bf16 v[120:123], v[136:139], v[160:163], v[120:123]
	v_mfma_f32_16x16x32_bf16 v[120:123], v[140:143], v[164:167], v[120:123]
	v_mfma_f32_16x16x32_bf16 v[112:115], v[152:155], v[160:163], v[112:115]
	v_mfma_f32_16x16x32_bf16 v[112:115], v[156:159], v[164:167], v[112:115]
	v_mfma_f32_16x16x32_bf16 v[108:111], v[128:131], v[182:185], v[108:111]
	v_mfma_f32_16x16x32_bf16 v[108:111], v[132:135], v[188:191], v[108:111]
	v_mfma_f32_16x16x32_bf16 v[100:103], v[144:147], v[182:185], v[100:103]
	v_mfma_f32_16x16x32_bf16 v[100:103], v[148:151], v[188:191], v[100:103]
	v_mfma_f32_16x16x32_bf16 v[104:107], v[136:139], v[182:185], v[104:107]
	v_mfma_f32_16x16x32_bf16 v[104:107], v[140:143], v[188:191], v[104:107]
	v_mfma_f32_16x16x32_bf16 v[96:99], v[152:155], v[182:185], v[96:99]
	v_mfma_f32_16x16x32_bf16 v[96:99], v[156:159], v[188:191], v[96:99]
	v_mfma_f32_16x16x32_bf16 v[92:95], v[128:131], v[192:195], v[92:95]
	v_mfma_f32_16x16x32_bf16 v[92:95], v[132:135], v[196:199], v[92:95]
	v_mfma_f32_16x16x32_bf16 v[84:87], v[144:147], v[192:195], v[84:87]
	v_mfma_f32_16x16x32_bf16 v[84:87], v[148:151], v[196:199], v[84:87]
	v_mfma_f32_16x16x32_bf16 v[88:91], v[136:139], v[192:195], v[88:91]
	v_mfma_f32_16x16x32_bf16 v[88:91], v[140:143], v[196:199], v[88:91]
	v_mfma_f32_16x16x32_bf16 v[80:83], v[152:155], v[192:195], v[80:83]
	v_mfma_f32_16x16x32_bf16 v[80:83], v[156:159], v[196:199], v[80:83]
	v_mfma_f32_16x16x32_bf16 v[76:79], v[128:131], v[200:203], v[76:79]
	v_mfma_f32_16x16x32_bf16 v[76:79], v[132:135], v[204:207], v[76:79]
	v_mfma_f32_16x16x32_bf16 v[68:71], v[144:147], v[200:203], v[68:71]
	v_mfma_f32_16x16x32_bf16 v[68:71], v[148:151], v[204:207], v[68:71]
	v_mfma_f32_16x16x32_bf16 v[72:75], v[136:139], v[200:203], v[72:75]
	v_mfma_f32_16x16x32_bf16 v[72:75], v[140:143], v[204:207], v[72:75]
	v_mfma_f32_16x16x32_bf16 v[64:67], v[152:155], v[200:203], v[64:67]
	v_mfma_f32_16x16x32_bf16 v[64:67], v[156:159], v[204:207], v[64:67]
	s_barrier
	s_add_i32 s90, s90, s24
	s_mov_b32 m0, s90
	ds_read_b128 v[160:163], v187 offset:16384
	ds_read_b128 v[164:167], v187 offset:17408
	ds_read_b128 v[182:185], v187 offset:18432
	ds_read_b128 v[188:191], v187 offset:19456
	ds_read_b128 v[192:195], v187 offset:20480
	ds_read_b128 v[196:199], v187 offset:21504
	ds_read_b128 v[200:203], v187 offset:22528
	ds_read_b128 v[204:207], v187 offset:23552
	global_load_lds_dwordx4 v172, s[82:83]
	s_add_i32 m0, s90, 0x2000
	s_add_u32 s90, s82, 0x80000
	s_addc_u32 s91, s83, 0
	s_add_i32 s67, s67, s24
	global_load_lds_dwordx4 v168, s[82:83]
	s_mov_b32 m0, s67
	s_nop 0
	global_load_lds_dwordx4 v172, s[90:91]
	s_add_i32 m0, s67, 0x2000
	s_nop 0
	global_load_lds_dwordx4 v168, s[90:91]
	s_mov_b32 m0, s29
	s_nop 0
	global_load_lds_dwordx4 v174, s[84:85]
	s_mov_b32 m0, s34
	s_nop 0
	global_load_lds_dwordx4 v170, s[84:85]
	s_waitcnt vmcnt(8)
	s_waitcnt lgkmcnt(0)
	s_barrier
	s_waitcnt lgkmcnt(0)
	v_mfma_f32_16x16x32_bf16 v[60:63], v[128:131], v[160:163], v[60:63]
	v_mfma_f32_16x16x32_bf16 v[60:63], v[132:135], v[164:167], v[60:63]
	v_mfma_f32_16x16x32_bf16 v[52:55], v[144:147], v[160:163], v[52:55]
	v_mfma_f32_16x16x32_bf16 v[52:55], v[148:151], v[164:167], v[52:55]
	v_mfma_f32_16x16x32_bf16 v[56:59], v[136:139], v[160:163], v[56:59]
	v_mfma_f32_16x16x32_bf16 v[56:59], v[140:143], v[164:167], v[56:59]
	v_mfma_f32_16x16x32_bf16 v[48:51], v[152:155], v[160:163], v[48:51]
	v_mfma_f32_16x16x32_bf16 v[48:51], v[156:159], v[164:167], v[48:51]
	v_mfma_f32_16x16x32_bf16 v[44:47], v[128:131], v[182:185], v[44:47]
	v_mfma_f32_16x16x32_bf16 v[44:47], v[132:135], v[188:191], v[44:47]
	v_mfma_f32_16x16x32_bf16 v[36:39], v[144:147], v[182:185], v[36:39]
	v_mfma_f32_16x16x32_bf16 v[36:39], v[148:151], v[188:191], v[36:39]
	v_mfma_f32_16x16x32_bf16 v[40:43], v[136:139], v[182:185], v[40:43]
	v_mfma_f32_16x16x32_bf16 v[40:43], v[140:143], v[188:191], v[40:43]
	v_mfma_f32_16x16x32_bf16 v[32:35], v[152:155], v[182:185], v[32:35]
	v_mfma_f32_16x16x32_bf16 v[32:35], v[156:159], v[188:191], v[32:35]
	v_mfma_f32_16x16x32_bf16 v[28:31], v[128:131], v[192:195], v[28:31]
	v_mfma_f32_16x16x32_bf16 v[28:31], v[132:135], v[196:199], v[28:31]
	v_mfma_f32_16x16x32_bf16 v[20:23], v[144:147], v[192:195], v[20:23]
	v_mfma_f32_16x16x32_bf16 v[20:23], v[148:151], v[196:199], v[20:23]
	v_mfma_f32_16x16x32_bf16 v[24:27], v[136:139], v[192:195], v[24:27]
	v_mfma_f32_16x16x32_bf16 v[24:27], v[140:143], v[196:199], v[24:27]
	v_mfma_f32_16x16x32_bf16 v[16:19], v[152:155], v[192:195], v[16:19]
	v_mfma_f32_16x16x32_bf16 v[16:19], v[156:159], v[196:199], v[16:19]
	v_mfma_f32_16x16x32_bf16 v[12:15], v[128:131], v[200:203], v[12:15]
	v_mfma_f32_16x16x32_bf16 v[12:15], v[132:135], v[204:207], v[12:15]
	v_mfma_f32_16x16x32_bf16 v[4:7], v[144:147], v[200:203], v[4:7]
	v_mfma_f32_16x16x32_bf16 v[4:7], v[148:151], v[204:207], v[4:7]
	v_mfma_f32_16x16x32_bf16 v[8:11], v[136:139], v[200:203], v[8:11]
	v_mfma_f32_16x16x32_bf16 v[8:11], v[140:143], v[204:207], v[8:11]
	v_mfma_f32_16x16x32_bf16 v[0:3], v[152:155], v[200:203], v[0:3]
	v_mfma_f32_16x16x32_bf16 v[0:3], v[156:159], v[204:207], v[0:3]
	s_barrier
	s_add_i32 s67, 0, 0x18000
	s_add_i32 s90, 0, 0x1c000
	v_add_u32_e32 v140, s67, v186
	v_add_u32_e32 v156, s90, v186
	ds_read_b128 v[128:131], v140
	ds_read_b128 v[132:135], v140 offset:1024
	ds_read_b128 v[136:139], v140 offset:2048
	ds_read_b128 v[140:143], v140 offset:3072
	ds_read_b128 v[144:147], v156
	ds_read_b128 v[148:151], v156 offset:1024
	ds_read_b128 v[152:155], v156 offset:2048
	ds_read_b128 v[156:159], v156 offset:3072
	s_add_u32 s84, s84, 0x80000
	s_addc_u32 s85, s85, 0
	s_mov_b32 m0, s35
	ds_read_b128 v[160:163], v187 offset:32768
	ds_read_b128 v[164:167], v187 offset:33792
	ds_read_b128 v[182:185], v187 offset:34816
	ds_read_b128 v[188:191], v187 offset:35840
	ds_read_b128 v[192:195], v187 offset:36864
	ds_read_b128 v[196:199], v187 offset:37888
	ds_read_b128 v[200:203], v187 offset:38912
	ds_read_b128 v[204:207], v187 offset:39936
	global_load_lds_dwordx4 v174, s[84:85]
	s_mov_b32 m0, s38
	s_nop 0
	global_load_lds_dwordx4 v170, s[84:85]
	s_waitcnt vmcnt(8)
	s_waitcnt lgkmcnt(0)
	s_barrier
	s_waitcnt lgkmcnt(0)
	v_mfma_f32_16x16x32_bf16 v[124:127], v[128:131], v[160:163], v[124:127]
	v_mfma_f32_16x16x32_bf16 v[124:127], v[132:135], v[164:167], v[124:127]
	v_mfma_f32_16x16x32_bf16 v[116:119], v[144:147], v[160:163], v[116:119]
	v_mfma_f32_16x16x32_bf16 v[116:119], v[148:151], v[164:167], v[116:119]
	v_mfma_f32_16x16x32_bf16 v[120:123], v[136:139], v[160:163], v[120:123]
	v_mfma_f32_16x16x32_bf16 v[120:123], v[140:143], v[164:167], v[120:123]
	v_mfma_f32_16x16x32_bf16 v[112:115], v[152:155], v[160:163], v[112:115]
	v_mfma_f32_16x16x32_bf16 v[112:115], v[156:159], v[164:167], v[112:115]
	v_mfma_f32_16x16x32_bf16 v[108:111], v[128:131], v[182:185], v[108:111]
	v_mfma_f32_16x16x32_bf16 v[108:111], v[132:135], v[188:191], v[108:111]
	v_mfma_f32_16x16x32_bf16 v[100:103], v[144:147], v[182:185], v[100:103]
	v_mfma_f32_16x16x32_bf16 v[100:103], v[148:151], v[188:191], v[100:103]
	v_mfma_f32_16x16x32_bf16 v[104:107], v[136:139], v[182:185], v[104:107]
	v_mfma_f32_16x16x32_bf16 v[104:107], v[140:143], v[188:191], v[104:107]
	v_mfma_f32_16x16x32_bf16 v[96:99], v[152:155], v[182:185], v[96:99]
	v_mfma_f32_16x16x32_bf16 v[96:99], v[156:159], v[188:191], v[96:99]
	v_mfma_f32_16x16x32_bf16 v[92:95], v[128:131], v[192:195], v[92:95]
	v_mfma_f32_16x16x32_bf16 v[92:95], v[132:135], v[196:199], v[92:95]
	v_mfma_f32_16x16x32_bf16 v[84:87], v[144:147], v[192:195], v[84:87]
	v_mfma_f32_16x16x32_bf16 v[84:87], v[148:151], v[196:199], v[84:87]
	v_mfma_f32_16x16x32_bf16 v[88:91], v[136:139], v[192:195], v[88:91]
	v_mfma_f32_16x16x32_bf16 v[88:91], v[140:143], v[196:199], v[88:91]
	v_mfma_f32_16x16x32_bf16 v[80:83], v[152:155], v[192:195], v[80:83]
	v_mfma_f32_16x16x32_bf16 v[80:83], v[156:159], v[196:199], v[80:83]
	v_mfma_f32_16x16x32_bf16 v[76:79], v[128:131], v[200:203], v[76:79]
	v_mfma_f32_16x16x32_bf16 v[76:79], v[132:135], v[204:207], v[76:79]
	v_mfma_f32_16x16x32_bf16 v[68:71], v[144:147], v[200:203], v[68:71]
	v_mfma_f32_16x16x32_bf16 v[68:71], v[148:151], v[204:207], v[68:71]
	v_mfma_f32_16x16x32_bf16 v[72:75], v[136:139], v[200:203], v[72:75]
	v_mfma_f32_16x16x32_bf16 v[72:75], v[140:143], v[204:207], v[72:75]
	v_mfma_f32_16x16x32_bf16 v[64:67], v[152:155], v[200:203], v[64:67]
	v_mfma_f32_16x16x32_bf16 v[64:67], v[156:159], v[204:207], v[64:67]
	s_barrier
	s_add_i32 s67, s67, s24
	s_add_u32 s98, s82, 0x80
	s_addc_u32 s99, s83, 0
	s_mov_b32 m0, s67
	ds_read_b128 v[160:163], v187 offset:49152
	ds_read_b128 v[164:167], v187 offset:50176
	ds_read_b128 v[182:185], v187 offset:51200
	ds_read_b128 v[188:191], v187 offset:52224
	ds_read_b128 v[192:195], v187 offset:53248
	ds_read_b128 v[196:199], v187 offset:54272
	ds_read_b128 v[200:203], v187 offset:55296
	ds_read_b128 v[204:207], v187 offset:56320
	global_load_lds_dwordx4 v172, s[98:99]
	s_add_i32 m0, s67, 0x2000
	s_add_u32 s82, s82, 0x80080
	s_addc_u32 s83, s83, 0
	s_add_i32 s67, s90, s24
	global_load_lds_dwordx4 v168, s[98:99]
	s_mov_b32 m0, s67
	s_nop 0
	global_load_lds_dwordx4 v172, s[82:83]
	s_add_i32 m0, s67, 0x2000
	s_nop 0
	global_load_lds_dwordx4 v168, s[82:83]
	s_add_u32 s98, s84, 0xfff80080
	s_addc_u32 s99, s85, -1
	s_mov_b32 m0, s54
	s_nop 0
	global_load_lds_dwordx4 v174, s[98:99]
	s_mov_b32 m0, s55
	s_nop 0
	global_load_lds_dwordx4 v170, s[98:99]
	s_waitcnt vmcnt(8)
	s_waitcnt lgkmcnt(0)
	s_barrier
	s_waitcnt lgkmcnt(0)
	v_mfma_f32_16x16x32_bf16 v[60:63], v[128:131], v[160:163], v[60:63]
	v_mfma_f32_16x16x32_bf16 v[60:63], v[132:135], v[164:167], v[60:63]
	v_mfma_f32_16x16x32_bf16 v[52:55], v[144:147], v[160:163], v[52:55]
	v_mfma_f32_16x16x32_bf16 v[52:55], v[148:151], v[164:167], v[52:55]
	v_mfma_f32_16x16x32_bf16 v[56:59], v[136:139], v[160:163], v[56:59]
	v_mfma_f32_16x16x32_bf16 v[56:59], v[140:143], v[164:167], v[56:59]
	v_mfma_f32_16x16x32_bf16 v[48:51], v[152:155], v[160:163], v[48:51]
	v_mfma_f32_16x16x32_bf16 v[48:51], v[156:159], v[164:167], v[48:51]
	v_mfma_f32_16x16x32_bf16 v[44:47], v[128:131], v[182:185], v[44:47]
	v_mfma_f32_16x16x32_bf16 v[44:47], v[132:135], v[188:191], v[44:47]
	v_mfma_f32_16x16x32_bf16 v[36:39], v[144:147], v[182:185], v[36:39]
	v_mfma_f32_16x16x32_bf16 v[36:39], v[148:151], v[188:191], v[36:39]
	v_mfma_f32_16x16x32_bf16 v[40:43], v[136:139], v[182:185], v[40:43]
	v_mfma_f32_16x16x32_bf16 v[40:43], v[140:143], v[188:191], v[40:43]
	v_mfma_f32_16x16x32_bf16 v[32:35], v[152:155], v[182:185], v[32:35]
	v_mfma_f32_16x16x32_bf16 v[32:35], v[156:159], v[188:191], v[32:35]
	v_mfma_f32_16x16x32_bf16 v[28:31], v[128:131], v[192:195], v[28:31]
	v_mfma_f32_16x16x32_bf16 v[28:31], v[132:135], v[196:199], v[28:31]
	v_mfma_f32_16x16x32_bf16 v[20:23], v[144:147], v[192:195], v[20:23]
	v_mfma_f32_16x16x32_bf16 v[20:23], v[148:151], v[196:199], v[20:23]
	v_mfma_f32_16x16x32_bf16 v[24:27], v[136:139], v[192:195], v[24:27]
	v_mfma_f32_16x16x32_bf16 v[24:27], v[140:143], v[196:199], v[24:27]
	v_mfma_f32_16x16x32_bf16 v[16:19], v[152:155], v[192:195], v[16:19]
	v_mfma_f32_16x16x32_bf16 v[16:19], v[156:159], v[196:199], v[16:19]
	v_mfma_f32_16x16x32_bf16 v[12:15], v[128:131], v[200:203], v[12:15]
	v_mfma_f32_16x16x32_bf16 v[12:15], v[132:135], v[204:207], v[12:15]
	v_mfma_f32_16x16x32_bf16 v[4:7], v[144:147], v[200:203], v[4:7]
	v_mfma_f32_16x16x32_bf16 v[4:7], v[148:151], v[204:207], v[4:7]
	v_mfma_f32_16x16x32_bf16 v[8:11], v[136:139], v[200:203], v[8:11]
	v_mfma_f32_16x16x32_bf16 v[8:11], v[140:143], v[204:207], v[8:11]
	v_mfma_f32_16x16x32_bf16 v[0:3], v[152:155], v[200:203], v[0:3]
	v_mfma_f32_16x16x32_bf16 v[0:3], v[156:159], v[204:207], v[0:3]
	s_barrier
	s_add_i32 s89, s89, 2
	s_add_u32 s80, s80, 0x100
	s_addc_u32 s81, s81, 0
	s_add_u32 s87, s87, 0x100
	s_addc_u32 s88, s88, 0
	s_cmp_gt_u32 s89, 29
	s_cbranch_scc0 .LBB0_385
	s_and_b64 vcc, exec, s[18:19]
	s_cbranch_vccz .LBB0_388
	s_barrier

.LBB0_594:
	s_ashr_i32 s81, s80, 31
	s_lshl_b64 s[84:85], s[80:81], 20
	s_add_u32 s84, s29, s84
	s_addc_u32 s85, s34, s85
	s_and_b64 s[86:87], s[82:83], exec
	s_cselect_b32 s81, s85, s95
	s_cselect_b32 vcc_lo, s84, s94
	s_ashr_i32 s79, s78, 31
	s_lshl_b64 s[86:87], s[78:79], 20
	s_add_u32 s86, s35, s86
	s_addc_u32 s87, s38, s87
	s_and_b64 s[2:3], s[82:83], exec
	s_cselect_b32 s79, s87, s93
	s_cselect_b32 vcc_hi, s86, s92
	s_lshl_b32 s88, s88, 8
	s_ashr_i32 s89, s88, 31
	s_lshl_b64 s[2:3], s[88:89], 2
	s_add_u32 s2, s90, s2
	s_addc_u32 s3, s91, s3
	s_add_i32 m0, s14, s41
	s_add_u32 s90, s94, 0x80080
	global_load_lds_dwordx4 v239, s[2:3]
	s_addc_u32 s91, s95, 0
	s_add_u32 s89, s92, 0x100
	s_addc_u32 s14, s93, 0
	s_mov_b32 s20, -2
	s_waitcnt vmcnt(0)
	s_add_u32 s2, s90, 0xfff80080
	s_addc_u32 s3, s91, -1
	s_add_i32 s67, 0, 0x10000
	s_cmp_eq_u32 s20, 28
	s_cselect_b32 s95, s81, s3
	s_cselect_b32 s94, vcc_lo, s2
	s_cselect_b32 s93, s79, s14
	s_cselect_b32 s92, vcc_hi, s89
	s_add_i32 s76, 0, 0x14000
	v_add_u32_e32 v96, s67, v238
	v_add_u32_e32 v140, s76, v238
	ds_read_b128 v[64:67], v96
	ds_read_b128 v[72:75], v96 offset:1024
	ds_read_b128 v[88:91], v96 offset:2048
	ds_read_b128 v[96:99], v96 offset:3072
	ds_read_b128 v[108:111], v140
	ds_read_b128 v[116:119], v140 offset:1024
	ds_read_b128 v[128:131], v140 offset:2048
	ds_read_b128 v[140:143], v140 offset:3072
	s_add_i32 m0, s39, 0xc000
	ds_read_b128 v[152:155], v240
	ds_read_b128 v[156:159], v240 offset:1024
	ds_read_b128 v[160:163], v240 offset:2048
	ds_read_b128 v[164:167], v240 offset:3072
	ds_read_b128 v[168:171], v240 offset:4096
	ds_read_b128 v[180:183], v240 offset:5120
	ds_read_b128 v[184:187], v240 offset:6144
	ds_read_b128 v[188:191], v240 offset:7168
	global_load_lds_dwordx4 v230, s[90:91]
	s_add_i32 m0, s39, 0xe000
	s_nop 0
	global_load_lds_dwordx4 v232, s[90:91]
	s_waitcnt vmcnt(8)
	s_waitcnt lgkmcnt(0)
	s_barrier
	s_waitcnt lgkmcnt(0)
	v_mfma_f32_16x16x32_bf16 v[176:179], v[64:67], v[152:155], 0
	v_mfma_f32_16x16x32_bf16 v[176:179], v[72:75], v[156:159], v[176:179]
	v_mfma_f32_16x16x32_bf16 v[148:151], v[108:111], v[152:155], 0
	v_mfma_f32_16x16x32_bf16 v[148:151], v[116:119], v[156:159], v[148:151]
	v_mfma_f32_16x16x32_bf16 v[172:175], v[88:91], v[152:155], 0
	v_mfma_f32_16x16x32_bf16 v[172:175], v[96:99], v[156:159], v[172:175]
	v_mfma_f32_16x16x32_bf16 v[144:147], v[128:131], v[152:155], 0
	v_mfma_f32_16x16x32_bf16 v[144:147], v[140:143], v[156:159], v[144:147]
	v_mfma_f32_16x16x32_bf16 v[136:139], v[64:67], v[160:163], 0
	v_mfma_f32_16x16x32_bf16 v[136:139], v[72:75], v[164:167], v[136:139]
	v_mfma_f32_16x16x32_bf16 v[124:127], v[108:111], v[160:163], 0
	v_mfma_f32_16x16x32_bf16 v[124:127], v[116:119], v[164:167], v[124:127]
	v_mfma_f32_16x16x32_bf16 v[132:135], v[88:91], v[160:163], 0
	v_mfma_f32_16x16x32_bf16 v[132:135], v[96:99], v[164:167], v[132:135]
	v_mfma_f32_16x16x32_bf16 v[120:123], v[128:131], v[160:163], 0
	v_mfma_f32_16x16x32_bf16 v[120:123], v[140:143], v[164:167], v[120:123]
	v_mfma_f32_16x16x32_bf16 v[112:115], v[64:67], v[168:171], 0
	v_mfma_f32_16x16x32_bf16 v[112:115], v[72:75], v[180:183], v[112:115]
	v_mfma_f32_16x16x32_bf16 v[100:103], v[108:111], v[168:171], 0
	v_mfma_f32_16x16x32_bf16 v[100:103], v[116:119], v[180:183], v[100:103]
	v_mfma_f32_16x16x32_bf16 v[104:107], v[88:91], v[168:171], 0
	v_mfma_f32_16x16x32_bf16 v[104:107], v[96:99], v[180:183], v[104:107]
	v_mfma_f32_16x16x32_bf16 v[92:95], v[128:131], v[168:171], 0
	v_mfma_f32_16x16x32_bf16 v[92:95], v[140:143], v[180:183], v[92:95]
	v_mfma_f32_16x16x32_bf16 v[84:87], v[64:67], v[184:187], 0
	v_mfma_f32_16x16x32_bf16 v[84:87], v[72:75], v[188:191], v[84:87]
	v_mfma_f32_16x16x32_bf16 v[76:79], v[108:111], v[184:187], 0
	v_mfma_f32_16x16x32_bf16 v[76:79], v[116:119], v[188:191], v[76:79]
	v_mfma_f32_16x16x32_bf16 v[80:83], v[88:91], v[184:187], 0
	v_mfma_f32_16x16x32_bf16 v[80:83], v[96:99], v[188:191], v[80:83]
	v_mfma_f32_16x16x32_bf16 v[68:71], v[128:131], v[184:187], 0
	v_mfma_f32_16x16x32_bf16 v[68:71], v[140:143], v[188:191], v[68:71]
	s_barrier
	s_add_i32 s2, s67, s28
	s_mov_b32 m0, s2
	ds_read_b128 v[152:155], v240 offset:16384
	ds_read_b128 v[156:159], v240 offset:17408
	ds_read_b128 v[160:163], v240 offset:18432
	ds_read_b128 v[164:167], v240 offset:19456
	ds_read_b128 v[168:171], v240 offset:20480
	ds_read_b128 v[180:183], v240 offset:21504
	ds_read_b128 v[184:187], v240 offset:22528
	ds_read_b128 v[188:191], v240 offset:23552
	global_load_lds_dwordx4 v216, s[92:93]
	s_add_i32 m0, s2, 0x2000
	s_add_u32 s2, s92, 0x80000
	s_addc_u32 s3, s93, 0
	s_add_i32 s67, s76, s28
	global_load_lds_dwordx4 v228, s[92:93]
	s_mov_b32 m0, s67
	s_nop 0
	global_load_lds_dwordx4 v216, s[2:3]
	s_add_i32 m0, s67, 0x2000
	s_nop 0
	global_load_lds_dwordx4 v228, s[2:3]
	s_mov_b32 m0, s39
	s_nop 0
	global_load_lds_dwordx4 v224, s[94:95]
	s_mov_b32 m0, s53
	s_nop 0
	global_load_lds_dwordx4 v226, s[94:95]
	s_waitcnt vmcnt(8)
	s_waitcnt lgkmcnt(0)
	s_barrier
	s_waitcnt lgkmcnt(0)
	v_mfma_f32_16x16x32_bf16 v[60:63], v[64:67], v[152:155], 0
	v_mfma_f32_16x16x32_bf16 v[60:63], v[72:75], v[156:159], v[60:63]
	v_mfma_f32_16x16x32_bf16 v[52:55], v[108:111], v[152:155], 0
	v_mfma_f32_16x16x32_bf16 v[52:55], v[116:119], v[156:159], v[52:55]
	v_mfma_f32_16x16x32_bf16 v[56:59], v[88:91], v[152:155], 0
	v_mfma_f32_16x16x32_bf16 v[56:59], v[96:99], v[156:159], v[56:59]
	v_mfma_f32_16x16x32_bf16 v[48:51], v[128:131], v[152:155], 0
	v_mfma_f32_16x16x32_bf16 v[48:51], v[140:143], v[156:159], v[48:51]
	v_mfma_f32_16x16x32_bf16 v[44:47], v[64:67], v[160:163], 0
	v_mfma_f32_16x16x32_bf16 v[44:47], v[72:75], v[164:167], v[44:47]
	v_mfma_f32_16x16x32_bf16 v[36:39], v[108:111], v[160:163], 0
	v_mfma_f32_16x16x32_bf16 v[36:39], v[116:119], v[164:167], v[36:39]
	v_mfma_f32_16x16x32_bf16 v[40:43], v[88:91], v[160:163], 0
	v_mfma_f32_16x16x32_bf16 v[40:43], v[96:99], v[164:167], v[40:43]
	v_mfma_f32_16x16x32_bf16 v[32:35], v[128:131], v[160:163], 0
	v_mfma_f32_16x16x32_bf16 v[32:35], v[140:143], v[164:167], v[32:35]
	v_mfma_f32_16x16x32_bf16 v[28:31], v[64:67], v[168:171], 0
	v_mfma_f32_16x16x32_bf16 v[28:31], v[72:75], v[180:183], v[28:31]
	v_mfma_f32_16x16x32_bf16 v[20:23], v[108:111], v[168:171], 0
	v_mfma_f32_16x16x32_bf16 v[20:23], v[116:119], v[180:183], v[20:23]
	v_mfma_f32_16x16x32_bf16 v[24:27], v[88:91], v[168:171], 0
	v_mfma_f32_16x16x32_bf16 v[24:27], v[96:99], v[180:183], v[24:27]
	v_mfma_f32_16x16x32_bf16 v[16:19], v[128:131], v[168:171], 0
	v_mfma_f32_16x16x32_bf16 v[16:19], v[140:143], v[180:183], v[16:19]
	v_mfma_f32_16x16x32_bf16 v[12:15], v[64:67], v[184:187], 0
	v_mfma_f32_16x16x32_bf16 v[12:15], v[72:75], v[188:191], v[12:15]
	v_mfma_f32_16x16x32_bf16 v[4:7], v[108:111], v[184:187], 0
	v_mfma_f32_16x16x32_bf16 v[4:7], v[116:119], v[188:191], v[4:7]
	v_mfma_f32_16x16x32_bf16 v[8:11], v[88:91], v[184:187], 0
	v_mfma_f32_16x16x32_bf16 v[8:11], v[96:99], v[188:191], v[8:11]
	v_mfma_f32_16x16x32_bf16 v[0:3], v[128:131], v[184:187], 0
	v_mfma_f32_16x16x32_bf16 v[0:3], v[140:143], v[188:191], v[0:3]
	s_barrier
	s_add_i32 s67, 0, 0x18000
	s_add_i32 s76, 0, 0x1c000
	v_add_u32_e32 v96, s67, v238
	v_add_u32_e32 v140, s76, v238
	ds_read_b128 v[64:67], v96
	ds_read_b128 v[72:75], v96 offset:1024
	ds_read_b128 v[88:91], v96 offset:2048
	ds_read_b128 v[96:99], v96 offset:3072
	ds_read_b128 v[108:111], v140
	ds_read_b128 v[116:119], v140 offset:1024
	ds_read_b128 v[128:131], v140 offset:2048
	ds_read_b128 v[140:143], v140 offset:3072
	s_add_u32 s2, s94, 0x80000
	s_addc_u32 s3, s95, 0
	s_mov_b32 m0, s55
	ds_read_b128 v[152:155], v240 offset:32768
	ds_read_b128 v[156:159], v240 offset:33792
	ds_read_b128 v[160:163], v240 offset:34816
	ds_read_b128 v[164:167], v240 offset:35840
	ds_read_b128 v[168:171], v240 offset:36864
	ds_read_b128 v[180:183], v240 offset:37888
	ds_read_b128 v[184:187], v240 offset:38912
	ds_read_b128 v[188:191], v240 offset:39936
	global_load_lds_dwordx4 v224, s[2:3]
	s_mov_b32 m0, s56
	s_nop 0
	global_load_lds_dwordx4 v226, s[2:3]
	s_waitcnt vmcnt(8)
	s_waitcnt lgkmcnt(0)
	s_barrier
	s_waitcnt lgkmcnt(0)
	v_mfma_f32_16x16x32_bf16 v[176:179], v[64:67], v[152:155], v[176:179]
	v_mfma_f32_16x16x32_bf16 v[176:179], v[72:75], v[156:159], v[176:179]
	v_mfma_f32_16x16x32_bf16 v[148:151], v[108:111], v[152:155], v[148:151]
	v_mfma_f32_16x16x32_bf16 v[148:151], v[116:119], v[156:159], v[148:151]
	v_mfma_f32_16x16x32_bf16 v[172:175], v[88:91], v[152:155], v[172:175]
	v_mfma_f32_16x16x32_bf16 v[172:175], v[96:99], v[156:159], v[172:175]
	v_mfma_f32_16x16x32_bf16 v[144:147], v[128:131], v[152:155], v[144:147]
	v_mfma_f32_16x16x32_bf16 v[144:147], v[140:143], v[156:159], v[144:147]
	v_mfma_f32_16x16x32_bf16 v[136:139], v[64:67], v[160:163], v[136:139]
	v_mfma_f32_16x16x32_bf16 v[136:139], v[72:75], v[164:167], v[136:139]
	v_mfma_f32_16x16x32_bf16 v[124:127], v[108:111], v[160:163], v[124:127]
	v_mfma_f32_16x16x32_bf16 v[124:127], v[116:119], v[164:167], v[124:127]
	v_mfma_f32_16x16x32_bf16 v[132:135], v[88:91], v[160:163], v[132:135]
	v_mfma_f32_16x16x32_bf16 v[132:135], v[96:99], v[164:167], v[132:135]
	v_mfma_f32_16x16x32_bf16 v[120:123], v[128:131], v[160:163], v[120:123]
	v_mfma_f32_16x16x32_bf16 v[120:123], v[140:143], v[164:167], v[120:123]
	v_mfma_f32_16x16x32_bf16 v[112:115], v[64:67], v[168:171], v[112:115]
	v_mfma_f32_16x16x32_bf16 v[112:115], v[72:75], v[180:183], v[112:115]
	v_mfma_f32_16x16x32_bf16 v[100:103], v[108:111], v[168:171], v[100:103]
	v_mfma_f32_16x16x32_bf16 v[100:103], v[116:119], v[180:183], v[100:103]
	v_mfma_f32_16x16x32_bf16 v[104:107], v[88:91], v[168:171], v[104:107]
	v_mfma_f32_16x16x32_bf16 v[104:107], v[96:99], v[180:183], v[104:107]
	v_mfma_f32_16x16x32_bf16 v[92:95], v[128:131], v[168:171], v[92:95]
	v_mfma_f32_16x16x32_bf16 v[92:95], v[140:143], v[180:183], v[92:95]
	v_mfma_f32_16x16x32_bf16 v[84:87], v[64:67], v[184:187], v[84:87]
	v_mfma_f32_16x16x32_bf16 v[84:87], v[72:75], v[188:191], v[84:87]
	v_mfma_f32_16x16x32_bf16 v[76:79], v[108:111], v[184:187], v[76:79]
	v_mfma_f32_16x16x32_bf16 v[76:79], v[116:119], v[188:191], v[76:79]
	v_mfma_f32_16x16x32_bf16 v[80:83], v[88:91], v[184:187], v[80:83]
	v_mfma_f32_16x16x32_bf16 v[80:83], v[96:99], v[188:191], v[80:83]
	v_mfma_f32_16x16x32_bf16 v[68:71], v[128:131], v[184:187], v[68:71]
	v_mfma_f32_16x16x32_bf16 v[68:71], v[140:143], v[188:191], v[68:71]
	s_barrier
	s_add_i32 s2, s67, s28
	s_add_u32 s98, s92, 0x80
	s_addc_u32 s99, s93, 0
	s_mov_b32 m0, s2
	ds_read_b128 v[152:155], v240 offset:49152
	ds_read_b128 v[156:159], v240 offset:50176
	ds_read_b128 v[160:163], v240 offset:51200
	ds_read_b128 v[164:167], v240 offset:52224
	ds_read_b128 v[168:171], v240 offset:53248
	ds_read_b128 v[180:183], v240 offset:54272
	ds_read_b128 v[184:187], v240 offset:55296
	ds_read_b128 v[188:191], v240 offset:56320
	global_load_lds_dwordx4 v216, s[98:99]
	s_add_i32 m0, s2, 0x2000
	s_add_u32 s2, s92, 0x80080
	s_addc_u32 s3, s93, 0
	s_add_i32 s67, s76, s28
	global_load_lds_dwordx4 v228, s[98:99]
	s_mov_b32 m0, s67
	s_nop 0
	global_load_lds_dwordx4 v216, s[2:3]
	s_add_i32 m0, s67, 0x2000
	s_nop 0
	global_load_lds_dwordx4 v228, s[2:3]
	s_add_u32 s98, s94, 0x80
	s_addc_u32 s99, s95, 0
	s_mov_b32 m0, s70
	s_nop 0
	global_load_lds_dwordx4 v224, s[98:99]
	s_mov_b32 m0, s71
	s_nop 0
	global_load_lds_dwordx4 v226, s[98:99]
	s_waitcnt vmcnt(8)
	s_waitcnt lgkmcnt(0)
	s_barrier
	s_waitcnt lgkmcnt(0)
	v_mfma_f32_16x16x32_bf16 v[60:63], v[64:67], v[152:155], v[60:63]
	v_mfma_f32_16x16x32_bf16 v[60:63], v[72:75], v[156:159], v[60:63]
	v_mfma_f32_16x16x32_bf16 v[52:55], v[108:111], v[152:155], v[52:55]
	v_mfma_f32_16x16x32_bf16 v[52:55], v[116:119], v[156:159], v[52:55]
	v_mfma_f32_16x16x32_bf16 v[56:59], v[88:91], v[152:155], v[56:59]
	v_mfma_f32_16x16x32_bf16 v[56:59], v[96:99], v[156:159], v[56:59]
	v_mfma_f32_16x16x32_bf16 v[48:51], v[128:131], v[152:155], v[48:51]
	v_mfma_f32_16x16x32_bf16 v[48:51], v[140:143], v[156:159], v[48:51]
	v_mfma_f32_16x16x32_bf16 v[44:47], v[64:67], v[160:163], v[44:47]
	v_mfma_f32_16x16x32_bf16 v[44:47], v[72:75], v[164:167], v[44:47]
	v_mfma_f32_16x16x32_bf16 v[36:39], v[108:111], v[160:163], v[36:39]
	v_mfma_f32_16x16x32_bf16 v[36:39], v[116:119], v[164:167], v[36:39]
	v_mfma_f32_16x16x32_bf16 v[40:43], v[88:91], v[160:163], v[40:43]
	v_mfma_f32_16x16x32_bf16 v[40:43], v[96:99], v[164:167], v[40:43]
	v_mfma_f32_16x16x32_bf16 v[32:35], v[128:131], v[160:163], v[32:35]
	v_mfma_f32_16x16x32_bf16 v[32:35], v[140:143], v[164:167], v[32:35]
	v_mfma_f32_16x16x32_bf16 v[28:31], v[64:67], v[168:171], v[28:31]
	v_mfma_f32_16x16x32_bf16 v[28:31], v[72:75], v[180:183], v[28:31]
	v_mfma_f32_16x16x32_bf16 v[20:23], v[108:111], v[168:171], v[20:23]
	v_mfma_f32_16x16x32_bf16 v[20:23], v[116:119], v[180:183], v[20:23]
	v_mfma_f32_16x16x32_bf16 v[24:27], v[88:91], v[168:171], v[24:27]
	v_mfma_f32_16x16x32_bf16 v[24:27], v[96:99], v[180:183], v[24:27]
	v_mfma_f32_16x16x32_bf16 v[16:19], v[128:131], v[168:171], v[16:19]
	v_mfma_f32_16x16x32_bf16 v[16:19], v[140:143], v[180:183], v[16:19]
	v_mfma_f32_16x16x32_bf16 v[12:15], v[64:67], v[184:187], v[12:15]
	v_mfma_f32_16x16x32_bf16 v[12:15], v[72:75], v[188:191], v[12:15]
	v_mfma_f32_16x16x32_bf16 v[4:7], v[108:111], v[184:187], v[4:7]
	v_mfma_f32_16x16x32_bf16 v[4:7], v[116:119], v[188:191], v[4:7]
	v_mfma_f32_16x16x32_bf16 v[8:11], v[88:91], v[184:187], v[8:11]
	v_mfma_f32_16x16x32_bf16 v[8:11], v[96:99], v[188:191], v[8:11]
	v_mfma_f32_16x16x32_bf16 v[0:3], v[128:131], v[184:187], v[0:3]
	v_mfma_f32_16x16x32_bf16 v[0:3], v[140:143], v[188:191], v[0:3]
	s_barrier
	s_add_i32 s20, s20, 2
	s_add_u32 s90, s90, 0x100
	s_addc_u32 s91, s91, 0
	s_add_u32 s89, s89, 0x100
	s_addc_u32 s14, s14, 0
.LBB0_595:
	s_add_u32 s2, s90, 0xfff80080
	s_addc_u32 s3, s91, -1
	s_add_i32 s67, 0, 0x10000
	s_cmp_eq_u32 s20, 28
	s_cselect_b32 s95, s81, s3
	s_cselect_b32 s94, vcc_lo, s2
	s_cselect_b32 s93, s79, s14
	s_cselect_b32 s92, vcc_hi, s89
	s_add_i32 s76, 0, 0x14000
	v_add_u32_e32 v96, s67, v238
	v_add_u32_e32 v140, s76, v238
	ds_read_b128 v[64:67], v96
	ds_read_b128 v[72:75], v96 offset:1024
	ds_read_b128 v[88:91], v96 offset:2048
	ds_read_b128 v[96:99], v96 offset:3072
	ds_read_b128 v[108:111], v140
	ds_read_b128 v[116:119], v140 offset:1024
	ds_read_b128 v[128:131], v140 offset:2048
	ds_read_b128 v[140:143], v140 offset:3072
	s_add_i32 m0, s39, 0xc000
	ds_read_b128 v[152:155], v240
	ds_read_b128 v[156:159], v240 offset:1024
	ds_read_b128 v[160:163], v240 offset:2048
	ds_read_b128 v[164:167], v240 offset:3072
	ds_read_b128 v[168:171], v240 offset:4096
	ds_read_b128 v[180:183], v240 offset:5120
	ds_read_b128 v[184:187], v240 offset:6144
	ds_read_b128 v[188:191], v240 offset:7168
	global_load_lds_dwordx4 v230, s[90:91]
	s_add_i32 m0, s39, 0xe000
	s_nop 0
	global_load_lds_dwordx4 v232, s[90:91]
	s_waitcnt vmcnt(8)
	s_waitcnt lgkmcnt(0)
	s_barrier
	s_waitcnt lgkmcnt(0)
	v_mfma_f32_16x16x32_bf16 v[176:179], v[64:67], v[152:155], v[176:179]
	v_mfma_f32_16x16x32_bf16 v[176:179], v[72:75], v[156:159], v[176:179]
	v_mfma_f32_16x16x32_bf16 v[148:151], v[108:111], v[152:155], v[148:151]
	v_mfma_f32_16x16x32_bf16 v[148:151], v[116:119], v[156:159], v[148:151]
	v_mfma_f32_16x16x32_bf16 v[172:175], v[88:91], v[152:155], v[172:175]
	v_mfma_f32_16x16x32_bf16 v[172:175], v[96:99], v[156:159], v[172:175]
	v_mfma_f32_16x16x32_bf16 v[144:147], v[128:131], v[152:155], v[144:147]
	v_mfma_f32_16x16x32_bf16 v[144:147], v[140:143], v[156:159], v[144:147]
	v_mfma_f32_16x16x32_bf16 v[136:139], v[64:67], v[160:163], v[136:139]
	v_mfma_f32_16x16x32_bf16 v[136:139], v[72:75], v[164:167], v[136:139]
	v_mfma_f32_16x16x32_bf16 v[124:127], v[108:111], v[160:163], v[124:127]
	v_mfma_f32_16x16x32_bf16 v[124:127], v[116:119], v[164:167], v[124:127]
	v_mfma_f32_16x16x32_bf16 v[132:135], v[88:91], v[160:163], v[132:135]
	v_mfma_f32_16x16x32_bf16 v[132:135], v[96:99], v[164:167], v[132:135]
	v_mfma_f32_16x16x32_bf16 v[120:123], v[128:131], v[160:163], v[120:123]
	v_mfma_f32_16x16x32_bf16 v[120:123], v[140:143], v[164:167], v[120:123]
	v_mfma_f32_16x16x32_bf16 v[112:115], v[64:67], v[168:171], v[112:115]
	v_mfma_f32_16x16x32_bf16 v[112:115], v[72:75], v[180:183], v[112:115]
	v_mfma_f32_16x16x32_bf16 v[100:103], v[108:111], v[168:171], v[100:103]
	v_mfma_f32_16x16x32_bf16 v[100:103], v[116:119], v[180:183], v[100:103]
	v_mfma_f32_16x16x32_bf16 v[104:107], v[88:91], v[168:171], v[104:107]
	v_mfma_f32_16x16x32_bf16 v[104:107], v[96:99], v[180:183], v[104:107]
	v_mfma_f32_16x16x32_bf16 v[92:95], v[128:131], v[168:171], v[92:95]
	v_mfma_f32_16x16x32_bf16 v[92:95], v[140:143], v[180:183], v[92:95]
	v_mfma_f32_16x16x32_bf16 v[84:87], v[64:67], v[184:187], v[84:87]
	v_mfma_f32_16x16x32_bf16 v[84:87], v[72:75], v[188:191], v[84:87]
	v_mfma_f32_16x16x32_bf16 v[76:79], v[108:111], v[184:187], v[76:79]
	v_mfma_f32_16x16x32_bf16 v[76:79], v[116:119], v[188:191], v[76:79]
	v_mfma_f32_16x16x32_bf16 v[80:83], v[88:91], v[184:187], v[80:83]
	v_mfma_f32_16x16x32_bf16 v[80:83], v[96:99], v[188:191], v[80:83]
	v_mfma_f32_16x16x32_bf16 v[68:71], v[128:131], v[184:187], v[68:71]
	v_mfma_f32_16x16x32_bf16 v[68:71], v[140:143], v[188:191], v[68:71]
	s_barrier
	s_add_i32 s2, s67, s28
	s_mov_b32 m0, s2
	ds_read_b128 v[152:155], v240 offset:16384
	ds_read_b128 v[156:159], v240 offset:17408
	ds_read_b128 v[160:163], v240 offset:18432
	ds_read_b128 v[164:167], v240 offset:19456
	ds_read_b128 v[168:171], v240 offset:20480
	ds_read_b128 v[180:183], v240 offset:21504
	ds_read_b128 v[184:187], v240 offset:22528
	ds_read_b128 v[188:191], v240 offset:23552
	global_load_lds_dwordx4 v216, s[92:93]
	s_add_i32 m0, s2, 0x2000
	s_add_u32 s2, s92, 0x80000
	s_addc_u32 s3, s93, 0
	s_add_i32 s67, s76, s28
	global_load_lds_dwordx4 v228, s[92:93]
	s_mov_b32 m0, s67
	s_nop 0
	global_load_lds_dwordx4 v216, s[2:3]
	s_add_i32 m0, s67, 0x2000
	s_nop 0
	global_load_lds_dwordx4 v228, s[2:3]
	s_mov_b32 m0, s39
	s_nop 0
	global_load_lds_dwordx4 v224, s[94:95]
	s_mov_b32 m0, s53
	s_nop 0
	global_load_lds_dwordx4 v226, s[94:95]
	s_waitcnt vmcnt(8)
	s_waitcnt lgkmcnt(0)
	s_barrier
	s_waitcnt lgkmcnt(0)
	v_mfma_f32_16x16x32_bf16 v[60:63], v[64:67], v[152:155], v[60:63]
	v_mfma_f32_16x16x32_bf16 v[60:63], v[72:75], v[156:159], v[60:63]
	v_mfma_f32_16x16x32_bf16 v[52:55], v[108:111], v[152:155], v[52:55]
	v_mfma_f32_16x16x32_bf16 v[52:55], v[116:119], v[156:159], v[52:55]
	v_mfma_f32_16x16x32_bf16 v[56:59], v[88:91], v[152:155], v[56:59]
	v_mfma_f32_16x16x32_bf16 v[56:59], v[96:99], v[156:159], v[56:59]
	v_mfma_f32_16x16x32_bf16 v[48:51], v[128:131], v[152:155], v[48:51]
	v_mfma_f32_16x16x32_bf16 v[48:51], v[140:143], v[156:159], v[48:51]
	v_mfma_f32_16x16x32_bf16 v[44:47], v[64:67], v[160:163], v[44:47]
	v_mfma_f32_16x16x32_bf16 v[44:47], v[72:75], v[164:167], v[44:47]
	v_mfma_f32_16x16x32_bf16 v[36:39], v[108:111], v[160:163], v[36:39]
	v_mfma_f32_16x16x32_bf16 v[36:39], v[116:119], v[164:167], v[36:39]
	v_mfma_f32_16x16x32_bf16 v[40:43], v[88:91], v[160:163], v[40:43]
	v_mfma_f32_16x16x32_bf16 v[40:43], v[96:99], v[164:167], v[40:43]
	v_mfma_f32_16x16x32_bf16 v[32:35], v[128:131], v[160:163], v[32:35]
	v_mfma_f32_16x16x32_bf16 v[32:35], v[140:143], v[164:167], v[32:35]
	v_mfma_f32_16x16x32_bf16 v[28:31], v[64:67], v[168:171], v[28:31]
	v_mfma_f32_16x16x32_bf16 v[28:31], v[72:75], v[180:183], v[28:31]
	v_mfma_f32_16x16x32_bf16 v[20:23], v[108:111], v[168:171], v[20:23]
	v_mfma_f32_16x16x32_bf16 v[20:23], v[116:119], v[180:183], v[20:23]
	v_mfma_f32_16x16x32_bf16 v[24:27], v[88:91], v[168:171], v[24:27]
	v_mfma_f32_16x16x32_bf16 v[24:27], v[96:99], v[180:183], v[24:27]
	v_mfma_f32_16x16x32_bf16 v[16:19], v[128:131], v[168:171], v[16:19]
	v_mfma_f32_16x16x32_bf16 v[16:19], v[140:143], v[180:183], v[16:19]
	v_mfma_f32_16x16x32_bf16 v[12:15], v[64:67], v[184:187], v[12:15]
	v_mfma_f32_16x16x32_bf16 v[12:15], v[72:75], v[188:191], v[12:15]
	v_mfma_f32_16x16x32_bf16 v[4:7], v[108:111], v[184:187], v[4:7]
	v_mfma_f32_16x16x32_bf16 v[4:7], v[116:119], v[188:191], v[4:7]
	v_mfma_f32_16x16x32_bf16 v[8:11], v[88:91], v[184:187], v[8:11]
	v_mfma_f32_16x16x32_bf16 v[8:11], v[96:99], v[188:191], v[8:11]
	v_mfma_f32_16x16x32_bf16 v[0:3], v[128:131], v[184:187], v[0:3]
	v_mfma_f32_16x16x32_bf16 v[0:3], v[140:143], v[188:191], v[0:3]
	s_barrier
	s_add_i32 s67, 0, 0x18000
	s_add_i32 s76, 0, 0x1c000
	v_add_u32_e32 v96, s67, v238
	v_add_u32_e32 v140, s76, v238
	ds_read_b128 v[64:67], v96
	ds_read_b128 v[72:75], v96 offset:1024
	ds_read_b128 v[88:91], v96 offset:2048
	ds_read_b128 v[96:99], v96 offset:3072
	ds_read_b128 v[108:111], v140
	ds_read_b128 v[116:119], v140 offset:1024
	ds_read_b128 v[128:131], v140 offset:2048
	ds_read_b128 v[140:143], v140 offset:3072
	s_add_u32 s2, s94, 0x80000
	s_addc_u32 s3, s95, 0
	s_mov_b32 m0, s55
	ds_read_b128 v[152:155], v240 offset:32768
	ds_read_b128 v[156:159], v240 offset:33792
	ds_read_b128 v[160:163], v240 offset:34816
	ds_read_b128 v[164:167], v240 offset:35840
	ds_read_b128 v[168:171], v240 offset:36864
	ds_read_b128 v[180:183], v240 offset:37888
	ds_read_b128 v[184:187], v240 offset:38912
	ds_read_b128 v[188:191], v240 offset:39936
	global_load_lds_dwordx4 v224, s[2:3]
	s_mov_b32 m0, s56
	s_nop 0
	global_load_lds_dwordx4 v226, s[2:3]
	s_waitcnt vmcnt(8)
	s_waitcnt lgkmcnt(0)
	s_barrier
	s_waitcnt lgkmcnt(0)
	v_mfma_f32_16x16x32_bf16 v[176:179], v[64:67], v[152:155], v[176:179]
	v_mfma_f32_16x16x32_bf16 v[176:179], v[72:75], v[156:159], v[176:179]
	v_mfma_f32_16x16x32_bf16 v[148:151], v[108:111], v[152:155], v[148:151]
	v_mfma_f32_16x16x32_bf16 v[148:151], v[116:119], v[156:159], v[148:151]
	v_mfma_f32_16x16x32_bf16 v[172:175], v[88:91], v[152:155], v[172:175]
	v_mfma_f32_16x16x32_bf16 v[172:175], v[96:99], v[156:159], v[172:175]
	v_mfma_f32_16x16x32_bf16 v[144:147], v[128:131], v[152:155], v[144:147]
	v_mfma_f32_16x16x32_bf16 v[144:147], v[140:143], v[156:159], v[144:147]
	v_mfma_f32_16x16x32_bf16 v[136:139], v[64:67], v[160:163], v[136:139]
	v_mfma_f32_16x16x32_bf16 v[136:139], v[72:75], v[164:167], v[136:139]
	v_mfma_f32_16x16x32_bf16 v[124:127], v[108:111], v[160:163], v[124:127]
	v_mfma_f32_16x16x32_bf16 v[124:127], v[116:119], v[164:167], v[124:127]
	v_mfma_f32_16x16x32_bf16 v[132:135], v[88:91], v[160:163], v[132:135]
	v_mfma_f32_16x16x32_bf16 v[132:135], v[96:99], v[164:167], v[132:135]
	v_mfma_f32_16x16x32_bf16 v[120:123], v[128:131], v[160:163], v[120:123]
	v_mfma_f32_16x16x32_bf16 v[120:123], v[140:143], v[164:167], v[120:123]
	v_mfma_f32_16x16x32_bf16 v[112:115], v[64:67], v[168:171], v[112:115]
	v_mfma_f32_16x16x32_bf16 v[112:115], v[72:75], v[180:183], v[112:115]
	v_mfma_f32_16x16x32_bf16 v[100:103], v[108:111], v[168:171], v[100:103]
	v_mfma_f32_16x16x32_bf16 v[100:103], v[116:119], v[180:183], v[100:103]
	v_mfma_f32_16x16x32_bf16 v[104:107], v[88:91], v[168:171], v[104:107]
	v_mfma_f32_16x16x32_bf16 v[104:107], v[96:99], v[180:183], v[104:107]
	v_mfma_f32_16x16x32_bf16 v[92:95], v[128:131], v[168:171], v[92:95]
	v_mfma_f32_16x16x32_bf16 v[92:95], v[140:143], v[180:183], v[92:95]
	v_mfma_f32_16x16x32_bf16 v[84:87], v[64:67], v[184:187], v[84:87]
	v_mfma_f32_16x16x32_bf16 v[84:87], v[72:75], v[188:191], v[84:87]
	v_mfma_f32_16x16x32_bf16 v[76:79], v[108:111], v[184:187], v[76:79]
	v_mfma_f32_16x16x32_bf16 v[76:79], v[116:119], v[188:191], v[76:79]
	v_mfma_f32_16x16x32_bf16 v[80:83], v[88:91], v[184:187], v[80:83]
	v_mfma_f32_16x16x32_bf16 v[80:83], v[96:99], v[188:191], v[80:83]
	v_mfma_f32_16x16x32_bf16 v[68:71], v[128:131], v[184:187], v[68:71]
	v_mfma_f32_16x16x32_bf16 v[68:71], v[140:143], v[188:191], v[68:71]
	s_barrier
	s_add_i32 s2, s67, s28
	s_add_u32 s98, s92, 0x80
	s_addc_u32 s99, s93, 0
	s_mov_b32 m0, s2
	ds_read_b128 v[152:155], v240 offset:49152
	ds_read_b128 v[156:159], v240 offset:50176
	ds_read_b128 v[160:163], v240 offset:51200
	ds_read_b128 v[164:167], v240 offset:52224
	ds_read_b128 v[168:171], v240 offset:53248
	ds_read_b128 v[180:183], v240 offset:54272
	ds_read_b128 v[184:187], v240 offset:55296
	ds_read_b128 v[188:191], v240 offset:56320
	global_load_lds_dwordx4 v216, s[98:99]
	s_add_i32 m0, s2, 0x2000
	s_add_u32 s2, s92, 0x80080
	s_addc_u32 s3, s93, 0
	s_add_i32 s67, s76, s28
	global_load_lds_dwordx4 v228, s[98:99]
	s_mov_b32 m0, s67
	s_nop 0
	global_load_lds_dwordx4 v216, s[2:3]
	s_add_i32 m0, s67, 0x2000
	s_nop 0
	global_load_lds_dwordx4 v228, s[2:3]
	s_add_u32 s98, s94, 0x80
	s_addc_u32 s99, s95, 0
	s_mov_b32 m0, s70
	s_nop 0
	global_load_lds_dwordx4 v224, s[98:99]
	s_mov_b32 m0, s71
	s_nop 0
	global_load_lds_dwordx4 v226, s[98:99]
	s_waitcnt vmcnt(8)
	s_waitcnt lgkmcnt(0)
	s_barrier
	s_waitcnt lgkmcnt(0)
	v_mfma_f32_16x16x32_bf16 v[60:63], v[64:67], v[152:155], v[60:63]
	v_mfma_f32_16x16x32_bf16 v[60:63], v[72:75], v[156:159], v[60:63]
	v_mfma_f32_16x16x32_bf16 v[52:55], v[108:111], v[152:155], v[52:55]
	v_mfma_f32_16x16x32_bf16 v[52:55], v[116:119], v[156:159], v[52:55]
	v_mfma_f32_16x16x32_bf16 v[56:59], v[88:91], v[152:155], v[56:59]
	v_mfma_f32_16x16x32_bf16 v[56:59], v[96:99], v[156:159], v[56:59]
	v_mfma_f32_16x16x32_bf16 v[48:51], v[128:131], v[152:155], v[48:51]
	v_mfma_f32_16x16x32_bf16 v[48:51], v[140:143], v[156:159], v[48:51]
	v_mfma_f32_16x16x32_bf16 v[44:47], v[64:67], v[160:163], v[44:47]
	v_mfma_f32_16x16x32_bf16 v[44:47], v[72:75], v[164:167], v[44:47]
	v_mfma_f32_16x16x32_bf16 v[36:39], v[108:111], v[160:163], v[36:39]
	v_mfma_f32_16x16x32_bf16 v[36:39], v[116:119], v[164:167], v[36:39]
	v_mfma_f32_16x16x32_bf16 v[40:43], v[88:91], v[160:163], v[40:43]
	v_mfma_f32_16x16x32_bf16 v[40:43], v[96:99], v[164:167], v[40:43]
	v_mfma_f32_16x16x32_bf16 v[32:35], v[128:131], v[160:163], v[32:35]
	v_mfma_f32_16x16x32_bf16 v[32:35], v[140:143], v[164:167], v[32:35]
	v_mfma_f32_16x16x32_bf16 v[28:31], v[64:67], v[168:171], v[28:31]
	v_mfma_f32_16x16x32_bf16 v[28:31], v[72:75], v[180:183], v[28:31]
	v_mfma_f32_16x16x32_bf16 v[20:23], v[108:111], v[168:171], v[20:23]
	v_mfma_f32_16x16x32_bf16 v[20:23], v[116:119], v[180:183], v[20:23]
	v_mfma_f32_16x16x32_bf16 v[24:27], v[88:91], v[168:171], v[24:27]
	v_mfma_f32_16x16x32_bf16 v[24:27], v[96:99], v[180:183], v[24:27]
	v_mfma_f32_16x16x32_bf16 v[16:19], v[128:131], v[168:171], v[16:19]
	v_mfma_f32_16x16x32_bf16 v[16:19], v[140:143], v[180:183], v[16:19]
	v_mfma_f32_16x16x32_bf16 v[12:15], v[64:67], v[184:187], v[12:15]
	v_mfma_f32_16x16x32_bf16 v[12:15], v[72:75], v[188:191], v[12:15]
	v_mfma_f32_16x16x32_bf16 v[4:7], v[108:111], v[184:187], v[4:7]
	v_mfma_f32_16x16x32_bf16 v[4:7], v[116:119], v[188:191], v[4:7]
	v_mfma_f32_16x16x32_bf16 v[8:11], v[88:91], v[184:187], v[8:11]
	v_mfma_f32_16x16x32_bf16 v[8:11], v[96:99], v[188:191], v[8:11]
	v_mfma_f32_16x16x32_bf16 v[0:3], v[128:131], v[184:187], v[0:3]
	v_mfma_f32_16x16x32_bf16 v[0:3], v[140:143], v[188:191], v[0:3]
	s_barrier
	s_add_i32 s20, s20, 2
	s_add_u32 s90, s90, 0x100
	s_addc_u32 s91, s91, 0
	s_add_u32 s89, s89, 0x100
	s_addc_u32 s14, s14, 0
	s_cmp_gt_u32 s20, 29
	s_cbranch_scc0 .LBB0_595
	s_and_b64 vcc, exec, s[74:75]
	s_cbranch_vccz .LBB0_598
	s_barrier

.LBB0_638:
	s_ashr_i32 s87, s86, 31
	s_lshl_b64 s[40:41], s[86:87], 20
	s_add_u32 s88, s14, s40
	s_addc_u32 s89, s15, s41
	s_and_b64 s[40:41], s[4:5], exec
	s_cselect_b32 s7, s89, s11
	s_cselect_b32 s9, s88, s10
	s_ashr_i32 s85, s84, 31
	s_lshl_b64 s[40:41], s[84:85], 20
	s_add_u32 s90, s24, s40
	s_addc_u32 s91, s26, s41
	s_and_b64 s[40:41], s[4:5], exec
	s_cselect_b32 s40, s91, s93
	s_cselect_b32 s41, s90, s92
	s_add_u32 s10, s10, 0x80080
	s_addc_u32 s11, s11, 0
	s_add_u32 s54, s92, 0x100
	s_addc_u32 s55, s93, 0
	s_mov_b32 s85, -2
	s_add_u32 s67, s10, 0xfff80080
	s_addc_u32 s87, s11, -1
	s_add_i32 s96, 0, 0x10000
	s_cmp_eq_u32 s85, 28
	s_cselect_b32 s95, s7, s87
	s_cselect_b32 s94, s9, s67
	s_cselect_b32 s93, s40, s55
	s_cselect_b32 s92, s41, s54
	s_add_i32 s67, 0, 0x14000
	v_add_u32_e32 v52, s96, v194
	v_add_u32_e32 v124, s67, v194
	ds_read_b128 v[40:43], v52
	ds_read_b128 v[44:47], v52 offset:1024
	ds_read_b128 v[48:51], v52 offset:2048
	ds_read_b128 v[52:55], v52 offset:3072
	ds_read_b128 v[64:67], v124
	ds_read_b128 v[100:103], v124 offset:1024
	ds_read_b128 v[120:123], v124 offset:2048
	ds_read_b128 v[124:127], v124 offset:3072
	s_add_i32 m0, s57, 0xc000
	ds_read_b128 v[136:139], v195
	ds_read_b128 v[140:143], v195 offset:1024
	ds_read_b128 v[144:147], v195 offset:2048
	ds_read_b128 v[172:175], v195 offset:3072
	ds_read_b128 v[190:193], v195 offset:4096
	ds_read_b128 v[196:199], v195 offset:5120
	ds_read_b128 v[200:203], v195 offset:6144
	ds_read_b128 v[204:207], v195 offset:7168
	global_load_lds_dwordx4 v186, s[10:11]
	s_add_i32 m0, s57, 0xe000
	s_nop 0
	global_load_lds_dwordx4 v188, s[10:11]
	s_waitcnt vmcnt(8)
	s_waitcnt lgkmcnt(0)
	s_barrier
	s_waitcnt lgkmcnt(0)
	v_mfma_f32_16x16x32_bf16 v[168:171], v[40:43], v[136:139], 0
	v_mfma_f32_16x16x32_bf16 v[168:171], v[44:47], v[140:143], v[168:171]
	v_mfma_f32_16x16x32_bf16 v[160:163], v[64:67], v[136:139], 0
	v_mfma_f32_16x16x32_bf16 v[160:163], v[100:103], v[140:143], v[160:163]
	v_mfma_f32_16x16x32_bf16 v[164:167], v[48:51], v[136:139], 0
	v_mfma_f32_16x16x32_bf16 v[164:167], v[52:55], v[140:143], v[164:167]
	v_mfma_f32_16x16x32_bf16 v[132:135], v[64:67], v[144:147], 0
	v_mfma_f32_16x16x32_bf16 v[132:135], v[100:103], v[172:175], v[132:135]
	v_mfma_f32_16x16x32_bf16 v[152:155], v[40:43], v[144:147], 0
	v_mfma_f32_16x16x32_bf16 v[152:155], v[44:47], v[172:175], v[152:155]
	v_mfma_f32_16x16x32_bf16 v[128:131], v[120:123], v[144:147], 0
	v_mfma_f32_16x16x32_bf16 v[128:131], v[124:127], v[172:175], v[128:131]
	v_mfma_f32_16x16x32_bf16 v[148:151], v[48:51], v[144:147], 0
	v_mfma_f32_16x16x32_bf16 v[148:151], v[52:55], v[172:175], v[148:151]
	v_mfma_f32_16x16x32_bf16 v[108:111], v[64:67], v[190:193], 0
	v_mfma_f32_16x16x32_bf16 v[108:111], v[100:103], v[196:199], v[108:111]
	v_mfma_f32_16x16x32_bf16 v[116:119], v[40:43], v[190:193], 0
	v_mfma_f32_16x16x32_bf16 v[116:119], v[44:47], v[196:199], v[116:119]
	v_mfma_f32_16x16x32_bf16 v[104:107], v[120:123], v[190:193], 0
	v_mfma_f32_16x16x32_bf16 v[104:107], v[124:127], v[196:199], v[104:107]
	v_mfma_f32_16x16x32_bf16 v[112:115], v[48:51], v[190:193], 0
	v_mfma_f32_16x16x32_bf16 v[112:115], v[52:55], v[196:199], v[112:115]
	v_mfma_f32_16x16x32_bf16 v[88:91], v[64:67], v[200:203], 0
	v_mfma_f32_16x16x32_bf16 v[88:91], v[100:103], v[204:207], v[88:91]
	v_mfma_f32_16x16x32_bf16 v[96:99], v[40:43], v[200:203], 0
	v_mfma_f32_16x16x32_bf16 v[96:99], v[44:47], v[204:207], v[96:99]
	v_mfma_f32_16x16x32_bf16 v[84:87], v[120:123], v[200:203], 0
	v_mfma_f32_16x16x32_bf16 v[84:87], v[124:127], v[204:207], v[84:87]
	v_mfma_f32_16x16x32_bf16 v[92:95], v[48:51], v[200:203], 0
	v_mfma_f32_16x16x32_bf16 v[92:95], v[52:55], v[204:207], v[92:95]
	v_mfma_f32_16x16x32_bf16 v[136:139], v[120:123], v[136:139], 0
	v_mfma_f32_16x16x32_bf16 v[136:139], v[124:127], v[140:143], v[136:139]
	s_barrier
	s_add_i32 s87, s96, s56
	s_mov_b32 m0, s87
	ds_read_b128 v[140:143], v195 offset:16384
	ds_read_b128 v[144:147], v195 offset:17408
	ds_read_b128 v[156:159], v195 offset:18432
	ds_read_b128 v[172:175], v195 offset:19456
	ds_read_b128 v[190:193], v195 offset:20480
	ds_read_b128 v[196:199], v195 offset:21504
	ds_read_b128 v[200:203], v195 offset:22528
	ds_read_b128 v[204:207], v195 offset:23552
	global_load_lds_dwordx4 v178, s[92:93]
	s_add_i32 m0, s87, 0x2000
	s_add_u32 vcc_lo, s92, 0x80000
	s_addc_u32 vcc_hi, s93, 0
	s_add_i32 s67, s67, s56
	global_load_lds_dwordx4 v182, s[92:93]
	v_lshl_add_u64 v[208:209], vcc, 0, v[178:179]
	s_mov_b32 m0, s67
	s_nop 0
	global_load_lds_dwordx4 v[208:209], off
	v_lshl_add_u64 v[208:209], vcc, 0, v[182:183]
	s_add_i32 m0, s67, 0x2000
	s_nop 0
	global_load_lds_dwordx4 v[208:209], off
	s_mov_b32 m0, s57
	s_nop 0
	global_load_lds_dwordx4 v176, s[94:95]
	s_mov_b32 m0, s61
	s_nop 0
	global_load_lds_dwordx4 v180, s[94:95]
	s_waitcnt vmcnt(8)
	s_waitcnt lgkmcnt(0)
	s_barrier
	s_waitcnt lgkmcnt(0)
	v_mfma_f32_16x16x32_bf16 v[80:83], v[40:43], v[140:143], 0
	v_mfma_f32_16x16x32_bf16 v[80:83], v[44:47], v[144:147], v[80:83]
	v_mfma_f32_16x16x32_bf16 v[36:39], v[64:67], v[156:159], 0
	v_mfma_f32_16x16x32_bf16 v[36:39], v[100:103], v[172:175], v[36:39]
	v_mfma_f32_16x16x32_bf16 v[76:79], v[48:51], v[140:143], 0
	v_mfma_f32_16x16x32_bf16 v[76:79], v[52:55], v[144:147], v[76:79]
	v_mfma_f32_16x16x32_bf16 v[32:35], v[120:123], v[156:159], 0
	v_mfma_f32_16x16x32_bf16 v[32:35], v[124:127], v[172:175], v[32:35]
	v_mfma_f32_16x16x32_bf16 v[60:63], v[40:43], v[156:159], 0
	v_mfma_f32_16x16x32_bf16 v[60:63], v[44:47], v[172:175], v[60:63]
	v_mfma_f32_16x16x32_bf16 v[20:23], v[64:67], v[190:193], 0
	v_mfma_f32_16x16x32_bf16 v[20:23], v[100:103], v[196:199], v[20:23]
	v_mfma_f32_16x16x32_bf16 v[56:59], v[48:51], v[156:159], 0
	v_mfma_f32_16x16x32_bf16 v[56:59], v[52:55], v[172:175], v[56:59]
	v_mfma_f32_16x16x32_bf16 v[16:19], v[120:123], v[190:193], 0
	v_mfma_f32_16x16x32_bf16 v[16:19], v[124:127], v[196:199], v[16:19]
	v_mfma_f32_16x16x32_bf16 v[28:31], v[40:43], v[190:193], 0
	v_mfma_f32_16x16x32_bf16 v[28:31], v[44:47], v[196:199], v[28:31]
	v_mfma_f32_16x16x32_bf16 v[4:7], v[64:67], v[200:203], 0
	v_mfma_f32_16x16x32_bf16 v[4:7], v[100:103], v[204:207], v[4:7]
	v_mfma_f32_16x16x32_bf16 v[24:27], v[48:51], v[190:193], 0
	v_mfma_f32_16x16x32_bf16 v[24:27], v[52:55], v[196:199], v[24:27]
	v_mfma_f32_16x16x32_bf16 v[0:3], v[120:123], v[200:203], 0
	v_mfma_f32_16x16x32_bf16 v[0:3], v[124:127], v[204:207], v[0:3]
	v_mfma_f32_16x16x32_bf16 v[12:15], v[40:43], v[200:203], 0
	v_mfma_f32_16x16x32_bf16 v[12:15], v[44:47], v[204:207], v[12:15]
	v_mfma_f32_16x16x32_bf16 v[40:43], v[64:67], v[140:143], 0
	v_mfma_f32_16x16x32_bf16 v[40:43], v[100:103], v[144:147], v[40:43]
	v_mfma_f32_16x16x32_bf16 v[8:11], v[48:51], v[200:203], 0
	v_mfma_f32_16x16x32_bf16 v[8:11], v[52:55], v[204:207], v[8:11]
	v_mfma_f32_16x16x32_bf16 v[44:47], v[120:123], v[140:143], 0
	v_mfma_f32_16x16x32_bf16 v[44:47], v[124:127], v[144:147], v[44:47]
	s_barrier
	s_add_i32 s67, 0, 0x18000
	s_add_i32 s87, 0, 0x1c000
	v_add_u32_e32 v68, s67, v194
	v_add_u32_e32 v72, s87, v194
	ds_read_b128 v[48:51], v68
	ds_read_b128 v[52:55], v68 offset:1024
	ds_read_b128 v[64:67], v68 offset:2048
	ds_read_b128 v[68:71], v68 offset:3072
	ds_read_b128 v[100:103], v72
	ds_read_b128 v[120:123], v72 offset:1024
	ds_read_b128 v[124:127], v72 offset:2048
	ds_read_b128 v[140:143], v72 offset:3072
	s_add_u32 s94, s94, 0x80000
	s_addc_u32 s95, s95, 0
	s_mov_b32 m0, s68
	ds_read_b128 v[72:75], v195 offset:32768
	ds_read_b128 v[144:147], v195 offset:33792
	ds_read_b128 v[172:175], v195 offset:34816
	ds_read_b128 v[190:193], v195 offset:35840
	ds_read_b128 v[196:199], v195 offset:36864
	ds_read_b128 v[200:203], v195 offset:37888
	ds_read_b128 v[204:207], v195 offset:38912
	ds_read_b128 v[208:211], v195 offset:39936
	global_load_lds_dwordx4 v176, s[94:95]
	s_mov_b32 m0, s69
	s_nop 0
	global_load_lds_dwordx4 v180, s[94:95]
	s_waitcnt vmcnt(8)
	s_waitcnt lgkmcnt(0)
	s_barrier
	s_waitcnt lgkmcnt(0)
	v_mfma_f32_16x16x32_bf16 v[156:159], v[48:51], v[72:75], v[168:171]
	v_mfma_f32_16x16x32_bf16 v[168:171], v[52:55], v[144:147], v[156:159]
	v_mfma_f32_16x16x32_bf16 v[156:159], v[64:67], v[72:75], v[164:167]
	v_mfma_f32_16x16x32_bf16 v[164:167], v[68:71], v[144:147], v[156:159]
	v_mfma_f32_16x16x32_bf16 v[152:155], v[48:51], v[172:175], v[152:155]
	v_mfma_f32_16x16x32_bf16 v[152:155], v[52:55], v[190:193], v[152:155]
	v_mfma_f32_16x16x32_bf16 v[148:151], v[64:67], v[172:175], v[148:151]
	v_mfma_f32_16x16x32_bf16 v[148:151], v[68:71], v[190:193], v[148:151]
	v_mfma_f32_16x16x32_bf16 v[116:119], v[48:51], v[196:199], v[116:119]
	v_mfma_f32_16x16x32_bf16 v[116:119], v[52:55], v[200:203], v[116:119]
	v_mfma_f32_16x16x32_bf16 v[112:115], v[64:67], v[196:199], v[112:115]
	v_mfma_f32_16x16x32_bf16 v[112:115], v[68:71], v[200:203], v[112:115]
	v_mfma_f32_16x16x32_bf16 v[96:99], v[48:51], v[204:207], v[96:99]
	v_mfma_f32_16x16x32_bf16 v[96:99], v[52:55], v[208:211], v[96:99]
	v_mfma_f32_16x16x32_bf16 v[92:95], v[64:67], v[204:207], v[92:95]
	v_mfma_f32_16x16x32_bf16 v[92:95], v[68:71], v[208:211], v[92:95]
	v_mfma_f32_16x16x32_bf16 v[156:159], v[100:103], v[72:75], v[160:163]
	v_mfma_f32_16x16x32_bf16 v[160:163], v[120:123], v[144:147], v[156:159]
	v_mfma_f32_16x16x32_bf16 v[72:75], v[124:127], v[72:75], v[136:139]
	v_mfma_f32_16x16x32_bf16 v[156:159], v[140:143], v[144:147], v[72:75]
	v_mfma_f32_16x16x32_bf16 v[72:75], v[100:103], v[172:175], v[132:135]
	v_mfma_f32_16x16x32_bf16 v[132:135], v[120:123], v[190:193], v[72:75]
	v_mfma_f32_16x16x32_bf16 v[72:75], v[124:127], v[172:175], v[128:131]
	v_mfma_f32_16x16x32_bf16 v[128:131], v[140:143], v[190:193], v[72:75]
	v_mfma_f32_16x16x32_bf16 v[72:75], v[100:103], v[196:199], v[108:111]
	v_mfma_f32_16x16x32_bf16 v[108:111], v[120:123], v[200:203], v[72:75]
	v_mfma_f32_16x16x32_bf16 v[72:75], v[124:127], v[196:199], v[104:107]
	v_mfma_f32_16x16x32_bf16 v[104:107], v[140:143], v[200:203], v[72:75]
	v_mfma_f32_16x16x32_bf16 v[72:75], v[100:103], v[204:207], v[88:91]
	v_mfma_f32_16x16x32_bf16 v[88:91], v[120:123], v[208:211], v[72:75]
	v_mfma_f32_16x16x32_bf16 v[72:75], v[124:127], v[204:207], v[84:87]
	v_mfma_f32_16x16x32_bf16 v[84:87], v[140:143], v[208:211], v[72:75]
	s_barrier
	s_add_i32 s67, s67, s56
	s_nop 3
	s_add_u32 s98, s92, 0x80
	s_addc_u32 s99, s93, 0
	s_mov_b32 m0, s67
	ds_read_b128 v[136:139], v195 offset:49152
	ds_read_b128 v[144:147], v195 offset:50176
	ds_read_b128 v[172:175], v195 offset:51200
	ds_read_b128 v[190:193], v195 offset:52224
	ds_read_b128 v[196:199], v195 offset:53248
	ds_read_b128 v[200:203], v195 offset:54272
	ds_read_b128 v[204:207], v195 offset:55296
	ds_read_b128 v[208:211], v195 offset:56320
	global_load_lds_dwordx4 v178, s[98:99]
	s_add_i32 m0, s67, 0x2000
	s_add_u32 s92, s92, 0x80080
	s_addc_u32 s93, s93, 0
	s_add_i32 s67, s87, s56
	global_load_lds_dwordx4 v182, s[98:99]
	s_mov_b32 m0, s67
	s_nop 0
	global_load_lds_dwordx4 v178, s[92:93]
	s_add_i32 m0, s67, 0x2000
	s_nop 0
	global_load_lds_dwordx4 v182, s[92:93]
	s_add_u32 s98, s94, 0xfff80080
	s_addc_u32 s99, s95, -1
	s_mov_b32 m0, s2
	s_nop 0
	global_load_lds_dwordx4 v176, s[98:99]
	s_mov_b32 m0, s28
	s_nop 0
	global_load_lds_dwordx4 v180, s[98:99]
	s_waitcnt vmcnt(8)
	s_waitcnt lgkmcnt(0)
	s_barrier
	s_waitcnt lgkmcnt(0)
	v_mfma_f32_16x16x32_bf16 v[72:75], v[48:51], v[136:139], v[80:83]
	v_mfma_f32_16x16x32_bf16 v[80:83], v[52:55], v[144:147], v[72:75]
	v_mfma_f32_16x16x32_bf16 v[72:75], v[64:67], v[136:139], v[76:79]
	v_mfma_f32_16x16x32_bf16 v[76:79], v[68:71], v[144:147], v[72:75]
	v_mfma_f32_16x16x32_bf16 v[60:63], v[48:51], v[172:175], v[60:63]
	v_mfma_f32_16x16x32_bf16 v[60:63], v[52:55], v[190:193], v[60:63]
	v_mfma_f32_16x16x32_bf16 v[56:59], v[64:67], v[172:175], v[56:59]
	v_mfma_f32_16x16x32_bf16 v[56:59], v[68:71], v[190:193], v[56:59]
	v_mfma_f32_16x16x32_bf16 v[28:31], v[48:51], v[196:199], v[28:31]
	v_mfma_f32_16x16x32_bf16 v[28:31], v[52:55], v[200:203], v[28:31]
	v_mfma_f32_16x16x32_bf16 v[24:27], v[64:67], v[196:199], v[24:27]
	v_mfma_f32_16x16x32_bf16 v[24:27], v[68:71], v[200:203], v[24:27]
	v_mfma_f32_16x16x32_bf16 v[12:15], v[48:51], v[204:207], v[12:15]
	v_mfma_f32_16x16x32_bf16 v[12:15], v[52:55], v[208:211], v[12:15]
	v_mfma_f32_16x16x32_bf16 v[8:11], v[64:67], v[204:207], v[8:11]
	v_mfma_f32_16x16x32_bf16 v[8:11], v[68:71], v[208:211], v[8:11]
	v_mfma_f32_16x16x32_bf16 v[40:43], v[100:103], v[136:139], v[40:43]
	v_mfma_f32_16x16x32_bf16 v[72:75], v[120:123], v[144:147], v[40:43]
	v_mfma_f32_16x16x32_bf16 v[40:43], v[124:127], v[136:139], v[44:47]
	v_mfma_f32_16x16x32_bf16 v[68:71], v[140:143], v[144:147], v[40:43]
	v_mfma_f32_16x16x32_bf16 v[36:39], v[100:103], v[172:175], v[36:39]
	v_mfma_f32_16x16x32_bf16 v[36:39], v[120:123], v[190:193], v[36:39]
	v_mfma_f32_16x16x32_bf16 v[32:35], v[124:127], v[172:175], v[32:35]
	v_mfma_f32_16x16x32_bf16 v[32:35], v[140:143], v[190:193], v[32:35]
	v_mfma_f32_16x16x32_bf16 v[20:23], v[100:103], v[196:199], v[20:23]
	v_mfma_f32_16x16x32_bf16 v[20:23], v[120:123], v[200:203], v[20:23]
	v_mfma_f32_16x16x32_bf16 v[16:19], v[124:127], v[196:199], v[16:19]
	v_mfma_f32_16x16x32_bf16 v[16:19], v[140:143], v[200:203], v[16:19]
	v_mfma_f32_16x16x32_bf16 v[4:7], v[100:103], v[204:207], v[4:7]
	v_mfma_f32_16x16x32_bf16 v[4:7], v[120:123], v[208:211], v[4:7]
	v_mfma_f32_16x16x32_bf16 v[0:3], v[124:127], v[204:207], v[0:3]
	v_mfma_f32_16x16x32_bf16 v[0:3], v[140:143], v[208:211], v[0:3]
	s_barrier
	s_add_i32 s85, s85, 2
	s_add_u32 s10, s10, 0x100
	s_addc_u32 s11, s11, 0
	s_add_u32 s54, s54, 0x100
	s_addc_u32 s55, s55, 0
.LBB0_639:
	s_add_u32 s67, s10, 0xfff80080
	s_addc_u32 s87, s11, -1
	s_add_i32 s96, 0, 0x10000
	s_cmp_eq_u32 s85, 28
	s_cselect_b32 s95, s7, s87
	s_cselect_b32 s94, s9, s67
	s_cselect_b32 s93, s40, s55
	s_cselect_b32 s92, s41, s54
	s_add_i32 s67, 0, 0x14000
	v_add_u32_e32 v52, s96, v194
	v_add_u32_e32 v124, s67, v194
	ds_read_b128 v[40:43], v52
	ds_read_b128 v[44:47], v52 offset:1024
	ds_read_b128 v[48:51], v52 offset:2048
	ds_read_b128 v[52:55], v52 offset:3072
	ds_read_b128 v[64:67], v124
	ds_read_b128 v[100:103], v124 offset:1024
	ds_read_b128 v[120:123], v124 offset:2048
	ds_read_b128 v[124:127], v124 offset:3072
	s_add_i32 m0, s57, 0xc000
	ds_read_b128 v[136:139], v195
	ds_read_b128 v[140:143], v195 offset:1024
	ds_read_b128 v[144:147], v195 offset:2048
	ds_read_b128 v[172:175], v195 offset:3072
	ds_read_b128 v[190:193], v195 offset:4096
	ds_read_b128 v[196:199], v195 offset:5120
	ds_read_b128 v[200:203], v195 offset:6144
	ds_read_b128 v[204:207], v195 offset:7168
	global_load_lds_dwordx4 v186, s[10:11]
	s_add_i32 m0, s57, 0xe000
	s_nop 0
	global_load_lds_dwordx4 v188, s[10:11]
	s_waitcnt vmcnt(8)
	s_waitcnt lgkmcnt(0)
	s_barrier
	s_waitcnt lgkmcnt(0)
	v_mfma_f32_16x16x32_bf16 v[168:171], v[40:43], v[136:139], v[168:171]
	v_mfma_f32_16x16x32_bf16 v[168:171], v[44:47], v[140:143], v[168:171]
	v_mfma_f32_16x16x32_bf16 v[160:163], v[64:67], v[136:139], v[160:163]
	v_mfma_f32_16x16x32_bf16 v[160:163], v[100:103], v[140:143], v[160:163]
	v_mfma_f32_16x16x32_bf16 v[164:167], v[48:51], v[136:139], v[164:167]
	v_mfma_f32_16x16x32_bf16 v[164:167], v[52:55], v[140:143], v[164:167]
	v_mfma_f32_16x16x32_bf16 v[132:135], v[64:67], v[144:147], v[132:135]
	v_mfma_f32_16x16x32_bf16 v[132:135], v[100:103], v[172:175], v[132:135]
	v_mfma_f32_16x16x32_bf16 v[152:155], v[40:43], v[144:147], v[152:155]
	v_mfma_f32_16x16x32_bf16 v[152:155], v[44:47], v[172:175], v[152:155]
	v_mfma_f32_16x16x32_bf16 v[128:131], v[120:123], v[144:147], v[128:131]
	v_mfma_f32_16x16x32_bf16 v[128:131], v[124:127], v[172:175], v[128:131]
	v_mfma_f32_16x16x32_bf16 v[148:151], v[48:51], v[144:147], v[148:151]
	v_mfma_f32_16x16x32_bf16 v[148:151], v[52:55], v[172:175], v[148:151]
	v_mfma_f32_16x16x32_bf16 v[108:111], v[64:67], v[190:193], v[108:111]
	v_mfma_f32_16x16x32_bf16 v[108:111], v[100:103], v[196:199], v[108:111]
	v_mfma_f32_16x16x32_bf16 v[116:119], v[40:43], v[190:193], v[116:119]
	v_mfma_f32_16x16x32_bf16 v[116:119], v[44:47], v[196:199], v[116:119]
	v_mfma_f32_16x16x32_bf16 v[104:107], v[120:123], v[190:193], v[104:107]
	v_mfma_f32_16x16x32_bf16 v[104:107], v[124:127], v[196:199], v[104:107]
	v_mfma_f32_16x16x32_bf16 v[112:115], v[48:51], v[190:193], v[112:115]
	v_mfma_f32_16x16x32_bf16 v[112:115], v[52:55], v[196:199], v[112:115]
	v_mfma_f32_16x16x32_bf16 v[88:91], v[64:67], v[200:203], v[88:91]
	v_mfma_f32_16x16x32_bf16 v[88:91], v[100:103], v[204:207], v[88:91]
	v_mfma_f32_16x16x32_bf16 v[96:99], v[40:43], v[200:203], v[96:99]
	v_mfma_f32_16x16x32_bf16 v[96:99], v[44:47], v[204:207], v[96:99]
	v_mfma_f32_16x16x32_bf16 v[84:87], v[120:123], v[200:203], v[84:87]
	v_mfma_f32_16x16x32_bf16 v[84:87], v[124:127], v[204:207], v[84:87]
	v_mfma_f32_16x16x32_bf16 v[92:95], v[48:51], v[200:203], v[92:95]
	v_mfma_f32_16x16x32_bf16 v[92:95], v[52:55], v[204:207], v[92:95]
	v_mfma_f32_16x16x32_bf16 v[136:139], v[120:123], v[136:139], v[156:159]
	v_mfma_f32_16x16x32_bf16 v[136:139], v[124:127], v[140:143], v[136:139]
	s_barrier
	s_add_i32 s87, s96, s56
	s_mov_b32 m0, s87
	ds_read_b128 v[140:143], v195 offset:16384
	ds_read_b128 v[144:147], v195 offset:17408
	ds_read_b128 v[156:159], v195 offset:18432
	ds_read_b128 v[172:175], v195 offset:19456
	ds_read_b128 v[190:193], v195 offset:20480
	ds_read_b128 v[196:199], v195 offset:21504
	ds_read_b128 v[200:203], v195 offset:22528
	ds_read_b128 v[204:207], v195 offset:23552
	global_load_lds_dwordx4 v178, s[92:93]
	s_add_i32 m0, s87, 0x2000
	s_add_u32 vcc_lo, s92, 0x80000
	s_addc_u32 vcc_hi, s93, 0
	s_add_i32 s67, s67, s56
	global_load_lds_dwordx4 v182, s[92:93]
	v_lshl_add_u64 v[208:209], vcc, 0, v[178:179]
	s_mov_b32 m0, s67
	s_nop 0
	global_load_lds_dwordx4 v[208:209], off
	v_lshl_add_u64 v[208:209], vcc, 0, v[182:183]
	s_add_i32 m0, s67, 0x2000
	s_nop 0
	global_load_lds_dwordx4 v[208:209], off
	s_mov_b32 m0, s57
	s_nop 0
	global_load_lds_dwordx4 v176, s[94:95]
	s_mov_b32 m0, s61
	s_nop 0
	global_load_lds_dwordx4 v180, s[94:95]
	s_waitcnt vmcnt(8)
	s_waitcnt lgkmcnt(0)
	s_barrier
	s_waitcnt lgkmcnt(0)
	v_mfma_f32_16x16x32_bf16 v[80:83], v[40:43], v[140:143], v[80:83]
	v_mfma_f32_16x16x32_bf16 v[80:83], v[44:47], v[144:147], v[80:83]
	v_mfma_f32_16x16x32_bf16 v[36:39], v[64:67], v[156:159], v[36:39]
	v_mfma_f32_16x16x32_bf16 v[36:39], v[100:103], v[172:175], v[36:39]
	v_mfma_f32_16x16x32_bf16 v[76:79], v[48:51], v[140:143], v[76:79]
	v_mfma_f32_16x16x32_bf16 v[76:79], v[52:55], v[144:147], v[76:79]
	v_mfma_f32_16x16x32_bf16 v[32:35], v[120:123], v[156:159], v[32:35]
	v_mfma_f32_16x16x32_bf16 v[32:35], v[124:127], v[172:175], v[32:35]
	v_mfma_f32_16x16x32_bf16 v[60:63], v[40:43], v[156:159], v[60:63]
	v_mfma_f32_16x16x32_bf16 v[60:63], v[44:47], v[172:175], v[60:63]
	v_mfma_f32_16x16x32_bf16 v[20:23], v[64:67], v[190:193], v[20:23]
	v_mfma_f32_16x16x32_bf16 v[20:23], v[100:103], v[196:199], v[20:23]
	v_mfma_f32_16x16x32_bf16 v[56:59], v[48:51], v[156:159], v[56:59]
	v_mfma_f32_16x16x32_bf16 v[56:59], v[52:55], v[172:175], v[56:59]
	v_mfma_f32_16x16x32_bf16 v[16:19], v[120:123], v[190:193], v[16:19]
	v_mfma_f32_16x16x32_bf16 v[16:19], v[124:127], v[196:199], v[16:19]
	v_mfma_f32_16x16x32_bf16 v[28:31], v[40:43], v[190:193], v[28:31]
	v_mfma_f32_16x16x32_bf16 v[28:31], v[44:47], v[196:199], v[28:31]
	v_mfma_f32_16x16x32_bf16 v[4:7], v[64:67], v[200:203], v[4:7]
	v_mfma_f32_16x16x32_bf16 v[4:7], v[100:103], v[204:207], v[4:7]
	v_mfma_f32_16x16x32_bf16 v[24:27], v[48:51], v[190:193], v[24:27]
	v_mfma_f32_16x16x32_bf16 v[24:27], v[52:55], v[196:199], v[24:27]
	v_mfma_f32_16x16x32_bf16 v[0:3], v[120:123], v[200:203], v[0:3]
	v_mfma_f32_16x16x32_bf16 v[0:3], v[124:127], v[204:207], v[0:3]
	v_mfma_f32_16x16x32_bf16 v[12:15], v[40:43], v[200:203], v[12:15]
	v_mfma_f32_16x16x32_bf16 v[12:15], v[44:47], v[204:207], v[12:15]
	v_mfma_f32_16x16x32_bf16 v[40:43], v[64:67], v[140:143], v[72:75]
	v_mfma_f32_16x16x32_bf16 v[40:43], v[100:103], v[144:147], v[40:43]
	v_mfma_f32_16x16x32_bf16 v[8:11], v[48:51], v[200:203], v[8:11]
	v_mfma_f32_16x16x32_bf16 v[8:11], v[52:55], v[204:207], v[8:11]
	v_mfma_f32_16x16x32_bf16 v[44:47], v[120:123], v[140:143], v[68:71]
	v_mfma_f32_16x16x32_bf16 v[44:47], v[124:127], v[144:147], v[44:47]
	s_barrier
	s_add_i32 s67, 0, 0x18000
	s_add_i32 s87, 0, 0x1c000
	v_add_u32_e32 v68, s67, v194
	v_add_u32_e32 v72, s87, v194
	ds_read_b128 v[48:51], v68
	ds_read_b128 v[52:55], v68 offset:1024
	ds_read_b128 v[64:67], v68 offset:2048
	ds_read_b128 v[68:71], v68 offset:3072
	ds_read_b128 v[100:103], v72
	ds_read_b128 v[120:123], v72 offset:1024
	ds_read_b128 v[124:127], v72 offset:2048
	ds_read_b128 v[140:143], v72 offset:3072
	s_add_u32 s94, s94, 0x80000
	s_addc_u32 s95, s95, 0
	s_mov_b32 m0, s68
	ds_read_b128 v[72:75], v195 offset:32768
	ds_read_b128 v[144:147], v195 offset:33792
	ds_read_b128 v[172:175], v195 offset:34816
	ds_read_b128 v[190:193], v195 offset:35840
	ds_read_b128 v[196:199], v195 offset:36864
	ds_read_b128 v[200:203], v195 offset:37888
	ds_read_b128 v[204:207], v195 offset:38912
	ds_read_b128 v[208:211], v195 offset:39936
	global_load_lds_dwordx4 v176, s[94:95]
	s_mov_b32 m0, s69
	s_nop 0
	global_load_lds_dwordx4 v180, s[94:95]
	s_waitcnt vmcnt(8)
	s_waitcnt lgkmcnt(0)
	s_barrier
	s_waitcnt lgkmcnt(0)
	v_mfma_f32_16x16x32_bf16 v[156:159], v[48:51], v[72:75], v[168:171]
	v_mfma_f32_16x16x32_bf16 v[168:171], v[52:55], v[144:147], v[156:159]
	v_mfma_f32_16x16x32_bf16 v[156:159], v[64:67], v[72:75], v[164:167]
	v_mfma_f32_16x16x32_bf16 v[164:167], v[68:71], v[144:147], v[156:159]
	v_mfma_f32_16x16x32_bf16 v[152:155], v[48:51], v[172:175], v[152:155]
	v_mfma_f32_16x16x32_bf16 v[152:155], v[52:55], v[190:193], v[152:155]
	v_mfma_f32_16x16x32_bf16 v[148:151], v[64:67], v[172:175], v[148:151]
	v_mfma_f32_16x16x32_bf16 v[148:151], v[68:71], v[190:193], v[148:151]
	v_mfma_f32_16x16x32_bf16 v[116:119], v[48:51], v[196:199], v[116:119]
	v_mfma_f32_16x16x32_bf16 v[116:119], v[52:55], v[200:203], v[116:119]
	v_mfma_f32_16x16x32_bf16 v[112:115], v[64:67], v[196:199], v[112:115]
	v_mfma_f32_16x16x32_bf16 v[112:115], v[68:71], v[200:203], v[112:115]
	v_mfma_f32_16x16x32_bf16 v[96:99], v[48:51], v[204:207], v[96:99]
	v_mfma_f32_16x16x32_bf16 v[96:99], v[52:55], v[208:211], v[96:99]
	v_mfma_f32_16x16x32_bf16 v[92:95], v[64:67], v[204:207], v[92:95]
	v_mfma_f32_16x16x32_bf16 v[92:95], v[68:71], v[208:211], v[92:95]
	v_mfma_f32_16x16x32_bf16 v[156:159], v[100:103], v[72:75], v[160:163]
	v_mfma_f32_16x16x32_bf16 v[160:163], v[120:123], v[144:147], v[156:159]
	v_mfma_f32_16x16x32_bf16 v[72:75], v[124:127], v[72:75], v[136:139]
	v_mfma_f32_16x16x32_bf16 v[156:159], v[140:143], v[144:147], v[72:75]
	v_mfma_f32_16x16x32_bf16 v[72:75], v[100:103], v[172:175], v[132:135]
	v_mfma_f32_16x16x32_bf16 v[132:135], v[120:123], v[190:193], v[72:75]
	v_mfma_f32_16x16x32_bf16 v[72:75], v[124:127], v[172:175], v[128:131]
	v_mfma_f32_16x16x32_bf16 v[128:131], v[140:143], v[190:193], v[72:75]
	v_mfma_f32_16x16x32_bf16 v[72:75], v[100:103], v[196:199], v[108:111]
	v_mfma_f32_16x16x32_bf16 v[108:111], v[120:123], v[200:203], v[72:75]
	v_mfma_f32_16x16x32_bf16 v[72:75], v[124:127], v[196:199], v[104:107]
	v_mfma_f32_16x16x32_bf16 v[104:107], v[140:143], v[200:203], v[72:75]
	v_mfma_f32_16x16x32_bf16 v[72:75], v[100:103], v[204:207], v[88:91]
	v_mfma_f32_16x16x32_bf16 v[88:91], v[120:123], v[208:211], v[72:75]
	v_mfma_f32_16x16x32_bf16 v[72:75], v[124:127], v[204:207], v[84:87]
	v_mfma_f32_16x16x32_bf16 v[84:87], v[140:143], v[208:211], v[72:75]
	s_barrier
	s_add_i32 s67, s67, s56
	s_nop 3
	s_add_u32 s98, s92, 0x80
	s_addc_u32 s99, s93, 0
	s_mov_b32 m0, s67
	ds_read_b128 v[136:139], v195 offset:49152
	ds_read_b128 v[144:147], v195 offset:50176
	ds_read_b128 v[172:175], v195 offset:51200
	ds_read_b128 v[190:193], v195 offset:52224
	ds_read_b128 v[196:199], v195 offset:53248
	ds_read_b128 v[200:203], v195 offset:54272
	ds_read_b128 v[204:207], v195 offset:55296
	ds_read_b128 v[208:211], v195 offset:56320
	global_load_lds_dwordx4 v178, s[98:99]
	s_add_i32 m0, s67, 0x2000
	s_add_u32 s92, s92, 0x80080
	s_addc_u32 s93, s93, 0
	s_add_i32 s67, s87, s56
	global_load_lds_dwordx4 v182, s[98:99]
	s_mov_b32 m0, s67
	s_nop 0
	global_load_lds_dwordx4 v178, s[92:93]
	s_add_i32 m0, s67, 0x2000
	s_nop 0
	global_load_lds_dwordx4 v182, s[92:93]
	s_add_u32 s98, s94, 0xfff80080
	s_addc_u32 s99, s95, -1
	s_mov_b32 m0, s2
	s_nop 0
	global_load_lds_dwordx4 v176, s[98:99]
	s_mov_b32 m0, s28
	s_nop 0
	global_load_lds_dwordx4 v180, s[98:99]
	s_waitcnt vmcnt(8)
	s_waitcnt lgkmcnt(0)
	s_barrier
	s_waitcnt lgkmcnt(0)
	v_mfma_f32_16x16x32_bf16 v[72:75], v[48:51], v[136:139], v[80:83]
	v_mfma_f32_16x16x32_bf16 v[80:83], v[52:55], v[144:147], v[72:75]
	v_mfma_f32_16x16x32_bf16 v[72:75], v[64:67], v[136:139], v[76:79]
	v_mfma_f32_16x16x32_bf16 v[76:79], v[68:71], v[144:147], v[72:75]
	v_mfma_f32_16x16x32_bf16 v[60:63], v[48:51], v[172:175], v[60:63]
	v_mfma_f32_16x16x32_bf16 v[60:63], v[52:55], v[190:193], v[60:63]
	v_mfma_f32_16x16x32_bf16 v[56:59], v[64:67], v[172:175], v[56:59]
	v_mfma_f32_16x16x32_bf16 v[56:59], v[68:71], v[190:193], v[56:59]
	v_mfma_f32_16x16x32_bf16 v[28:31], v[48:51], v[196:199], v[28:31]
	v_mfma_f32_16x16x32_bf16 v[28:31], v[52:55], v[200:203], v[28:31]
	v_mfma_f32_16x16x32_bf16 v[24:27], v[64:67], v[196:199], v[24:27]
	v_mfma_f32_16x16x32_bf16 v[24:27], v[68:71], v[200:203], v[24:27]
	v_mfma_f32_16x16x32_bf16 v[12:15], v[48:51], v[204:207], v[12:15]
	v_mfma_f32_16x16x32_bf16 v[12:15], v[52:55], v[208:211], v[12:15]
	v_mfma_f32_16x16x32_bf16 v[8:11], v[64:67], v[204:207], v[8:11]
	v_mfma_f32_16x16x32_bf16 v[8:11], v[68:71], v[208:211], v[8:11]
	v_mfma_f32_16x16x32_bf16 v[40:43], v[100:103], v[136:139], v[40:43]
	v_mfma_f32_16x16x32_bf16 v[72:75], v[120:123], v[144:147], v[40:43]
	v_mfma_f32_16x16x32_bf16 v[40:43], v[124:127], v[136:139], v[44:47]
	v_mfma_f32_16x16x32_bf16 v[68:71], v[140:143], v[144:147], v[40:43]
	v_mfma_f32_16x16x32_bf16 v[36:39], v[100:103], v[172:175], v[36:39]
	v_mfma_f32_16x16x32_bf16 v[36:39], v[120:123], v[190:193], v[36:39]
	v_mfma_f32_16x16x32_bf16 v[32:35], v[124:127], v[172:175], v[32:35]
	v_mfma_f32_16x16x32_bf16 v[32:35], v[140:143], v[190:193], v[32:35]
	v_mfma_f32_16x16x32_bf16 v[20:23], v[100:103], v[196:199], v[20:23]
	v_mfma_f32_16x16x32_bf16 v[20:23], v[120:123], v[200:203], v[20:23]
	v_mfma_f32_16x16x32_bf16 v[16:19], v[124:127], v[196:199], v[16:19]
	v_mfma_f32_16x16x32_bf16 v[16:19], v[140:143], v[200:203], v[16:19]
	v_mfma_f32_16x16x32_bf16 v[4:7], v[100:103], v[204:207], v[4:7]
	v_mfma_f32_16x16x32_bf16 v[4:7], v[120:123], v[208:211], v[4:7]
	v_mfma_f32_16x16x32_bf16 v[0:3], v[124:127], v[204:207], v[0:3]
	v_mfma_f32_16x16x32_bf16 v[0:3], v[140:143], v[208:211], v[0:3]
	s_barrier
	s_add_i32 s85, s85, 2
	s_add_u32 s10, s10, 0x100
	s_addc_u32 s11, s11, 0
	s_add_u32 s54, s54, 0x100
	s_addc_u32 s55, s55, 0
	s_cmp_gt_u32 s85, 29
	s_cbranch_scc0 .LBB0_639
	s_and_b64 vcc, exec, s[80:81]
	s_cbranch_vccz .LBB0_642
	s_barrier

.LBB0_964:
	s_ashr_i32 s79, s78, 31
	s_lshl_b64 s[82:83], s[78:79], 20
	s_add_u32 s82, s14, s82
	s_addc_u32 s83, s15, s83
	s_and_b64 s[84:85], s[80:81], exec
	s_cselect_b32 s79, s83, s93
	s_cselect_b32 s96, s82, s92
	s_ashr_i32 s77, s76, 31
	s_lshl_b64 s[84:85], s[76:77], 20
	s_add_u32 s84, s24, s84
	s_addc_u32 s85, s26, s85
	s_and_b64 vcc, s[80:81], exec
	s_cselect_b32 s77, s85, s91
	s_cselect_b32 vcc_lo, s84, s90
	s_lshl_b32 s86, s86, 8
	s_ashr_i32 s87, s86, 31
	s_lshl_b64 s[74:75], s[86:87], 2
	s_add_u32 s74, s88, s74
	s_addc_u32 s75, s89, s75
	s_add_i32 m0, s71, s40
	s_add_u32 s88, s92, 0x80080
	global_load_lds_dwordx4 v239, s[74:75]
	s_addc_u32 s89, s93, 0
	s_add_u32 s87, s90, 0x100
	s_addc_u32 vcc_hi, s91, 0
	s_mov_b32 s71, -2
	s_waitcnt vmcnt(0)
	s_add_u32 s67, s88, 0xfff80080
	s_addc_u32 s74, s89, -1
	s_add_i32 s75, 0, 0x10000
	s_cmp_eq_u32 s71, 28
	s_cselect_b32 s93, s79, s74
	s_cselect_b32 s92, s96, s67
	s_cselect_b32 s91, s77, vcc_hi
	s_cselect_b32 s90, vcc_lo, s87
	s_add_i32 s67, 0, 0x14000
	v_add_u32_e32 v96, s75, v238
	v_add_u32_e32 v140, s67, v238
	ds_read_b128 v[64:67], v96
	ds_read_b128 v[72:75], v96 offset:1024
	ds_read_b128 v[88:91], v96 offset:2048
	ds_read_b128 v[96:99], v96 offset:3072
	ds_read_b128 v[108:111], v140
	ds_read_b128 v[116:119], v140 offset:1024
	ds_read_b128 v[128:131], v140 offset:2048
	ds_read_b128 v[140:143], v140 offset:3072
	s_add_i32 m0, s28, 0xc000
	ds_read_b128 v[152:155], v240
	ds_read_b128 v[156:159], v240 offset:1024
	ds_read_b128 v[160:163], v240 offset:2048
	ds_read_b128 v[164:167], v240 offset:3072
	ds_read_b128 v[168:171], v240 offset:4096
	ds_read_b128 v[180:183], v240 offset:5120
	ds_read_b128 v[184:187], v240 offset:6144
	ds_read_b128 v[188:191], v240 offset:7168
	global_load_lds_dwordx4 v230, s[88:89]
	s_add_i32 m0, s28, 0xe000
	s_nop 0
	global_load_lds_dwordx4 v232, s[88:89]
	s_waitcnt vmcnt(8)
	s_waitcnt lgkmcnt(0)
	s_barrier
	s_waitcnt lgkmcnt(0)
	v_mfma_f32_16x16x32_bf16 v[176:179], v[64:67], v[152:155], 0
	v_mfma_f32_16x16x32_bf16 v[176:179], v[72:75], v[156:159], v[176:179]
	v_mfma_f32_16x16x32_bf16 v[148:151], v[108:111], v[152:155], 0
	v_mfma_f32_16x16x32_bf16 v[148:151], v[116:119], v[156:159], v[148:151]
	v_mfma_f32_16x16x32_bf16 v[172:175], v[88:91], v[152:155], 0
	v_mfma_f32_16x16x32_bf16 v[172:175], v[96:99], v[156:159], v[172:175]
	v_mfma_f32_16x16x32_bf16 v[144:147], v[128:131], v[152:155], 0
	v_mfma_f32_16x16x32_bf16 v[144:147], v[140:143], v[156:159], v[144:147]
	v_mfma_f32_16x16x32_bf16 v[136:139], v[64:67], v[160:163], 0
	v_mfma_f32_16x16x32_bf16 v[136:139], v[72:75], v[164:167], v[136:139]
	v_mfma_f32_16x16x32_bf16 v[124:127], v[108:111], v[160:163], 0
	v_mfma_f32_16x16x32_bf16 v[124:127], v[116:119], v[164:167], v[124:127]
	v_mfma_f32_16x16x32_bf16 v[132:135], v[88:91], v[160:163], 0
	v_mfma_f32_16x16x32_bf16 v[132:135], v[96:99], v[164:167], v[132:135]
	v_mfma_f32_16x16x32_bf16 v[120:123], v[128:131], v[160:163], 0
	v_mfma_f32_16x16x32_bf16 v[120:123], v[140:143], v[164:167], v[120:123]
	v_mfma_f32_16x16x32_bf16 v[112:115], v[64:67], v[168:171], 0
	v_mfma_f32_16x16x32_bf16 v[112:115], v[72:75], v[180:183], v[112:115]
	v_mfma_f32_16x16x32_bf16 v[100:103], v[108:111], v[168:171], 0
	v_mfma_f32_16x16x32_bf16 v[100:103], v[116:119], v[180:183], v[100:103]
	v_mfma_f32_16x16x32_bf16 v[104:107], v[88:91], v[168:171], 0
	v_mfma_f32_16x16x32_bf16 v[104:107], v[96:99], v[180:183], v[104:107]
	v_mfma_f32_16x16x32_bf16 v[92:95], v[128:131], v[168:171], 0
	v_mfma_f32_16x16x32_bf16 v[92:95], v[140:143], v[180:183], v[92:95]
	v_mfma_f32_16x16x32_bf16 v[84:87], v[64:67], v[184:187], 0
	v_mfma_f32_16x16x32_bf16 v[84:87], v[72:75], v[188:191], v[84:87]
	v_mfma_f32_16x16x32_bf16 v[76:79], v[108:111], v[184:187], 0
	v_mfma_f32_16x16x32_bf16 v[76:79], v[116:119], v[188:191], v[76:79]
	v_mfma_f32_16x16x32_bf16 v[80:83], v[88:91], v[184:187], 0
	v_mfma_f32_16x16x32_bf16 v[80:83], v[96:99], v[188:191], v[80:83]
	v_mfma_f32_16x16x32_bf16 v[68:71], v[128:131], v[184:187], 0
	v_mfma_f32_16x16x32_bf16 v[68:71], v[140:143], v[188:191], v[68:71]
	s_barrier
	s_add_i32 s74, s75, s2
	s_mov_b32 m0, s74
	ds_read_b128 v[152:155], v240 offset:16384
	ds_read_b128 v[156:159], v240 offset:17408
	ds_read_b128 v[160:163], v240 offset:18432
	ds_read_b128 v[164:167], v240 offset:19456
	ds_read_b128 v[168:171], v240 offset:20480
	ds_read_b128 v[180:183], v240 offset:21504
	ds_read_b128 v[184:187], v240 offset:22528
	ds_read_b128 v[188:191], v240 offset:23552
	global_load_lds_dwordx4 v216, s[90:91]
	s_add_i32 m0, s74, 0x2000
	s_add_u32 s74, s90, 0x80000
	s_addc_u32 s75, s91, 0
	s_add_i32 s67, s67, s2
	global_load_lds_dwordx4 v228, s[90:91]
	s_mov_b32 m0, s67
	s_nop 0
	global_load_lds_dwordx4 v216, s[74:75]
	s_add_i32 m0, s67, 0x2000
	s_nop 0
	global_load_lds_dwordx4 v228, s[74:75]
	s_mov_b32 m0, s28
	s_nop 0
	global_load_lds_dwordx4 v224, s[92:93]
	s_mov_b32 m0, s29
	s_nop 0
	global_load_lds_dwordx4 v226, s[92:93]
	s_waitcnt vmcnt(8)
	s_waitcnt lgkmcnt(0)
	s_barrier
	s_waitcnt lgkmcnt(0)
	v_mfma_f32_16x16x32_bf16 v[60:63], v[64:67], v[152:155], 0
	v_mfma_f32_16x16x32_bf16 v[60:63], v[72:75], v[156:159], v[60:63]
	v_mfma_f32_16x16x32_bf16 v[52:55], v[108:111], v[152:155], 0
	v_mfma_f32_16x16x32_bf16 v[52:55], v[116:119], v[156:159], v[52:55]
	v_mfma_f32_16x16x32_bf16 v[56:59], v[88:91], v[152:155], 0
	v_mfma_f32_16x16x32_bf16 v[56:59], v[96:99], v[156:159], v[56:59]
	v_mfma_f32_16x16x32_bf16 v[48:51], v[128:131], v[152:155], 0
	v_mfma_f32_16x16x32_bf16 v[48:51], v[140:143], v[156:159], v[48:51]
	v_mfma_f32_16x16x32_bf16 v[44:47], v[64:67], v[160:163], 0
	v_mfma_f32_16x16x32_bf16 v[44:47], v[72:75], v[164:167], v[44:47]
	v_mfma_f32_16x16x32_bf16 v[36:39], v[108:111], v[160:163], 0
	v_mfma_f32_16x16x32_bf16 v[36:39], v[116:119], v[164:167], v[36:39]
	v_mfma_f32_16x16x32_bf16 v[40:43], v[88:91], v[160:163], 0
	v_mfma_f32_16x16x32_bf16 v[40:43], v[96:99], v[164:167], v[40:43]
	v_mfma_f32_16x16x32_bf16 v[32:35], v[128:131], v[160:163], 0
	v_mfma_f32_16x16x32_bf16 v[32:35], v[140:143], v[164:167], v[32:35]
	v_mfma_f32_16x16x32_bf16 v[28:31], v[64:67], v[168:171], 0
	v_mfma_f32_16x16x32_bf16 v[28:31], v[72:75], v[180:183], v[28:31]
	v_mfma_f32_16x16x32_bf16 v[20:23], v[108:111], v[168:171], 0
	v_mfma_f32_16x16x32_bf16 v[20:23], v[116:119], v[180:183], v[20:23]
	v_mfma_f32_16x16x32_bf16 v[24:27], v[88:91], v[168:171], 0
	v_mfma_f32_16x16x32_bf16 v[24:27], v[96:99], v[180:183], v[24:27]
	v_mfma_f32_16x16x32_bf16 v[16:19], v[128:131], v[168:171], 0
	v_mfma_f32_16x16x32_bf16 v[16:19], v[140:143], v[180:183], v[16:19]
	v_mfma_f32_16x16x32_bf16 v[12:15], v[64:67], v[184:187], 0
	v_mfma_f32_16x16x32_bf16 v[12:15], v[72:75], v[188:191], v[12:15]
	v_mfma_f32_16x16x32_bf16 v[4:7], v[108:111], v[184:187], 0
	v_mfma_f32_16x16x32_bf16 v[4:7], v[116:119], v[188:191], v[4:7]
	v_mfma_f32_16x16x32_bf16 v[8:11], v[88:91], v[184:187], 0
	v_mfma_f32_16x16x32_bf16 v[8:11], v[96:99], v[188:191], v[8:11]
	v_mfma_f32_16x16x32_bf16 v[0:3], v[128:131], v[184:187], 0
	v_mfma_f32_16x16x32_bf16 v[0:3], v[140:143], v[188:191], v[0:3]
	s_barrier
	s_add_i32 s67, 0, 0x18000
	s_add_i32 s3, 0, 0x1c000
	v_add_u32_e32 v96, s67, v238
	v_add_u32_e32 v140, s3, v238
	ds_read_b128 v[64:67], v96
	ds_read_b128 v[72:75], v96 offset:1024
	ds_read_b128 v[88:91], v96 offset:2048
	ds_read_b128 v[96:99], v96 offset:3072
	ds_read_b128 v[108:111], v140
	ds_read_b128 v[116:119], v140 offset:1024
	ds_read_b128 v[128:131], v140 offset:2048
	ds_read_b128 v[140:143], v140 offset:3072
	s_add_u32 s74, s92, 0x80000
	s_addc_u32 s75, s93, 0
	s_mov_b32 m0, s34
	ds_read_b128 v[152:155], v240 offset:32768
	ds_read_b128 v[156:159], v240 offset:33792
	ds_read_b128 v[160:163], v240 offset:34816
	ds_read_b128 v[164:167], v240 offset:35840
	ds_read_b128 v[168:171], v240 offset:36864
	ds_read_b128 v[180:183], v240 offset:37888
	ds_read_b128 v[184:187], v240 offset:38912
	ds_read_b128 v[188:191], v240 offset:39936
	global_load_lds_dwordx4 v224, s[74:75]
	s_mov_b32 m0, s35
	s_nop 0
	global_load_lds_dwordx4 v226, s[74:75]
	s_waitcnt vmcnt(8)
	s_waitcnt lgkmcnt(0)
	s_barrier
	s_waitcnt lgkmcnt(0)
	v_mfma_f32_16x16x32_bf16 v[176:179], v[64:67], v[152:155], v[176:179]
	v_mfma_f32_16x16x32_bf16 v[176:179], v[72:75], v[156:159], v[176:179]
	v_mfma_f32_16x16x32_bf16 v[148:151], v[108:111], v[152:155], v[148:151]
	v_mfma_f32_16x16x32_bf16 v[148:151], v[116:119], v[156:159], v[148:151]
	v_mfma_f32_16x16x32_bf16 v[172:175], v[88:91], v[152:155], v[172:175]
	v_mfma_f32_16x16x32_bf16 v[172:175], v[96:99], v[156:159], v[172:175]
	v_mfma_f32_16x16x32_bf16 v[144:147], v[128:131], v[152:155], v[144:147]
	v_mfma_f32_16x16x32_bf16 v[144:147], v[140:143], v[156:159], v[144:147]
	v_mfma_f32_16x16x32_bf16 v[136:139], v[64:67], v[160:163], v[136:139]
	v_mfma_f32_16x16x32_bf16 v[136:139], v[72:75], v[164:167], v[136:139]
	v_mfma_f32_16x16x32_bf16 v[124:127], v[108:111], v[160:163], v[124:127]
	v_mfma_f32_16x16x32_bf16 v[124:127], v[116:119], v[164:167], v[124:127]
	v_mfma_f32_16x16x32_bf16 v[132:135], v[88:91], v[160:163], v[132:135]
	v_mfma_f32_16x16x32_bf16 v[132:135], v[96:99], v[164:167], v[132:135]
	v_mfma_f32_16x16x32_bf16 v[120:123], v[128:131], v[160:163], v[120:123]
	v_mfma_f32_16x16x32_bf16 v[120:123], v[140:143], v[164:167], v[120:123]
	v_mfma_f32_16x16x32_bf16 v[112:115], v[64:67], v[168:171], v[112:115]
	v_mfma_f32_16x16x32_bf16 v[112:115], v[72:75], v[180:183], v[112:115]
	v_mfma_f32_16x16x32_bf16 v[100:103], v[108:111], v[168:171], v[100:103]
	v_mfma_f32_16x16x32_bf16 v[100:103], v[116:119], v[180:183], v[100:103]
	v_mfma_f32_16x16x32_bf16 v[104:107], v[88:91], v[168:171], v[104:107]
	v_mfma_f32_16x16x32_bf16 v[104:107], v[96:99], v[180:183], v[104:107]
	v_mfma_f32_16x16x32_bf16 v[92:95], v[128:131], v[168:171], v[92:95]
	v_mfma_f32_16x16x32_bf16 v[92:95], v[140:143], v[180:183], v[92:95]
	v_mfma_f32_16x16x32_bf16 v[84:87], v[64:67], v[184:187], v[84:87]
	v_mfma_f32_16x16x32_bf16 v[84:87], v[72:75], v[188:191], v[84:87]
	v_mfma_f32_16x16x32_bf16 v[76:79], v[108:111], v[184:187], v[76:79]
	v_mfma_f32_16x16x32_bf16 v[76:79], v[116:119], v[188:191], v[76:79]
	v_mfma_f32_16x16x32_bf16 v[80:83], v[88:91], v[184:187], v[80:83]
	v_mfma_f32_16x16x32_bf16 v[80:83], v[96:99], v[188:191], v[80:83]
	v_mfma_f32_16x16x32_bf16 v[68:71], v[128:131], v[184:187], v[68:71]
	v_mfma_f32_16x16x32_bf16 v[68:71], v[140:143], v[188:191], v[68:71]
	s_barrier
	s_add_i32 s67, s67, s2
	s_add_u32 s98, s90, 0x80
	s_addc_u32 s99, s91, 0
	s_mov_b32 m0, s67
	ds_read_b128 v[152:155], v240 offset:49152
	ds_read_b128 v[156:159], v240 offset:50176
	ds_read_b128 v[160:163], v240 offset:51200
	ds_read_b128 v[164:167], v240 offset:52224
	ds_read_b128 v[168:171], v240 offset:53248
	ds_read_b128 v[180:183], v240 offset:54272
	ds_read_b128 v[184:187], v240 offset:55296
	ds_read_b128 v[188:191], v240 offset:56320
	global_load_lds_dwordx4 v216, s[98:99]
	s_add_i32 m0, s67, 0x2000
	s_add_u32 s74, s90, 0x80080
	s_addc_u32 s75, s91, 0
	s_add_i32 s3, s3, s2
	global_load_lds_dwordx4 v228, s[98:99]
	s_mov_b32 m0, s3
	s_nop 0
	global_load_lds_dwordx4 v216, s[74:75]
	s_add_i32 m0, s3, 0x2000
	s_nop 0
	global_load_lds_dwordx4 v228, s[74:75]
	s_add_u32 s98, s92, 0x80
	s_addc_u32 s99, s93, 0
	s_mov_b32 m0, s60
	s_nop 0
	global_load_lds_dwordx4 v224, s[98:99]
	s_mov_b32 m0, s61
	s_nop 0
	global_load_lds_dwordx4 v226, s[98:99]
	s_waitcnt vmcnt(8)
	s_waitcnt lgkmcnt(0)
	s_barrier
	s_waitcnt lgkmcnt(0)
	v_mfma_f32_16x16x32_bf16 v[60:63], v[64:67], v[152:155], v[60:63]
	v_mfma_f32_16x16x32_bf16 v[60:63], v[72:75], v[156:159], v[60:63]
	v_mfma_f32_16x16x32_bf16 v[52:55], v[108:111], v[152:155], v[52:55]
	v_mfma_f32_16x16x32_bf16 v[52:55], v[116:119], v[156:159], v[52:55]
	v_mfma_f32_16x16x32_bf16 v[56:59], v[88:91], v[152:155], v[56:59]
	v_mfma_f32_16x16x32_bf16 v[56:59], v[96:99], v[156:159], v[56:59]
	v_mfma_f32_16x16x32_bf16 v[48:51], v[128:131], v[152:155], v[48:51]
	v_mfma_f32_16x16x32_bf16 v[48:51], v[140:143], v[156:159], v[48:51]
	v_mfma_f32_16x16x32_bf16 v[44:47], v[64:67], v[160:163], v[44:47]
	v_mfma_f32_16x16x32_bf16 v[44:47], v[72:75], v[164:167], v[44:47]
	v_mfma_f32_16x16x32_bf16 v[36:39], v[108:111], v[160:163], v[36:39]
	v_mfma_f32_16x16x32_bf16 v[36:39], v[116:119], v[164:167], v[36:39]
	v_mfma_f32_16x16x32_bf16 v[40:43], v[88:91], v[160:163], v[40:43]
	v_mfma_f32_16x16x32_bf16 v[40:43], v[96:99], v[164:167], v[40:43]
	v_mfma_f32_16x16x32_bf16 v[32:35], v[128:131], v[160:163], v[32:35]
	v_mfma_f32_16x16x32_bf16 v[32:35], v[140:143], v[164:167], v[32:35]
	v_mfma_f32_16x16x32_bf16 v[28:31], v[64:67], v[168:171], v[28:31]
	v_mfma_f32_16x16x32_bf16 v[28:31], v[72:75], v[180:183], v[28:31]
	v_mfma_f32_16x16x32_bf16 v[20:23], v[108:111], v[168:171], v[20:23]
	v_mfma_f32_16x16x32_bf16 v[20:23], v[116:119], v[180:183], v[20:23]
	v_mfma_f32_16x16x32_bf16 v[24:27], v[88:91], v[168:171], v[24:27]
	v_mfma_f32_16x16x32_bf16 v[24:27], v[96:99], v[180:183], v[24:27]
	v_mfma_f32_16x16x32_bf16 v[16:19], v[128:131], v[168:171], v[16:19]
	v_mfma_f32_16x16x32_bf16 v[16:19], v[140:143], v[180:183], v[16:19]
	v_mfma_f32_16x16x32_bf16 v[12:15], v[64:67], v[184:187], v[12:15]
	v_mfma_f32_16x16x32_bf16 v[12:15], v[72:75], v[188:191], v[12:15]
	v_mfma_f32_16x16x32_bf16 v[4:7], v[108:111], v[184:187], v[4:7]
	v_mfma_f32_16x16x32_bf16 v[4:7], v[116:119], v[188:191], v[4:7]
	v_mfma_f32_16x16x32_bf16 v[8:11], v[88:91], v[184:187], v[8:11]
	v_mfma_f32_16x16x32_bf16 v[8:11], v[96:99], v[188:191], v[8:11]
	v_mfma_f32_16x16x32_bf16 v[0:3], v[128:131], v[184:187], v[0:3]
	v_mfma_f32_16x16x32_bf16 v[0:3], v[140:143], v[188:191], v[0:3]
	s_barrier
	s_add_i32 s71, s71, 2
	s_add_u32 s88, s88, 0x100
	s_addc_u32 s89, s89, 0
	s_add_u32 s87, s87, 0x100
	s_addc_u32 vcc_hi, vcc_hi, 0
.LBB0_965:
	s_add_u32 s67, s88, 0xfff80080
	s_addc_u32 s74, s89, -1
	s_add_i32 s75, 0, 0x10000
	s_cmp_eq_u32 s71, 28
	s_cselect_b32 s93, s79, s74
	s_cselect_b32 s92, s96, s67
	s_cselect_b32 s91, s77, vcc_hi
	s_cselect_b32 s90, vcc_lo, s87
	s_add_i32 s67, 0, 0x14000
	v_add_u32_e32 v96, s75, v238
	v_add_u32_e32 v140, s67, v238
	ds_read_b128 v[64:67], v96
	ds_read_b128 v[72:75], v96 offset:1024
	ds_read_b128 v[88:91], v96 offset:2048
	ds_read_b128 v[96:99], v96 offset:3072
	ds_read_b128 v[108:111], v140
	ds_read_b128 v[116:119], v140 offset:1024
	ds_read_b128 v[128:131], v140 offset:2048
	ds_read_b128 v[140:143], v140 offset:3072
	s_add_i32 m0, s28, 0xc000
	ds_read_b128 v[152:155], v240
	ds_read_b128 v[156:159], v240 offset:1024
	ds_read_b128 v[160:163], v240 offset:2048
	ds_read_b128 v[164:167], v240 offset:3072
	ds_read_b128 v[168:171], v240 offset:4096
	ds_read_b128 v[180:183], v240 offset:5120
	ds_read_b128 v[184:187], v240 offset:6144
	ds_read_b128 v[188:191], v240 offset:7168
	global_load_lds_dwordx4 v230, s[88:89]
	s_add_i32 m0, s28, 0xe000
	s_nop 0
	global_load_lds_dwordx4 v232, s[88:89]
	s_waitcnt vmcnt(8)
	s_waitcnt lgkmcnt(0)
	s_barrier
	s_waitcnt lgkmcnt(0)
	v_mfma_f32_16x16x32_bf16 v[176:179], v[64:67], v[152:155], v[176:179]
	v_mfma_f32_16x16x32_bf16 v[176:179], v[72:75], v[156:159], v[176:179]
	v_mfma_f32_16x16x32_bf16 v[148:151], v[108:111], v[152:155], v[148:151]
	v_mfma_f32_16x16x32_bf16 v[148:151], v[116:119], v[156:159], v[148:151]
	v_mfma_f32_16x16x32_bf16 v[172:175], v[88:91], v[152:155], v[172:175]
	v_mfma_f32_16x16x32_bf16 v[172:175], v[96:99], v[156:159], v[172:175]
	v_mfma_f32_16x16x32_bf16 v[144:147], v[128:131], v[152:155], v[144:147]
	v_mfma_f32_16x16x32_bf16 v[144:147], v[140:143], v[156:159], v[144:147]
	v_mfma_f32_16x16x32_bf16 v[136:139], v[64:67], v[160:163], v[136:139]
	v_mfma_f32_16x16x32_bf16 v[136:139], v[72:75], v[164:167], v[136:139]
	v_mfma_f32_16x16x32_bf16 v[124:127], v[108:111], v[160:163], v[124:127]
	v_mfma_f32_16x16x32_bf16 v[124:127], v[116:119], v[164:167], v[124:127]
	v_mfma_f32_16x16x32_bf16 v[132:135], v[88:91], v[160:163], v[132:135]
	v_mfma_f32_16x16x32_bf16 v[132:135], v[96:99], v[164:167], v[132:135]
	v_mfma_f32_16x16x32_bf16 v[120:123], v[128:131], v[160:163], v[120:123]
	v_mfma_f32_16x16x32_bf16 v[120:123], v[140:143], v[164:167], v[120:123]
	v_mfma_f32_16x16x32_bf16 v[112:115], v[64:67], v[168:171], v[112:115]
	v_mfma_f32_16x16x32_bf16 v[112:115], v[72:75], v[180:183], v[112:115]
	v_mfma_f32_16x16x32_bf16 v[100:103], v[108:111], v[168:171], v[100:103]
	v_mfma_f32_16x16x32_bf16 v[100:103], v[116:119], v[180:183], v[100:103]
	v_mfma_f32_16x16x32_bf16 v[104:107], v[88:91], v[168:171], v[104:107]
	v_mfma_f32_16x16x32_bf16 v[104:107], v[96:99], v[180:183], v[104:107]
	v_mfma_f32_16x16x32_bf16 v[92:95], v[128:131], v[168:171], v[92:95]
	v_mfma_f32_16x16x32_bf16 v[92:95], v[140:143], v[180:183], v[92:95]
	v_mfma_f32_16x16x32_bf16 v[84:87], v[64:67], v[184:187], v[84:87]
	v_mfma_f32_16x16x32_bf16 v[84:87], v[72:75], v[188:191], v[84:87]
	v_mfma_f32_16x16x32_bf16 v[76:79], v[108:111], v[184:187], v[76:79]
	v_mfma_f32_16x16x32_bf16 v[76:79], v[116:119], v[188:191], v[76:79]
	v_mfma_f32_16x16x32_bf16 v[80:83], v[88:91], v[184:187], v[80:83]
	v_mfma_f32_16x16x32_bf16 v[80:83], v[96:99], v[188:191], v[80:83]
	v_mfma_f32_16x16x32_bf16 v[68:71], v[128:131], v[184:187], v[68:71]
	v_mfma_f32_16x16x32_bf16 v[68:71], v[140:143], v[188:191], v[68:71]
	s_barrier
	s_add_i32 s74, s75, s2
	s_mov_b32 m0, s74
	ds_read_b128 v[152:155], v240 offset:16384
	ds_read_b128 v[156:159], v240 offset:17408
	ds_read_b128 v[160:163], v240 offset:18432
	ds_read_b128 v[164:167], v240 offset:19456
	ds_read_b128 v[168:171], v240 offset:20480
	ds_read_b128 v[180:183], v240 offset:21504
	ds_read_b128 v[184:187], v240 offset:22528
	ds_read_b128 v[188:191], v240 offset:23552
	global_load_lds_dwordx4 v216, s[90:91]
	s_add_i32 m0, s74, 0x2000
	s_add_u32 s74, s90, 0x80000
	s_addc_u32 s75, s91, 0
	s_add_i32 s67, s67, s2
	global_load_lds_dwordx4 v228, s[90:91]
	s_mov_b32 m0, s67
	s_nop 0
	global_load_lds_dwordx4 v216, s[74:75]
	s_add_i32 m0, s67, 0x2000
	s_nop 0
	global_load_lds_dwordx4 v228, s[74:75]
	s_mov_b32 m0, s28
	s_nop 0
	global_load_lds_dwordx4 v224, s[92:93]
	s_mov_b32 m0, s29
	s_nop 0
	global_load_lds_dwordx4 v226, s[92:93]
	s_waitcnt vmcnt(8)
	s_waitcnt lgkmcnt(0)
	s_barrier
	s_waitcnt lgkmcnt(0)
	v_mfma_f32_16x16x32_bf16 v[60:63], v[64:67], v[152:155], v[60:63]
	v_mfma_f32_16x16x32_bf16 v[60:63], v[72:75], v[156:159], v[60:63]
	v_mfma_f32_16x16x32_bf16 v[52:55], v[108:111], v[152:155], v[52:55]
	v_mfma_f32_16x16x32_bf16 v[52:55], v[116:119], v[156:159], v[52:55]
	v_mfma_f32_16x16x32_bf16 v[56:59], v[88:91], v[152:155], v[56:59]
	v_mfma_f32_16x16x32_bf16 v[56:59], v[96:99], v[156:159], v[56:59]
	v_mfma_f32_16x16x32_bf16 v[48:51], v[128:131], v[152:155], v[48:51]
	v_mfma_f32_16x16x32_bf16 v[48:51], v[140:143], v[156:159], v[48:51]
	v_mfma_f32_16x16x32_bf16 v[44:47], v[64:67], v[160:163], v[44:47]
	v_mfma_f32_16x16x32_bf16 v[44:47], v[72:75], v[164:167], v[44:47]
	v_mfma_f32_16x16x32_bf16 v[36:39], v[108:111], v[160:163], v[36:39]
	v_mfma_f32_16x16x32_bf16 v[36:39], v[116:119], v[164:167], v[36:39]
	v_mfma_f32_16x16x32_bf16 v[40:43], v[88:91], v[160:163], v[40:43]
	v_mfma_f32_16x16x32_bf16 v[40:43], v[96:99], v[164:167], v[40:43]
	v_mfma_f32_16x16x32_bf16 v[32:35], v[128:131], v[160:163], v[32:35]
	v_mfma_f32_16x16x32_bf16 v[32:35], v[140:143], v[164:167], v[32:35]
	v_mfma_f32_16x16x32_bf16 v[28:31], v[64:67], v[168:171], v[28:31]
	v_mfma_f32_16x16x32_bf16 v[28:31], v[72:75], v[180:183], v[28:31]
	v_mfma_f32_16x16x32_bf16 v[20:23], v[108:111], v[168:171], v[20:23]
	v_mfma_f32_16x16x32_bf16 v[20:23], v[116:119], v[180:183], v[20:23]
	v_mfma_f32_16x16x32_bf16 v[24:27], v[88:91], v[168:171], v[24:27]
	v_mfma_f32_16x16x32_bf16 v[24:27], v[96:99], v[180:183], v[24:27]
	v_mfma_f32_16x16x32_bf16 v[16:19], v[128:131], v[168:171], v[16:19]
	v_mfma_f32_16x16x32_bf16 v[16:19], v[140:143], v[180:183], v[16:19]
	v_mfma_f32_16x16x32_bf16 v[12:15], v[64:67], v[184:187], v[12:15]
	v_mfma_f32_16x16x32_bf16 v[12:15], v[72:75], v[188:191], v[12:15]
	v_mfma_f32_16x16x32_bf16 v[4:7], v[108:111], v[184:187], v[4:7]
	v_mfma_f32_16x16x32_bf16 v[4:7], v[116:119], v[188:191], v[4:7]
	v_mfma_f32_16x16x32_bf16 v[8:11], v[88:91], v[184:187], v[8:11]
	v_mfma_f32_16x16x32_bf16 v[8:11], v[96:99], v[188:191], v[8:11]
	v_mfma_f32_16x16x32_bf16 v[0:3], v[128:131], v[184:187], v[0:3]
	v_mfma_f32_16x16x32_bf16 v[0:3], v[140:143], v[188:191], v[0:3]
	s_barrier
	s_add_i32 s67, 0, 0x18000
	s_add_i32 s3, 0, 0x1c000
	v_add_u32_e32 v96, s67, v238
	v_add_u32_e32 v140, s3, v238
	ds_read_b128 v[64:67], v96
	ds_read_b128 v[72:75], v96 offset:1024
	ds_read_b128 v[88:91], v96 offset:2048
	ds_read_b128 v[96:99], v96 offset:3072
	ds_read_b128 v[108:111], v140
	ds_read_b128 v[116:119], v140 offset:1024
	ds_read_b128 v[128:131], v140 offset:2048
	ds_read_b128 v[140:143], v140 offset:3072
	s_add_u32 s74, s92, 0x80000
	s_addc_u32 s75, s93, 0
	s_mov_b32 m0, s34
	ds_read_b128 v[152:155], v240 offset:32768
	ds_read_b128 v[156:159], v240 offset:33792
	ds_read_b128 v[160:163], v240 offset:34816
	ds_read_b128 v[164:167], v240 offset:35840
	ds_read_b128 v[168:171], v240 offset:36864
	ds_read_b128 v[180:183], v240 offset:37888
	ds_read_b128 v[184:187], v240 offset:38912
	ds_read_b128 v[188:191], v240 offset:39936
	global_load_lds_dwordx4 v224, s[74:75]
	s_mov_b32 m0, s35
	s_nop 0
	global_load_lds_dwordx4 v226, s[74:75]
	s_waitcnt vmcnt(8)
	s_waitcnt lgkmcnt(0)
	s_barrier
	s_waitcnt lgkmcnt(0)
	v_mfma_f32_16x16x32_bf16 v[176:179], v[64:67], v[152:155], v[176:179]
	v_mfma_f32_16x16x32_bf16 v[176:179], v[72:75], v[156:159], v[176:179]
	v_mfma_f32_16x16x32_bf16 v[148:151], v[108:111], v[152:155], v[148:151]
	v_mfma_f32_16x16x32_bf16 v[148:151], v[116:119], v[156:159], v[148:151]
	v_mfma_f32_16x16x32_bf16 v[172:175], v[88:91], v[152:155], v[172:175]
	v_mfma_f32_16x16x32_bf16 v[172:175], v[96:99], v[156:159], v[172:175]
	v_mfma_f32_16x16x32_bf16 v[144:147], v[128:131], v[152:155], v[144:147]
	v_mfma_f32_16x16x32_bf16 v[144:147], v[140:143], v[156:159], v[144:147]
	v_mfma_f32_16x16x32_bf16 v[136:139], v[64:67], v[160:163], v[136:139]
	v_mfma_f32_16x16x32_bf16 v[136:139], v[72:75], v[164:167], v[136:139]
	v_mfma_f32_16x16x32_bf16 v[124:127], v[108:111], v[160:163], v[124:127]
	v_mfma_f32_16x16x32_bf16 v[124:127], v[116:119], v[164:167], v[124:127]
	v_mfma_f32_16x16x32_bf16 v[132:135], v[88:91], v[160:163], v[132:135]
	v_mfma_f32_16x16x32_bf16 v[132:135], v[96:99], v[164:167], v[132:135]
	v_mfma_f32_16x16x32_bf16 v[120:123], v[128:131], v[160:163], v[120:123]
	v_mfma_f32_16x16x32_bf16 v[120:123], v[140:143], v[164:167], v[120:123]
	v_mfma_f32_16x16x32_bf16 v[112:115], v[64:67], v[168:171], v[112:115]
	v_mfma_f32_16x16x32_bf16 v[112:115], v[72:75], v[180:183], v[112:115]
	v_mfma_f32_16x16x32_bf16 v[100:103], v[108:111], v[168:171], v[100:103]
	v_mfma_f32_16x16x32_bf16 v[100:103], v[116:119], v[180:183], v[100:103]
	v_mfma_f32_16x16x32_bf16 v[104:107], v[88:91], v[168:171], v[104:107]
	v_mfma_f32_16x16x32_bf16 v[104:107], v[96:99], v[180:183], v[104:107]
	v_mfma_f32_16x16x32_bf16 v[92:95], v[128:131], v[168:171], v[92:95]
	v_mfma_f32_16x16x32_bf16 v[92:95], v[140:143], v[180:183], v[92:95]
	v_mfma_f32_16x16x32_bf16 v[84:87], v[64:67], v[184:187], v[84:87]
	v_mfma_f32_16x16x32_bf16 v[84:87], v[72:75], v[188:191], v[84:87]
	v_mfma_f32_16x16x32_bf16 v[76:79], v[108:111], v[184:187], v[76:79]
	v_mfma_f32_16x16x32_bf16 v[76:79], v[116:119], v[188:191], v[76:79]
	v_mfma_f32_16x16x32_bf16 v[80:83], v[88:91], v[184:187], v[80:83]
	v_mfma_f32_16x16x32_bf16 v[80:83], v[96:99], v[188:191], v[80:83]
	v_mfma_f32_16x16x32_bf16 v[68:71], v[128:131], v[184:187], v[68:71]
	v_mfma_f32_16x16x32_bf16 v[68:71], v[140:143], v[188:191], v[68:71]
	s_barrier
	s_add_i32 s67, s67, s2
	s_add_u32 s98, s90, 0x80
	s_addc_u32 s99, s91, 0
	s_mov_b32 m0, s67
	ds_read_b128 v[152:155], v240 offset:49152
	ds_read_b128 v[156:159], v240 offset:50176
	ds_read_b128 v[160:163], v240 offset:51200
	ds_read_b128 v[164:167], v240 offset:52224
	ds_read_b128 v[168:171], v240 offset:53248
	ds_read_b128 v[180:183], v240 offset:54272
	ds_read_b128 v[184:187], v240 offset:55296
	ds_read_b128 v[188:191], v240 offset:56320
	global_load_lds_dwordx4 v216, s[98:99]
	s_add_i32 m0, s67, 0x2000
	s_add_u32 s74, s90, 0x80080
	s_addc_u32 s75, s91, 0
	s_add_i32 s3, s3, s2
	global_load_lds_dwordx4 v228, s[98:99]
	s_mov_b32 m0, s3
	s_nop 0
	global_load_lds_dwordx4 v216, s[74:75]
	s_add_i32 m0, s3, 0x2000
	s_nop 0
	global_load_lds_dwordx4 v228, s[74:75]
	s_add_u32 s98, s92, 0x80
	s_addc_u32 s99, s93, 0
	s_mov_b32 m0, s60
	s_nop 0
	global_load_lds_dwordx4 v224, s[98:99]
	s_mov_b32 m0, s61
	s_nop 0
	global_load_lds_dwordx4 v226, s[98:99]
	s_waitcnt vmcnt(8)
	s_waitcnt lgkmcnt(0)
	s_barrier
	s_waitcnt lgkmcnt(0)
	v_mfma_f32_16x16x32_bf16 v[60:63], v[64:67], v[152:155], v[60:63]
	v_mfma_f32_16x16x32_bf16 v[60:63], v[72:75], v[156:159], v[60:63]
	v_mfma_f32_16x16x32_bf16 v[52:55], v[108:111], v[152:155], v[52:55]
	v_mfma_f32_16x16x32_bf16 v[52:55], v[116:119], v[156:159], v[52:55]
	v_mfma_f32_16x16x32_bf16 v[56:59], v[88:91], v[152:155], v[56:59]
	v_mfma_f32_16x16x32_bf16 v[56:59], v[96:99], v[156:159], v[56:59]
	v_mfma_f32_16x16x32_bf16 v[48:51], v[128:131], v[152:155], v[48:51]
	v_mfma_f32_16x16x32_bf16 v[48:51], v[140:143], v[156:159], v[48:51]
	v_mfma_f32_16x16x32_bf16 v[44:47], v[64:67], v[160:163], v[44:47]
	v_mfma_f32_16x16x32_bf16 v[44:47], v[72:75], v[164:167], v[44:47]
	v_mfma_f32_16x16x32_bf16 v[36:39], v[108:111], v[160:163], v[36:39]
	v_mfma_f32_16x16x32_bf16 v[36:39], v[116:119], v[164:167], v[36:39]
	v_mfma_f32_16x16x32_bf16 v[40:43], v[88:91], v[160:163], v[40:43]
	v_mfma_f32_16x16x32_bf16 v[40:43], v[96:99], v[164:167], v[40:43]
	v_mfma_f32_16x16x32_bf16 v[32:35], v[128:131], v[160:163], v[32:35]
	v_mfma_f32_16x16x32_bf16 v[32:35], v[140:143], v[164:167], v[32:35]
	v_mfma_f32_16x16x32_bf16 v[28:31], v[64:67], v[168:171], v[28:31]
	v_mfma_f32_16x16x32_bf16 v[28:31], v[72:75], v[180:183], v[28:31]
	v_mfma_f32_16x16x32_bf16 v[20:23], v[108:111], v[168:171], v[20:23]
	v_mfma_f32_16x16x32_bf16 v[20:23], v[116:119], v[180:183], v[20:23]
	v_mfma_f32_16x16x32_bf16 v[24:27], v[88:91], v[168:171], v[24:27]
	v_mfma_f32_16x16x32_bf16 v[24:27], v[96:99], v[180:183], v[24:27]
	v_mfma_f32_16x16x32_bf16 v[16:19], v[128:131], v[168:171], v[16:19]
	v_mfma_f32_16x16x32_bf16 v[16:19], v[140:143], v[180:183], v[16:19]
	v_mfma_f32_16x16x32_bf16 v[12:15], v[64:67], v[184:187], v[12:15]
	v_mfma_f32_16x16x32_bf16 v[12:15], v[72:75], v[188:191], v[12:15]
	v_mfma_f32_16x16x32_bf16 v[4:7], v[108:111], v[184:187], v[4:7]
	v_mfma_f32_16x16x32_bf16 v[4:7], v[116:119], v[188:191], v[4:7]
	v_mfma_f32_16x16x32_bf16 v[8:11], v[88:91], v[184:187], v[8:11]
	v_mfma_f32_16x16x32_bf16 v[8:11], v[96:99], v[188:191], v[8:11]
	v_mfma_f32_16x16x32_bf16 v[0:3], v[128:131], v[184:187], v[0:3]
	v_mfma_f32_16x16x32_bf16 v[0:3], v[140:143], v[188:191], v[0:3]
	s_barrier
	s_add_i32 s71, s71, 2
	s_add_u32 s88, s88, 0x100
	s_addc_u32 s89, s89, 0
	s_add_u32 s87, s87, 0x100
	s_addc_u32 vcc_hi, vcc_hi, 0
	s_cmp_gt_u32 s71, 29
	s_cbranch_scc0 .LBB0_965
	s_and_b64 vcc, exec, s[22:23]
	s_cbranch_vccz .LBB0_968
	s_barrier

.LBB0_1189:
	s_ashr_i32 s75, s74, 31
	s_lshl_b64 s[72:73], s[74:75], 20
	s_add_u32 s76, s2, s72
	s_addc_u32 s77, s3, s73
	s_and_b64 s[72:73], s[4:5], exec
	s_cselect_b32 s71, s77, s83
	s_cselect_b32 s72, s76, s82
	s_ashr_i32 s23, s22, 31
	s_lshl_b64 s[78:79], s[22:23], 20
	s_add_u32 s78, s14, s78
	s_addc_u32 s79, s15, s79
	s_and_b64 s[86:87], s[4:5], exec
	s_cselect_b32 s23, s79, s85
	s_cselect_b32 s73, s78, s84
	s_add_u32 s82, s82, 0x80080
	s_addc_u32 s83, s83, 0
	s_add_u32 s75, s84, 0x100
	s_addc_u32 s81, s85, 0
	s_mov_b32 s88, -2
	s_add_u32 s67, s82, 0xfff80080
	s_addc_u32 s84, s83, -1
	s_add_i32 s89, 0, 0x10000
	s_cmp_eq_u32 s88, 28
	s_cselect_b32 s87, s71, s84
	s_cselect_b32 s86, s72, s67
	s_cselect_b32 s85, s23, s81
	s_cselect_b32 s84, s73, s75
	s_add_i32 s67, 0, 0x14000
	v_add_u32_e32 v76, s89, v192
	v_add_u32_e32 v156, s67, v192
	ds_read_b128 v[64:67], v76
	ds_read_b128 v[68:71], v76 offset:1024
	ds_read_b128 v[72:75], v76 offset:2048
	ds_read_b128 v[76:79], v76 offset:3072
	ds_read_b128 v[80:83], v156
	ds_read_b128 v[116:119], v156 offset:1024
	ds_read_b128 v[152:155], v156 offset:2048
	ds_read_b128 v[156:159], v156 offset:3072
	s_add_i32 m0, s28, 0xc000
	ds_read_b128 v[160:163], v193
	ds_read_b128 v[164:167], v193 offset:1024
	ds_read_b128 v[168:171], v193 offset:2048
	ds_read_b128 v[172:175], v193 offset:3072
	ds_read_b128 v[194:197], v193 offset:4096
	ds_read_b128 v[198:201], v193 offset:5120
	ds_read_b128 v[202:205], v193 offset:6144
	ds_read_b128 v[206:209], v193 offset:7168
	global_load_lds_dwordx4 v186, s[82:83]
	s_add_i32 m0, s28, 0xe000
	s_nop 0
	global_load_lds_dwordx4 v188, s[82:83]
	s_waitcnt vmcnt(8)
	s_waitcnt lgkmcnt(0)
	s_barrier
	s_waitcnt lgkmcnt(0)
	v_mfma_f32_16x16x32_bf16 v[148:151], v[64:67], v[160:163], 0
	v_mfma_f32_16x16x32_bf16 v[148:151], v[68:71], v[164:167], v[148:151]
	v_mfma_f32_16x16x32_bf16 v[140:143], v[80:83], v[160:163], 0
	v_mfma_f32_16x16x32_bf16 v[140:143], v[116:119], v[164:167], v[140:143]
	v_mfma_f32_16x16x32_bf16 v[144:147], v[72:75], v[160:163], 0
	v_mfma_f32_16x16x32_bf16 v[144:147], v[76:79], v[164:167], v[144:147]
	v_mfma_f32_16x16x32_bf16 v[136:139], v[152:155], v[160:163], 0
	v_mfma_f32_16x16x32_bf16 v[136:139], v[156:159], v[164:167], v[136:139]
	v_mfma_f32_16x16x32_bf16 v[132:135], v[64:67], v[168:171], 0
	v_mfma_f32_16x16x32_bf16 v[132:135], v[68:71], v[172:175], v[132:135]
	v_mfma_f32_16x16x32_bf16 v[124:127], v[80:83], v[168:171], 0
	v_mfma_f32_16x16x32_bf16 v[124:127], v[116:119], v[172:175], v[124:127]
	v_mfma_f32_16x16x32_bf16 v[128:131], v[72:75], v[168:171], 0
	v_mfma_f32_16x16x32_bf16 v[128:131], v[76:79], v[172:175], v[128:131]
	v_mfma_f32_16x16x32_bf16 v[120:123], v[152:155], v[168:171], 0
	v_mfma_f32_16x16x32_bf16 v[120:123], v[156:159], v[172:175], v[120:123]
	v_mfma_f32_16x16x32_bf16 v[112:115], v[64:67], v[194:197], 0
	v_mfma_f32_16x16x32_bf16 v[112:115], v[68:71], v[198:201], v[112:115]
	v_mfma_f32_16x16x32_bf16 v[104:107], v[80:83], v[194:197], 0
	v_mfma_f32_16x16x32_bf16 v[104:107], v[116:119], v[198:201], v[104:107]
	v_mfma_f32_16x16x32_bf16 v[108:111], v[72:75], v[194:197], 0
	v_mfma_f32_16x16x32_bf16 v[108:111], v[76:79], v[198:201], v[108:111]
	v_mfma_f32_16x16x32_bf16 v[100:103], v[152:155], v[194:197], 0
	v_mfma_f32_16x16x32_bf16 v[100:103], v[156:159], v[198:201], v[100:103]
	v_mfma_f32_16x16x32_bf16 v[96:99], v[64:67], v[202:205], 0
	v_mfma_f32_16x16x32_bf16 v[96:99], v[68:71], v[206:209], v[96:99]
	v_mfma_f32_16x16x32_bf16 v[88:91], v[80:83], v[202:205], 0
	v_mfma_f32_16x16x32_bf16 v[88:91], v[116:119], v[206:209], v[88:91]
	v_mfma_f32_16x16x32_bf16 v[92:95], v[72:75], v[202:205], 0
	v_mfma_f32_16x16x32_bf16 v[92:95], v[76:79], v[206:209], v[92:95]
	v_mfma_f32_16x16x32_bf16 v[84:87], v[152:155], v[202:205], 0
	v_mfma_f32_16x16x32_bf16 v[84:87], v[156:159], v[206:209], v[84:87]
	s_barrier
	s_add_i32 s89, s89, s24
	s_mov_b32 m0, s89
	ds_read_b128 v[160:163], v193 offset:16384
	ds_read_b128 v[164:167], v193 offset:17408
	ds_read_b128 v[168:171], v193 offset:18432
	ds_read_b128 v[172:175], v193 offset:19456
	ds_read_b128 v[194:197], v193 offset:20480
	ds_read_b128 v[198:201], v193 offset:21504
	ds_read_b128 v[202:205], v193 offset:22528
	ds_read_b128 v[206:209], v193 offset:23552
	global_load_lds_dwordx4 v180, s[84:85]
	s_add_i32 m0, s89, 0x2000
	s_add_u32 s90, s84, 0x80000
	s_addc_u32 s91, s85, 0
	s_add_i32 s67, s67, s24
	global_load_lds_dwordx4 v176, s[84:85]
	s_mov_b32 m0, s67
	s_nop 0
	global_load_lds_dwordx4 v180, s[90:91]
	s_add_i32 m0, s67, 0x2000
	s_nop 0
	global_load_lds_dwordx4 v176, s[90:91]
	s_mov_b32 m0, s28
	s_nop 0
	global_load_lds_dwordx4 v182, s[86:87]
	s_mov_b32 m0, s29
	s_nop 0
	global_load_lds_dwordx4 v178, s[86:87]
	s_waitcnt vmcnt(8)
	s_waitcnt lgkmcnt(0)
	s_barrier
	s_waitcnt lgkmcnt(0)
	v_mfma_f32_16x16x32_bf16 v[60:63], v[64:67], v[160:163], 0
	v_mfma_f32_16x16x32_bf16 v[60:63], v[68:71], v[164:167], v[60:63]
	v_mfma_f32_16x16x32_bf16 v[52:55], v[80:83], v[160:163], 0
	v_mfma_f32_16x16x32_bf16 v[52:55], v[116:119], v[164:167], v[52:55]
	v_mfma_f32_16x16x32_bf16 v[56:59], v[72:75], v[160:163], 0
	v_mfma_f32_16x16x32_bf16 v[56:59], v[76:79], v[164:167], v[56:59]
	v_mfma_f32_16x16x32_bf16 v[48:51], v[152:155], v[160:163], 0
	v_mfma_f32_16x16x32_bf16 v[48:51], v[156:159], v[164:167], v[48:51]
	v_mfma_f32_16x16x32_bf16 v[44:47], v[64:67], v[168:171], 0
	v_mfma_f32_16x16x32_bf16 v[44:47], v[68:71], v[172:175], v[44:47]
	v_mfma_f32_16x16x32_bf16 v[36:39], v[80:83], v[168:171], 0
	v_mfma_f32_16x16x32_bf16 v[36:39], v[116:119], v[172:175], v[36:39]
	v_mfma_f32_16x16x32_bf16 v[40:43], v[72:75], v[168:171], 0
	v_mfma_f32_16x16x32_bf16 v[40:43], v[76:79], v[172:175], v[40:43]
	v_mfma_f32_16x16x32_bf16 v[32:35], v[152:155], v[168:171], 0
	v_mfma_f32_16x16x32_bf16 v[32:35], v[156:159], v[172:175], v[32:35]
	v_mfma_f32_16x16x32_bf16 v[28:31], v[64:67], v[194:197], 0
	v_mfma_f32_16x16x32_bf16 v[28:31], v[68:71], v[198:201], v[28:31]
	v_mfma_f32_16x16x32_bf16 v[20:23], v[80:83], v[194:197], 0
	v_mfma_f32_16x16x32_bf16 v[20:23], v[116:119], v[198:201], v[20:23]
	v_mfma_f32_16x16x32_bf16 v[24:27], v[72:75], v[194:197], 0
	v_mfma_f32_16x16x32_bf16 v[24:27], v[76:79], v[198:201], v[24:27]
	v_mfma_f32_16x16x32_bf16 v[16:19], v[152:155], v[194:197], 0
	v_mfma_f32_16x16x32_bf16 v[16:19], v[156:159], v[198:201], v[16:19]
	v_mfma_f32_16x16x32_bf16 v[12:15], v[64:67], v[202:205], 0
	v_mfma_f32_16x16x32_bf16 v[12:15], v[68:71], v[206:209], v[12:15]
	v_mfma_f32_16x16x32_bf16 v[4:7], v[80:83], v[202:205], 0
	v_mfma_f32_16x16x32_bf16 v[4:7], v[116:119], v[206:209], v[4:7]
	v_mfma_f32_16x16x32_bf16 v[8:11], v[72:75], v[202:205], 0
	v_mfma_f32_16x16x32_bf16 v[8:11], v[76:79], v[206:209], v[8:11]
	v_mfma_f32_16x16x32_bf16 v[0:3], v[152:155], v[202:205], 0
	v_mfma_f32_16x16x32_bf16 v[0:3], v[156:159], v[206:209], v[0:3]
	s_barrier
	s_add_i32 s67, 0, 0x18000
	s_add_i32 s89, 0, 0x1c000
	v_add_u32_e32 v76, s67, v192
	v_add_u32_e32 v156, s89, v192
	ds_read_b128 v[64:67], v76
	ds_read_b128 v[68:71], v76 offset:1024
	ds_read_b128 v[72:75], v76 offset:2048
	ds_read_b128 v[76:79], v76 offset:3072
	ds_read_b128 v[80:83], v156
	ds_read_b128 v[116:119], v156 offset:1024
	ds_read_b128 v[152:155], v156 offset:2048
	ds_read_b128 v[156:159], v156 offset:3072
	s_add_u32 s86, s86, 0x80000
	s_addc_u32 s87, s87, 0
	s_mov_b32 m0, s34
	ds_read_b128 v[160:163], v193 offset:32768
	ds_read_b128 v[164:167], v193 offset:33792
	ds_read_b128 v[168:171], v193 offset:34816
	ds_read_b128 v[172:175], v193 offset:35840
	ds_read_b128 v[194:197], v193 offset:36864
	ds_read_b128 v[198:201], v193 offset:37888
	ds_read_b128 v[202:205], v193 offset:38912
	ds_read_b128 v[206:209], v193 offset:39936
	global_load_lds_dwordx4 v182, s[86:87]
	s_mov_b32 m0, s35
	s_nop 0
	global_load_lds_dwordx4 v178, s[86:87]
	s_waitcnt vmcnt(8)
	s_waitcnt lgkmcnt(0)
	s_barrier
	s_waitcnt lgkmcnt(0)
	v_mfma_f32_16x16x32_bf16 v[148:151], v[64:67], v[160:163], v[148:151]
	v_mfma_f32_16x16x32_bf16 v[148:151], v[68:71], v[164:167], v[148:151]
	v_mfma_f32_16x16x32_bf16 v[140:143], v[80:83], v[160:163], v[140:143]
	v_mfma_f32_16x16x32_bf16 v[140:143], v[116:119], v[164:167], v[140:143]
	v_mfma_f32_16x16x32_bf16 v[144:147], v[72:75], v[160:163], v[144:147]
	v_mfma_f32_16x16x32_bf16 v[144:147], v[76:79], v[164:167], v[144:147]
	v_mfma_f32_16x16x32_bf16 v[136:139], v[152:155], v[160:163], v[136:139]
	v_mfma_f32_16x16x32_bf16 v[136:139], v[156:159], v[164:167], v[136:139]
	v_mfma_f32_16x16x32_bf16 v[132:135], v[64:67], v[168:171], v[132:135]
	v_mfma_f32_16x16x32_bf16 v[132:135], v[68:71], v[172:175], v[132:135]
	v_mfma_f32_16x16x32_bf16 v[124:127], v[80:83], v[168:171], v[124:127]
	v_mfma_f32_16x16x32_bf16 v[124:127], v[116:119], v[172:175], v[124:127]
	v_mfma_f32_16x16x32_bf16 v[128:131], v[72:75], v[168:171], v[128:131]
	v_mfma_f32_16x16x32_bf16 v[128:131], v[76:79], v[172:175], v[128:131]
	v_mfma_f32_16x16x32_bf16 v[120:123], v[152:155], v[168:171], v[120:123]
	v_mfma_f32_16x16x32_bf16 v[120:123], v[156:159], v[172:175], v[120:123]
	v_mfma_f32_16x16x32_bf16 v[112:115], v[64:67], v[194:197], v[112:115]
	v_mfma_f32_16x16x32_bf16 v[112:115], v[68:71], v[198:201], v[112:115]
	v_mfma_f32_16x16x32_bf16 v[104:107], v[80:83], v[194:197], v[104:107]
	v_mfma_f32_16x16x32_bf16 v[104:107], v[116:119], v[198:201], v[104:107]
	v_mfma_f32_16x16x32_bf16 v[108:111], v[72:75], v[194:197], v[108:111]
	v_mfma_f32_16x16x32_bf16 v[108:111], v[76:79], v[198:201], v[108:111]
	v_mfma_f32_16x16x32_bf16 v[100:103], v[152:155], v[194:197], v[100:103]
	v_mfma_f32_16x16x32_bf16 v[100:103], v[156:159], v[198:201], v[100:103]
	v_mfma_f32_16x16x32_bf16 v[96:99], v[64:67], v[202:205], v[96:99]
	v_mfma_f32_16x16x32_bf16 v[96:99], v[68:71], v[206:209], v[96:99]
	v_mfma_f32_16x16x32_bf16 v[88:91], v[80:83], v[202:205], v[88:91]
	v_mfma_f32_16x16x32_bf16 v[88:91], v[116:119], v[206:209], v[88:91]
	v_mfma_f32_16x16x32_bf16 v[92:95], v[72:75], v[202:205], v[92:95]
	v_mfma_f32_16x16x32_bf16 v[92:95], v[76:79], v[206:209], v[92:95]
	v_mfma_f32_16x16x32_bf16 v[84:87], v[152:155], v[202:205], v[84:87]
	v_mfma_f32_16x16x32_bf16 v[84:87], v[156:159], v[206:209], v[84:87]
	s_barrier
	s_add_i32 s67, s67, s24
	s_add_u32 s98, s84, 0x80
	s_addc_u32 s99, s85, 0
	s_mov_b32 m0, s67
	ds_read_b128 v[160:163], v193 offset:49152
	ds_read_b128 v[164:167], v193 offset:50176
	ds_read_b128 v[168:171], v193 offset:51200
	ds_read_b128 v[172:175], v193 offset:52224
	ds_read_b128 v[194:197], v193 offset:53248
	ds_read_b128 v[198:201], v193 offset:54272
	ds_read_b128 v[202:205], v193 offset:55296
	ds_read_b128 v[206:209], v193 offset:56320
	global_load_lds_dwordx4 v180, s[98:99]
	s_add_i32 m0, s67, 0x2000
	s_add_u32 s84, s84, 0x80080
	s_addc_u32 s85, s85, 0
	s_add_i32 s67, s89, s24
	global_load_lds_dwordx4 v176, s[98:99]
	s_mov_b32 m0, s67
	s_nop 0
	global_load_lds_dwordx4 v180, s[84:85]
	s_add_i32 m0, s67, 0x2000
	s_nop 0
	global_load_lds_dwordx4 v176, s[84:85]
	s_add_u32 s98, s86, 0xfff80080
	s_addc_u32 s99, s87, -1
	s_mov_b32 m0, s53
	s_nop 0
	global_load_lds_dwordx4 v182, s[98:99]
	s_mov_b32 m0, s54
	s_nop 0
	global_load_lds_dwordx4 v178, s[98:99]
	s_waitcnt vmcnt(8)
	s_waitcnt lgkmcnt(0)
	s_barrier
	s_waitcnt lgkmcnt(0)
	v_mfma_f32_16x16x32_bf16 v[60:63], v[64:67], v[160:163], v[60:63]
	v_mfma_f32_16x16x32_bf16 v[60:63], v[68:71], v[164:167], v[60:63]
	v_mfma_f32_16x16x32_bf16 v[52:55], v[80:83], v[160:163], v[52:55]
	v_mfma_f32_16x16x32_bf16 v[52:55], v[116:119], v[164:167], v[52:55]
	v_mfma_f32_16x16x32_bf16 v[56:59], v[72:75], v[160:163], v[56:59]
	v_mfma_f32_16x16x32_bf16 v[56:59], v[76:79], v[164:167], v[56:59]
	v_mfma_f32_16x16x32_bf16 v[48:51], v[152:155], v[160:163], v[48:51]
	v_mfma_f32_16x16x32_bf16 v[48:51], v[156:159], v[164:167], v[48:51]
	v_mfma_f32_16x16x32_bf16 v[44:47], v[64:67], v[168:171], v[44:47]
	v_mfma_f32_16x16x32_bf16 v[44:47], v[68:71], v[172:175], v[44:47]
	v_mfma_f32_16x16x32_bf16 v[36:39], v[80:83], v[168:171], v[36:39]
	v_mfma_f32_16x16x32_bf16 v[36:39], v[116:119], v[172:175], v[36:39]
	v_mfma_f32_16x16x32_bf16 v[40:43], v[72:75], v[168:171], v[40:43]
	v_mfma_f32_16x16x32_bf16 v[40:43], v[76:79], v[172:175], v[40:43]
	v_mfma_f32_16x16x32_bf16 v[32:35], v[152:155], v[168:171], v[32:35]
	v_mfma_f32_16x16x32_bf16 v[32:35], v[156:159], v[172:175], v[32:35]
	v_mfma_f32_16x16x32_bf16 v[28:31], v[64:67], v[194:197], v[28:31]
	v_mfma_f32_16x16x32_bf16 v[28:31], v[68:71], v[198:201], v[28:31]
	v_mfma_f32_16x16x32_bf16 v[20:23], v[80:83], v[194:197], v[20:23]
	v_mfma_f32_16x16x32_bf16 v[20:23], v[116:119], v[198:201], v[20:23]
	v_mfma_f32_16x16x32_bf16 v[24:27], v[72:75], v[194:197], v[24:27]
	v_mfma_f32_16x16x32_bf16 v[24:27], v[76:79], v[198:201], v[24:27]
	v_mfma_f32_16x16x32_bf16 v[16:19], v[152:155], v[194:197], v[16:19]
	v_mfma_f32_16x16x32_bf16 v[16:19], v[156:159], v[198:201], v[16:19]
	v_mfma_f32_16x16x32_bf16 v[12:15], v[64:67], v[202:205], v[12:15]
	v_mfma_f32_16x16x32_bf16 v[12:15], v[68:71], v[206:209], v[12:15]
	v_mfma_f32_16x16x32_bf16 v[4:7], v[80:83], v[202:205], v[4:7]
	v_mfma_f32_16x16x32_bf16 v[4:7], v[116:119], v[206:209], v[4:7]
	v_mfma_f32_16x16x32_bf16 v[8:11], v[72:75], v[202:205], v[8:11]
	v_mfma_f32_16x16x32_bf16 v[8:11], v[76:79], v[206:209], v[8:11]
	v_mfma_f32_16x16x32_bf16 v[0:3], v[152:155], v[202:205], v[0:3]
	v_mfma_f32_16x16x32_bf16 v[0:3], v[156:159], v[206:209], v[0:3]
	s_barrier
	s_add_i32 s88, s88, 2
	s_add_u32 s82, s82, 0x100
	s_addc_u32 s83, s83, 0
	s_add_u32 s75, s75, 0x100
	s_addc_u32 s81, s81, 0
.LBB0_1190:
	s_add_u32 s67, s82, 0xfff80080
	s_addc_u32 s84, s83, -1
	s_add_i32 s89, 0, 0x10000
	s_cmp_eq_u32 s88, 28
	s_cselect_b32 s87, s71, s84
	s_cselect_b32 s86, s72, s67
	s_cselect_b32 s85, s23, s81
	s_cselect_b32 s84, s73, s75
	s_add_i32 s67, 0, 0x14000
	v_add_u32_e32 v76, s89, v192
	v_add_u32_e32 v156, s67, v192
	ds_read_b128 v[64:67], v76
	ds_read_b128 v[68:71], v76 offset:1024
	ds_read_b128 v[72:75], v76 offset:2048
	ds_read_b128 v[76:79], v76 offset:3072
	ds_read_b128 v[80:83], v156
	ds_read_b128 v[116:119], v156 offset:1024
	ds_read_b128 v[152:155], v156 offset:2048
	ds_read_b128 v[156:159], v156 offset:3072
	s_add_i32 m0, s28, 0xc000
	ds_read_b128 v[160:163], v193
	ds_read_b128 v[164:167], v193 offset:1024
	ds_read_b128 v[168:171], v193 offset:2048
	ds_read_b128 v[172:175], v193 offset:3072
	ds_read_b128 v[194:197], v193 offset:4096
	ds_read_b128 v[198:201], v193 offset:5120
	ds_read_b128 v[202:205], v193 offset:6144
	ds_read_b128 v[206:209], v193 offset:7168
	global_load_lds_dwordx4 v186, s[82:83]
	s_add_i32 m0, s28, 0xe000
	s_nop 0
	global_load_lds_dwordx4 v188, s[82:83]
	s_waitcnt vmcnt(8)
	s_waitcnt lgkmcnt(0)
	s_barrier
	s_waitcnt lgkmcnt(0)
	v_mfma_f32_16x16x32_bf16 v[148:151], v[64:67], v[160:163], v[148:151]
	v_mfma_f32_16x16x32_bf16 v[148:151], v[68:71], v[164:167], v[148:151]
	v_mfma_f32_16x16x32_bf16 v[140:143], v[80:83], v[160:163], v[140:143]
	v_mfma_f32_16x16x32_bf16 v[140:143], v[116:119], v[164:167], v[140:143]
	v_mfma_f32_16x16x32_bf16 v[144:147], v[72:75], v[160:163], v[144:147]
	v_mfma_f32_16x16x32_bf16 v[144:147], v[76:79], v[164:167], v[144:147]
	v_mfma_f32_16x16x32_bf16 v[136:139], v[152:155], v[160:163], v[136:139]
	v_mfma_f32_16x16x32_bf16 v[136:139], v[156:159], v[164:167], v[136:139]
	v_mfma_f32_16x16x32_bf16 v[132:135], v[64:67], v[168:171], v[132:135]
	v_mfma_f32_16x16x32_bf16 v[132:135], v[68:71], v[172:175], v[132:135]
	v_mfma_f32_16x16x32_bf16 v[124:127], v[80:83], v[168:171], v[124:127]
	v_mfma_f32_16x16x32_bf16 v[124:127], v[116:119], v[172:175], v[124:127]
	v_mfma_f32_16x16x32_bf16 v[128:131], v[72:75], v[168:171], v[128:131]
	v_mfma_f32_16x16x32_bf16 v[128:131], v[76:79], v[172:175], v[128:131]
	v_mfma_f32_16x16x32_bf16 v[120:123], v[152:155], v[168:171], v[120:123]
	v_mfma_f32_16x16x32_bf16 v[120:123], v[156:159], v[172:175], v[120:123]
	v_mfma_f32_16x16x32_bf16 v[112:115], v[64:67], v[194:197], v[112:115]
	v_mfma_f32_16x16x32_bf16 v[112:115], v[68:71], v[198:201], v[112:115]
	v_mfma_f32_16x16x32_bf16 v[104:107], v[80:83], v[194:197], v[104:107]
	v_mfma_f32_16x16x32_bf16 v[104:107], v[116:119], v[198:201], v[104:107]
	v_mfma_f32_16x16x32_bf16 v[108:111], v[72:75], v[194:197], v[108:111]
	v_mfma_f32_16x16x32_bf16 v[108:111], v[76:79], v[198:201], v[108:111]
	v_mfma_f32_16x16x32_bf16 v[100:103], v[152:155], v[194:197], v[100:103]
	v_mfma_f32_16x16x32_bf16 v[100:103], v[156:159], v[198:201], v[100:103]
	v_mfma_f32_16x16x32_bf16 v[96:99], v[64:67], v[202:205], v[96:99]
	v_mfma_f32_16x16x32_bf16 v[96:99], v[68:71], v[206:209], v[96:99]
	v_mfma_f32_16x16x32_bf16 v[88:91], v[80:83], v[202:205], v[88:91]
	v_mfma_f32_16x16x32_bf16 v[88:91], v[116:119], v[206:209], v[88:91]
	v_mfma_f32_16x16x32_bf16 v[92:95], v[72:75], v[202:205], v[92:95]
	v_mfma_f32_16x16x32_bf16 v[92:95], v[76:79], v[206:209], v[92:95]
	v_mfma_f32_16x16x32_bf16 v[84:87], v[152:155], v[202:205], v[84:87]
	v_mfma_f32_16x16x32_bf16 v[84:87], v[156:159], v[206:209], v[84:87]
	s_barrier
	s_add_i32 s89, s89, s24
	s_mov_b32 m0, s89
	ds_read_b128 v[160:163], v193 offset:16384
	ds_read_b128 v[164:167], v193 offset:17408
	ds_read_b128 v[168:171], v193 offset:18432
	ds_read_b128 v[172:175], v193 offset:19456
	ds_read_b128 v[194:197], v193 offset:20480
	ds_read_b128 v[198:201], v193 offset:21504
	ds_read_b128 v[202:205], v193 offset:22528
	ds_read_b128 v[206:209], v193 offset:23552
	global_load_lds_dwordx4 v180, s[84:85]
	s_add_i32 m0, s89, 0x2000
	s_add_u32 s90, s84, 0x80000
	s_addc_u32 s91, s85, 0
	s_add_i32 s67, s67, s24
	global_load_lds_dwordx4 v176, s[84:85]
	s_mov_b32 m0, s67
	s_nop 0
	global_load_lds_dwordx4 v180, s[90:91]
	s_add_i32 m0, s67, 0x2000
	s_nop 0
	global_load_lds_dwordx4 v176, s[90:91]
	s_mov_b32 m0, s28
	s_nop 0
	global_load_lds_dwordx4 v182, s[86:87]
	s_mov_b32 m0, s29
	s_nop 0
	global_load_lds_dwordx4 v178, s[86:87]
	s_waitcnt vmcnt(8)
	s_waitcnt lgkmcnt(0)
	s_barrier
	s_waitcnt lgkmcnt(0)
	v_mfma_f32_16x16x32_bf16 v[60:63], v[64:67], v[160:163], v[60:63]
	v_mfma_f32_16x16x32_bf16 v[60:63], v[68:71], v[164:167], v[60:63]
	v_mfma_f32_16x16x32_bf16 v[52:55], v[80:83], v[160:163], v[52:55]
	v_mfma_f32_16x16x32_bf16 v[52:55], v[116:119], v[164:167], v[52:55]
	v_mfma_f32_16x16x32_bf16 v[56:59], v[72:75], v[160:163], v[56:59]
	v_mfma_f32_16x16x32_bf16 v[56:59], v[76:79], v[164:167], v[56:59]
	v_mfma_f32_16x16x32_bf16 v[48:51], v[152:155], v[160:163], v[48:51]
	v_mfma_f32_16x16x32_bf16 v[48:51], v[156:159], v[164:167], v[48:51]
	v_mfma_f32_16x16x32_bf16 v[44:47], v[64:67], v[168:171], v[44:47]
	v_mfma_f32_16x16x32_bf16 v[44:47], v[68:71], v[172:175], v[44:47]
	v_mfma_f32_16x16x32_bf16 v[36:39], v[80:83], v[168:171], v[36:39]
	v_mfma_f32_16x16x32_bf16 v[36:39], v[116:119], v[172:175], v[36:39]
	v_mfma_f32_16x16x32_bf16 v[40:43], v[72:75], v[168:171], v[40:43]
	v_mfma_f32_16x16x32_bf16 v[40:43], v[76:79], v[172:175], v[40:43]
	v_mfma_f32_16x16x32_bf16 v[32:35], v[152:155], v[168:171], v[32:35]
	v_mfma_f32_16x16x32_bf16 v[32:35], v[156:159], v[172:175], v[32:35]
	v_mfma_f32_16x16x32_bf16 v[28:31], v[64:67], v[194:197], v[28:31]
	v_mfma_f32_16x16x32_bf16 v[28:31], v[68:71], v[198:201], v[28:31]
	v_mfma_f32_16x16x32_bf16 v[20:23], v[80:83], v[194:197], v[20:23]
	v_mfma_f32_16x16x32_bf16 v[20:23], v[116:119], v[198:201], v[20:23]
	v_mfma_f32_16x16x32_bf16 v[24:27], v[72:75], v[194:197], v[24:27]
	v_mfma_f32_16x16x32_bf16 v[24:27], v[76:79], v[198:201], v[24:27]
	v_mfma_f32_16x16x32_bf16 v[16:19], v[152:155], v[194:197], v[16:19]
	v_mfma_f32_16x16x32_bf16 v[16:19], v[156:159], v[198:201], v[16:19]
	v_mfma_f32_16x16x32_bf16 v[12:15], v[64:67], v[202:205], v[12:15]
	v_mfma_f32_16x16x32_bf16 v[12:15], v[68:71], v[206:209], v[12:15]
	v_mfma_f32_16x16x32_bf16 v[4:7], v[80:83], v[202:205], v[4:7]
	v_mfma_f32_16x16x32_bf16 v[4:7], v[116:119], v[206:209], v[4:7]
	v_mfma_f32_16x16x32_bf16 v[8:11], v[72:75], v[202:205], v[8:11]
	v_mfma_f32_16x16x32_bf16 v[8:11], v[76:79], v[206:209], v[8:11]
	v_mfma_f32_16x16x32_bf16 v[0:3], v[152:155], v[202:205], v[0:3]
	v_mfma_f32_16x16x32_bf16 v[0:3], v[156:159], v[206:209], v[0:3]
	s_barrier
	s_add_i32 s67, 0, 0x18000
	s_add_i32 s89, 0, 0x1c000
	v_add_u32_e32 v76, s67, v192
	v_add_u32_e32 v156, s89, v192
	ds_read_b128 v[64:67], v76
	ds_read_b128 v[68:71], v76 offset:1024
	ds_read_b128 v[72:75], v76 offset:2048
	ds_read_b128 v[76:79], v76 offset:3072
	ds_read_b128 v[80:83], v156
	ds_read_b128 v[116:119], v156 offset:1024
	ds_read_b128 v[152:155], v156 offset:2048
	ds_read_b128 v[156:159], v156 offset:3072
	s_add_u32 s86, s86, 0x80000
	s_addc_u32 s87, s87, 0
	s_mov_b32 m0, s34
	ds_read_b128 v[160:163], v193 offset:32768
	ds_read_b128 v[164:167], v193 offset:33792
	ds_read_b128 v[168:171], v193 offset:34816
	ds_read_b128 v[172:175], v193 offset:35840
	ds_read_b128 v[194:197], v193 offset:36864
	ds_read_b128 v[198:201], v193 offset:37888
	ds_read_b128 v[202:205], v193 offset:38912
	ds_read_b128 v[206:209], v193 offset:39936
	global_load_lds_dwordx4 v182, s[86:87]
	s_mov_b32 m0, s35
	s_nop 0
	global_load_lds_dwordx4 v178, s[86:87]
	s_waitcnt vmcnt(8)
	s_waitcnt lgkmcnt(0)
	s_barrier
	s_waitcnt lgkmcnt(0)
	v_mfma_f32_16x16x32_bf16 v[148:151], v[64:67], v[160:163], v[148:151]
	v_mfma_f32_16x16x32_bf16 v[148:151], v[68:71], v[164:167], v[148:151]
	v_mfma_f32_16x16x32_bf16 v[140:143], v[80:83], v[160:163], v[140:143]
	v_mfma_f32_16x16x32_bf16 v[140:143], v[116:119], v[164:167], v[140:143]
	v_mfma_f32_16x16x32_bf16 v[144:147], v[72:75], v[160:163], v[144:147]
	v_mfma_f32_16x16x32_bf16 v[144:147], v[76:79], v[164:167], v[144:147]
	v_mfma_f32_16x16x32_bf16 v[136:139], v[152:155], v[160:163], v[136:139]
	v_mfma_f32_16x16x32_bf16 v[136:139], v[156:159], v[164:167], v[136:139]
	v_mfma_f32_16x16x32_bf16 v[132:135], v[64:67], v[168:171], v[132:135]
	v_mfma_f32_16x16x32_bf16 v[132:135], v[68:71], v[172:175], v[132:135]
	v_mfma_f32_16x16x32_bf16 v[124:127], v[80:83], v[168:171], v[124:127]
	v_mfma_f32_16x16x32_bf16 v[124:127], v[116:119], v[172:175], v[124:127]
	v_mfma_f32_16x16x32_bf16 v[128:131], v[72:75], v[168:171], v[128:131]
	v_mfma_f32_16x16x32_bf16 v[128:131], v[76:79], v[172:175], v[128:131]
	v_mfma_f32_16x16x32_bf16 v[120:123], v[152:155], v[168:171], v[120:123]
	v_mfma_f32_16x16x32_bf16 v[120:123], v[156:159], v[172:175], v[120:123]
	v_mfma_f32_16x16x32_bf16 v[112:115], v[64:67], v[194:197], v[112:115]
	v_mfma_f32_16x16x32_bf16 v[112:115], v[68:71], v[198:201], v[112:115]
	v_mfma_f32_16x16x32_bf16 v[104:107], v[80:83], v[194:197], v[104:107]
	v_mfma_f32_16x16x32_bf16 v[104:107], v[116:119], v[198:201], v[104:107]
	v_mfma_f32_16x16x32_bf16 v[108:111], v[72:75], v[194:197], v[108:111]
	v_mfma_f32_16x16x32_bf16 v[108:111], v[76:79], v[198:201], v[108:111]
	v_mfma_f32_16x16x32_bf16 v[100:103], v[152:155], v[194:197], v[100:103]
	v_mfma_f32_16x16x32_bf16 v[100:103], v[156:159], v[198:201], v[100:103]
	v_mfma_f32_16x16x32_bf16 v[96:99], v[64:67], v[202:205], v[96:99]
	v_mfma_f32_16x16x32_bf16 v[96:99], v[68:71], v[206:209], v[96:99]
	v_mfma_f32_16x16x32_bf16 v[88:91], v[80:83], v[202:205], v[88:91]
	v_mfma_f32_16x16x32_bf16 v[88:91], v[116:119], v[206:209], v[88:91]
	v_mfma_f32_16x16x32_bf16 v[92:95], v[72:75], v[202:205], v[92:95]
	v_mfma_f32_16x16x32_bf16 v[92:95], v[76:79], v[206:209], v[92:95]
	v_mfma_f32_16x16x32_bf16 v[84:87], v[152:155], v[202:205], v[84:87]
	v_mfma_f32_16x16x32_bf16 v[84:87], v[156:159], v[206:209], v[84:87]
	s_barrier
	s_add_i32 s67, s67, s24
	s_add_u32 s98, s84, 0x80
	s_addc_u32 s99, s85, 0
	s_mov_b32 m0, s67
	ds_read_b128 v[160:163], v193 offset:49152
	ds_read_b128 v[164:167], v193 offset:50176
	ds_read_b128 v[168:171], v193 offset:51200
	ds_read_b128 v[172:175], v193 offset:52224
	ds_read_b128 v[194:197], v193 offset:53248
	ds_read_b128 v[198:201], v193 offset:54272
	ds_read_b128 v[202:205], v193 offset:55296
	ds_read_b128 v[206:209], v193 offset:56320
	global_load_lds_dwordx4 v180, s[98:99]
	s_add_i32 m0, s67, 0x2000
	s_add_u32 s84, s84, 0x80080
	s_addc_u32 s85, s85, 0
	s_add_i32 s67, s89, s24
	global_load_lds_dwordx4 v176, s[98:99]
	s_mov_b32 m0, s67
	s_nop 0
	global_load_lds_dwordx4 v180, s[84:85]
	s_add_i32 m0, s67, 0x2000
	s_nop 0
	global_load_lds_dwordx4 v176, s[84:85]
	s_add_u32 s98, s86, 0xfff80080
	s_addc_u32 s99, s87, -1
	s_mov_b32 m0, s53
	s_nop 0
	global_load_lds_dwordx4 v182, s[98:99]
	s_mov_b32 m0, s54
	s_nop 0
	global_load_lds_dwordx4 v178, s[98:99]
	s_waitcnt vmcnt(8)
	s_waitcnt lgkmcnt(0)
	s_barrier
	s_waitcnt lgkmcnt(0)
	v_mfma_f32_16x16x32_bf16 v[60:63], v[64:67], v[160:163], v[60:63]
	v_mfma_f32_16x16x32_bf16 v[60:63], v[68:71], v[164:167], v[60:63]
	v_mfma_f32_16x16x32_bf16 v[52:55], v[80:83], v[160:163], v[52:55]
	v_mfma_f32_16x16x32_bf16 v[52:55], v[116:119], v[164:167], v[52:55]
	v_mfma_f32_16x16x32_bf16 v[56:59], v[72:75], v[160:163], v[56:59]
	v_mfma_f32_16x16x32_bf16 v[56:59], v[76:79], v[164:167], v[56:59]
	v_mfma_f32_16x16x32_bf16 v[48:51], v[152:155], v[160:163], v[48:51]
	v_mfma_f32_16x16x32_bf16 v[48:51], v[156:159], v[164:167], v[48:51]
	v_mfma_f32_16x16x32_bf16 v[44:47], v[64:67], v[168:171], v[44:47]
	v_mfma_f32_16x16x32_bf16 v[44:47], v[68:71], v[172:175], v[44:47]
	v_mfma_f32_16x16x32_bf16 v[36:39], v[80:83], v[168:171], v[36:39]
	v_mfma_f32_16x16x32_bf16 v[36:39], v[116:119], v[172:175], v[36:39]
	v_mfma_f32_16x16x32_bf16 v[40:43], v[72:75], v[168:171], v[40:43]
	v_mfma_f32_16x16x32_bf16 v[40:43], v[76:79], v[172:175], v[40:43]
	v_mfma_f32_16x16x32_bf16 v[32:35], v[152:155], v[168:171], v[32:35]
	v_mfma_f32_16x16x32_bf16 v[32:35], v[156:159], v[172:175], v[32:35]
	v_mfma_f32_16x16x32_bf16 v[28:31], v[64:67], v[194:197], v[28:31]
	v_mfma_f32_16x16x32_bf16 v[28:31], v[68:71], v[198:201], v[28:31]
	v_mfma_f32_16x16x32_bf16 v[20:23], v[80:83], v[194:197], v[20:23]
	v_mfma_f32_16x16x32_bf16 v[20:23], v[116:119], v[198:201], v[20:23]
	v_mfma_f32_16x16x32_bf16 v[24:27], v[72:75], v[194:197], v[24:27]
	v_mfma_f32_16x16x32_bf16 v[24:27], v[76:79], v[198:201], v[24:27]
	v_mfma_f32_16x16x32_bf16 v[16:19], v[152:155], v[194:197], v[16:19]
	v_mfma_f32_16x16x32_bf16 v[16:19], v[156:159], v[198:201], v[16:19]
	v_mfma_f32_16x16x32_bf16 v[12:15], v[64:67], v[202:205], v[12:15]
	v_mfma_f32_16x16x32_bf16 v[12:15], v[68:71], v[206:209], v[12:15]
	v_mfma_f32_16x16x32_bf16 v[4:7], v[80:83], v[202:205], v[4:7]
	v_mfma_f32_16x16x32_bf16 v[4:7], v[116:119], v[206:209], v[4:7]
	v_mfma_f32_16x16x32_bf16 v[8:11], v[72:75], v[202:205], v[8:11]
	v_mfma_f32_16x16x32_bf16 v[8:11], v[76:79], v[206:209], v[8:11]
	v_mfma_f32_16x16x32_bf16 v[0:3], v[152:155], v[202:205], v[0:3]
	v_mfma_f32_16x16x32_bf16 v[0:3], v[156:159], v[206:209], v[0:3]
	s_barrier
	s_add_i32 s88, s88, 2
	s_add_u32 s82, s82, 0x100
	s_addc_u32 s83, s83, 0
	s_add_u32 s75, s75, 0x100
	s_addc_u32 s81, s81, 0
	s_cmp_gt_u32 s88, 29
	s_cbranch_scc0 .LBB0_1190
	s_and_b64 vcc, exec, s[18:19]
	s_cbranch_vccz .LBB0_1193
	s_barrier

.LBB0_1289:
	s_lshl_b32 s80, s96, 8
	s_ashr_i32 s81, s80, 31
	s_lshl_b64 s[86:87], s[80:81], 2
	s_add_u32 s84, s84, s86
	s_addc_u32 s85, s85, s87
	s_add_i32 m0, s94, s41
	s_add_u32 s81, s82, 0x100
	global_load_lds_dwordx4 v239, s[84:85]
	s_addc_u32 s96, s83, 0
	s_cmp_eq_u32 s54, 5
	s_cselect_b32 vcc_lo, 66, -2
	s_bfe_u32 s86, s1, 0x20003
	s_cmp_eq_u32 s86, 3
	s_cselect_b32 s86, -8, 0
	s_cmp_eq_u32 s54, 5
	s_cselect_b32 s86, s86, 0
	s_add_i32 vcc_lo, vcc_lo, s86
	s_add_u32 s82, s78, 0x100
	s_addc_u32 s83, s79, 0
	s_add_i32 s94, 0, 0x10000
	s_cmpk_eq_i32 vcc_lo, 0x54
	s_cselect_b32 s87, s75, s83
	s_cselect_b32 s86, s74, s82
	s_cselect_b32 s85, s77, s96
	s_cselect_b32 s84, s76, s81
	s_add_i32 vcc_hi, 0, 0x14000
	v_add_u32_e32 v96, s94, v238
	v_add_u32_e32 v140, vcc_hi, v238
	ds_read_b128 v[64:67], v96
	ds_read_b128 v[72:75], v96 offset:1024
	ds_read_b128 v[88:91], v96 offset:2048
	ds_read_b128 v[96:99], v96 offset:3072
	ds_read_b128 v[108:111], v140
	ds_read_b128 v[116:119], v140 offset:1024
	ds_read_b128 v[128:131], v140 offset:2048
	ds_read_b128 v[140:143], v140 offset:3072
	s_add_i32 m0, s29, 0xc000
	ds_read_b128 v[152:155], v240
	ds_read_b128 v[156:159], v240 offset:1024
	ds_read_b128 v[160:163], v240 offset:2048
	ds_read_b128 v[164:167], v240 offset:3072
	ds_read_b128 v[168:171], v240 offset:4096
	ds_read_b128 v[180:183], v240 offset:5120
	ds_read_b128 v[184:187], v240 offset:6144
	ds_read_b128 v[188:191], v240 offset:7168
	global_load_lds_dwordx4 v230, s[78:79]
	s_add_i32 m0, s29, 0xe000
	s_nop 0
	global_load_lds_dwordx4 v232, s[78:79]
	s_waitcnt vmcnt(8)
	s_waitcnt lgkmcnt(0)
	s_barrier
	s_waitcnt lgkmcnt(0)
	v_mfma_f32_16x16x32_bf16 v[176:179], v[64:67], v[152:155], 0
	v_mfma_f32_16x16x32_bf16 v[176:179], v[72:75], v[156:159], v[176:179]
	v_mfma_f32_16x16x32_bf16 v[148:151], v[108:111], v[152:155], 0
	v_mfma_f32_16x16x32_bf16 v[148:151], v[116:119], v[156:159], v[148:151]
	v_mfma_f32_16x16x32_bf16 v[172:175], v[88:91], v[152:155], 0
	v_mfma_f32_16x16x32_bf16 v[172:175], v[96:99], v[156:159], v[172:175]
	v_mfma_f32_16x16x32_bf16 v[144:147], v[128:131], v[152:155], 0
	v_mfma_f32_16x16x32_bf16 v[144:147], v[140:143], v[156:159], v[144:147]
	v_mfma_f32_16x16x32_bf16 v[136:139], v[64:67], v[160:163], 0
	v_mfma_f32_16x16x32_bf16 v[136:139], v[72:75], v[164:167], v[136:139]
	v_mfma_f32_16x16x32_bf16 v[124:127], v[108:111], v[160:163], 0
	v_mfma_f32_16x16x32_bf16 v[124:127], v[116:119], v[164:167], v[124:127]
	v_mfma_f32_16x16x32_bf16 v[132:135], v[88:91], v[160:163], 0
	v_mfma_f32_16x16x32_bf16 v[132:135], v[96:99], v[164:167], v[132:135]
	v_mfma_f32_16x16x32_bf16 v[120:123], v[128:131], v[160:163], 0
	v_mfma_f32_16x16x32_bf16 v[120:123], v[140:143], v[164:167], v[120:123]
	v_mfma_f32_16x16x32_bf16 v[112:115], v[64:67], v[168:171], 0
	v_mfma_f32_16x16x32_bf16 v[112:115], v[72:75], v[180:183], v[112:115]
	v_mfma_f32_16x16x32_bf16 v[100:103], v[108:111], v[168:171], 0
	v_mfma_f32_16x16x32_bf16 v[100:103], v[116:119], v[180:183], v[100:103]
	v_mfma_f32_16x16x32_bf16 v[104:107], v[88:91], v[168:171], 0
	v_mfma_f32_16x16x32_bf16 v[104:107], v[96:99], v[180:183], v[104:107]
	v_mfma_f32_16x16x32_bf16 v[92:95], v[128:131], v[168:171], 0
	v_mfma_f32_16x16x32_bf16 v[92:95], v[140:143], v[180:183], v[92:95]
	v_mfma_f32_16x16x32_bf16 v[84:87], v[64:67], v[184:187], 0
	v_mfma_f32_16x16x32_bf16 v[84:87], v[72:75], v[188:191], v[84:87]
	v_mfma_f32_16x16x32_bf16 v[76:79], v[108:111], v[184:187], 0
	v_mfma_f32_16x16x32_bf16 v[76:79], v[116:119], v[188:191], v[76:79]
	v_mfma_f32_16x16x32_bf16 v[80:83], v[88:91], v[184:187], 0
	v_mfma_f32_16x16x32_bf16 v[80:83], v[96:99], v[188:191], v[80:83]
	v_mfma_f32_16x16x32_bf16 v[68:71], v[128:131], v[184:187], 0
	v_mfma_f32_16x16x32_bf16 v[68:71], v[140:143], v[188:191], v[68:71]
	s_barrier
	s_add_i32 s78, s94, s2
	s_mov_b32 m0, s78
	ds_read_b128 v[152:155], v240 offset:16384
	ds_read_b128 v[156:159], v240 offset:17408
	ds_read_b128 v[160:163], v240 offset:18432
	ds_read_b128 v[164:167], v240 offset:19456
	ds_read_b128 v[168:171], v240 offset:20480
	ds_read_b128 v[180:183], v240 offset:21504
	ds_read_b128 v[184:187], v240 offset:22528
	ds_read_b128 v[188:191], v240 offset:23552
	global_load_lds_dwordx4 v216, s[84:85]
	s_add_i32 m0, s78, 0x2000
	s_add_u32 s78, s84, 0x160000
	s_addc_u32 s79, s85, 0
	s_add_i32 s94, vcc_hi, s2
	global_load_lds_dwordx4 v228, s[84:85]
	s_mov_b32 m0, s94
	s_nop 0
	global_load_lds_dwordx4 v216, s[78:79]
	s_add_i32 m0, s94, 0x2000
	s_nop 0
	global_load_lds_dwordx4 v228, s[78:79]
	s_mov_b32 m0, s29
	s_nop 0
	global_load_lds_dwordx4 v224, s[86:87]
	s_mov_b32 m0, s34
	s_nop 0
	global_load_lds_dwordx4 v226, s[86:87]
	s_waitcnt vmcnt(8)
	s_waitcnt lgkmcnt(0)
	s_barrier
	s_waitcnt lgkmcnt(0)
	v_mfma_f32_16x16x32_bf16 v[60:63], v[64:67], v[152:155], 0
	v_mfma_f32_16x16x32_bf16 v[60:63], v[72:75], v[156:159], v[60:63]
	v_mfma_f32_16x16x32_bf16 v[52:55], v[108:111], v[152:155], 0
	v_mfma_f32_16x16x32_bf16 v[52:55], v[116:119], v[156:159], v[52:55]
	v_mfma_f32_16x16x32_bf16 v[56:59], v[88:91], v[152:155], 0
	v_mfma_f32_16x16x32_bf16 v[56:59], v[96:99], v[156:159], v[56:59]
	v_mfma_f32_16x16x32_bf16 v[48:51], v[128:131], v[152:155], 0
	v_mfma_f32_16x16x32_bf16 v[48:51], v[140:143], v[156:159], v[48:51]
	v_mfma_f32_16x16x32_bf16 v[44:47], v[64:67], v[160:163], 0
	v_mfma_f32_16x16x32_bf16 v[44:47], v[72:75], v[164:167], v[44:47]
	v_mfma_f32_16x16x32_bf16 v[36:39], v[108:111], v[160:163], 0
	v_mfma_f32_16x16x32_bf16 v[36:39], v[116:119], v[164:167], v[36:39]
	v_mfma_f32_16x16x32_bf16 v[40:43], v[88:91], v[160:163], 0
	v_mfma_f32_16x16x32_bf16 v[40:43], v[96:99], v[164:167], v[40:43]
	v_mfma_f32_16x16x32_bf16 v[32:35], v[128:131], v[160:163], 0
	v_mfma_f32_16x16x32_bf16 v[32:35], v[140:143], v[164:167], v[32:35]
	v_mfma_f32_16x16x32_bf16 v[28:31], v[64:67], v[168:171], 0
	v_mfma_f32_16x16x32_bf16 v[28:31], v[72:75], v[180:183], v[28:31]
	v_mfma_f32_16x16x32_bf16 v[20:23], v[108:111], v[168:171], 0
	v_mfma_f32_16x16x32_bf16 v[20:23], v[116:119], v[180:183], v[20:23]
	v_mfma_f32_16x16x32_bf16 v[24:27], v[88:91], v[168:171], 0
	v_mfma_f32_16x16x32_bf16 v[24:27], v[96:99], v[180:183], v[24:27]
	v_mfma_f32_16x16x32_bf16 v[16:19], v[128:131], v[168:171], 0
	v_mfma_f32_16x16x32_bf16 v[16:19], v[140:143], v[180:183], v[16:19]
	v_mfma_f32_16x16x32_bf16 v[12:15], v[64:67], v[184:187], 0
	v_mfma_f32_16x16x32_bf16 v[12:15], v[72:75], v[188:191], v[12:15]
	v_mfma_f32_16x16x32_bf16 v[4:7], v[108:111], v[184:187], 0
	v_mfma_f32_16x16x32_bf16 v[4:7], v[116:119], v[188:191], v[4:7]
	v_mfma_f32_16x16x32_bf16 v[8:11], v[88:91], v[184:187], 0
	v_mfma_f32_16x16x32_bf16 v[8:11], v[96:99], v[188:191], v[8:11]
	v_mfma_f32_16x16x32_bf16 v[0:3], v[128:131], v[184:187], 0
	v_mfma_f32_16x16x32_bf16 v[0:3], v[140:143], v[188:191], v[0:3]
	s_barrier
	s_add_i32 s94, 0, 0x18000
	s_add_i32 vcc_hi, 0, 0x1c000
	v_add_u32_e32 v96, s94, v238
	v_add_u32_e32 v140, vcc_hi, v238
	ds_read_b128 v[64:67], v96
	ds_read_b128 v[72:75], v96 offset:1024
	ds_read_b128 v[88:91], v96 offset:2048
	ds_read_b128 v[96:99], v96 offset:3072
	ds_read_b128 v[108:111], v140
	ds_read_b128 v[116:119], v140 offset:1024
	ds_read_b128 v[128:131], v140 offset:2048
	ds_read_b128 v[140:143], v140 offset:3072
	s_add_u32 s78, s86, 0x160000
	s_addc_u32 s79, s87, 0
	s_mov_b32 m0, s35
	ds_read_b128 v[152:155], v240 offset:32768
	ds_read_b128 v[156:159], v240 offset:33792
	ds_read_b128 v[160:163], v240 offset:34816
	ds_read_b128 v[164:167], v240 offset:35840
	ds_read_b128 v[168:171], v240 offset:36864
	ds_read_b128 v[180:183], v240 offset:37888
	ds_read_b128 v[184:187], v240 offset:38912
	ds_read_b128 v[188:191], v240 offset:39936
	global_load_lds_dwordx4 v224, s[78:79]
	s_mov_b32 m0, s38
	s_nop 0
	global_load_lds_dwordx4 v226, s[78:79]
	s_waitcnt vmcnt(8)
	s_waitcnt lgkmcnt(0)
	s_barrier
	s_waitcnt lgkmcnt(0)
	v_mfma_f32_16x16x32_bf16 v[176:179], v[64:67], v[152:155], v[176:179]
	v_mfma_f32_16x16x32_bf16 v[176:179], v[72:75], v[156:159], v[176:179]
	v_mfma_f32_16x16x32_bf16 v[148:151], v[108:111], v[152:155], v[148:151]
	v_mfma_f32_16x16x32_bf16 v[148:151], v[116:119], v[156:159], v[148:151]
	v_mfma_f32_16x16x32_bf16 v[172:175], v[88:91], v[152:155], v[172:175]
	v_mfma_f32_16x16x32_bf16 v[172:175], v[96:99], v[156:159], v[172:175]
	v_mfma_f32_16x16x32_bf16 v[144:147], v[128:131], v[152:155], v[144:147]
	v_mfma_f32_16x16x32_bf16 v[144:147], v[140:143], v[156:159], v[144:147]
	v_mfma_f32_16x16x32_bf16 v[136:139], v[64:67], v[160:163], v[136:139]
	v_mfma_f32_16x16x32_bf16 v[136:139], v[72:75], v[164:167], v[136:139]
	v_mfma_f32_16x16x32_bf16 v[124:127], v[108:111], v[160:163], v[124:127]
	v_mfma_f32_16x16x32_bf16 v[124:127], v[116:119], v[164:167], v[124:127]
	v_mfma_f32_16x16x32_bf16 v[132:135], v[88:91], v[160:163], v[132:135]
	v_mfma_f32_16x16x32_bf16 v[132:135], v[96:99], v[164:167], v[132:135]
	v_mfma_f32_16x16x32_bf16 v[120:123], v[128:131], v[160:163], v[120:123]
	v_mfma_f32_16x16x32_bf16 v[120:123], v[140:143], v[164:167], v[120:123]
	v_mfma_f32_16x16x32_bf16 v[112:115], v[64:67], v[168:171], v[112:115]
	v_mfma_f32_16x16x32_bf16 v[112:115], v[72:75], v[180:183], v[112:115]
	v_mfma_f32_16x16x32_bf16 v[100:103], v[108:111], v[168:171], v[100:103]
	v_mfma_f32_16x16x32_bf16 v[100:103], v[116:119], v[180:183], v[100:103]
	v_mfma_f32_16x16x32_bf16 v[104:107], v[88:91], v[168:171], v[104:107]
	v_mfma_f32_16x16x32_bf16 v[104:107], v[96:99], v[180:183], v[104:107]
	v_mfma_f32_16x16x32_bf16 v[92:95], v[128:131], v[168:171], v[92:95]
	v_mfma_f32_16x16x32_bf16 v[92:95], v[140:143], v[180:183], v[92:95]
	v_mfma_f32_16x16x32_bf16 v[84:87], v[64:67], v[184:187], v[84:87]
	v_mfma_f32_16x16x32_bf16 v[84:87], v[72:75], v[188:191], v[84:87]
	v_mfma_f32_16x16x32_bf16 v[76:79], v[108:111], v[184:187], v[76:79]
	v_mfma_f32_16x16x32_bf16 v[76:79], v[116:119], v[188:191], v[76:79]
	v_mfma_f32_16x16x32_bf16 v[80:83], v[88:91], v[184:187], v[80:83]
	v_mfma_f32_16x16x32_bf16 v[80:83], v[96:99], v[188:191], v[80:83]
	v_mfma_f32_16x16x32_bf16 v[68:71], v[128:131], v[184:187], v[68:71]
	v_mfma_f32_16x16x32_bf16 v[68:71], v[140:143], v[188:191], v[68:71]
	s_barrier
	s_add_i32 s78, s94, s2
	s_add_u32 s98, s84, 0x80
	s_addc_u32 s99, s85, 0
	s_mov_b32 m0, s78
	ds_read_b128 v[152:155], v240 offset:49152
	ds_read_b128 v[156:159], v240 offset:50176
	ds_read_b128 v[160:163], v240 offset:51200
	ds_read_b128 v[164:167], v240 offset:52224
	ds_read_b128 v[168:171], v240 offset:53248
	ds_read_b128 v[180:183], v240 offset:54272
	ds_read_b128 v[184:187], v240 offset:55296
	ds_read_b128 v[188:191], v240 offset:56320
	global_load_lds_dwordx4 v216, s[98:99]
	s_add_i32 m0, s78, 0x2000
	s_add_u32 s78, s84, 0x160080
	s_addc_u32 s79, s85, 0
	s_add_i32 s84, vcc_hi, s2
	global_load_lds_dwordx4 v228, s[98:99]
	s_mov_b32 m0, s84
	s_nop 0
	global_load_lds_dwordx4 v216, s[78:79]
	s_add_i32 m0, s84, 0x2000
	s_nop 0
	global_load_lds_dwordx4 v228, s[78:79]
	s_add_u32 s98, s86, 0x80
	s_addc_u32 s99, s87, 0
	s_mov_b32 m0, s60
	s_nop 0
	global_load_lds_dwordx4 v224, s[98:99]
	s_mov_b32 m0, s61
	s_nop 0
	global_load_lds_dwordx4 v226, s[98:99]
	s_waitcnt vmcnt(8)
	s_waitcnt lgkmcnt(0)
	s_barrier
	s_waitcnt lgkmcnt(0)
	v_mfma_f32_16x16x32_bf16 v[60:63], v[64:67], v[152:155], v[60:63]
	v_mfma_f32_16x16x32_bf16 v[60:63], v[72:75], v[156:159], v[60:63]
	v_mfma_f32_16x16x32_bf16 v[52:55], v[108:111], v[152:155], v[52:55]
	v_mfma_f32_16x16x32_bf16 v[52:55], v[116:119], v[156:159], v[52:55]
	v_mfma_f32_16x16x32_bf16 v[56:59], v[88:91], v[152:155], v[56:59]
	v_mfma_f32_16x16x32_bf16 v[56:59], v[96:99], v[156:159], v[56:59]
	v_mfma_f32_16x16x32_bf16 v[48:51], v[128:131], v[152:155], v[48:51]
	v_mfma_f32_16x16x32_bf16 v[48:51], v[140:143], v[156:159], v[48:51]
	v_mfma_f32_16x16x32_bf16 v[44:47], v[64:67], v[160:163], v[44:47]
	v_mfma_f32_16x16x32_bf16 v[44:47], v[72:75], v[164:167], v[44:47]
	v_mfma_f32_16x16x32_bf16 v[36:39], v[108:111], v[160:163], v[36:39]
	v_mfma_f32_16x16x32_bf16 v[36:39], v[116:119], v[164:167], v[36:39]
	v_mfma_f32_16x16x32_bf16 v[40:43], v[88:91], v[160:163], v[40:43]
	v_mfma_f32_16x16x32_bf16 v[40:43], v[96:99], v[164:167], v[40:43]
	v_mfma_f32_16x16x32_bf16 v[32:35], v[128:131], v[160:163], v[32:35]
	v_mfma_f32_16x16x32_bf16 v[32:35], v[140:143], v[164:167], v[32:35]
	v_mfma_f32_16x16x32_bf16 v[28:31], v[64:67], v[168:171], v[28:31]
	v_mfma_f32_16x16x32_bf16 v[28:31], v[72:75], v[180:183], v[28:31]
	v_mfma_f32_16x16x32_bf16 v[20:23], v[108:111], v[168:171], v[20:23]
	v_mfma_f32_16x16x32_bf16 v[20:23], v[116:119], v[180:183], v[20:23]
	v_mfma_f32_16x16x32_bf16 v[24:27], v[88:91], v[168:171], v[24:27]
	v_mfma_f32_16x16x32_bf16 v[24:27], v[96:99], v[180:183], v[24:27]
	v_mfma_f32_16x16x32_bf16 v[16:19], v[128:131], v[168:171], v[16:19]
	v_mfma_f32_16x16x32_bf16 v[16:19], v[140:143], v[180:183], v[16:19]
	v_mfma_f32_16x16x32_bf16 v[12:15], v[64:67], v[184:187], v[12:15]
	v_mfma_f32_16x16x32_bf16 v[12:15], v[72:75], v[188:191], v[12:15]
	v_mfma_f32_16x16x32_bf16 v[4:7], v[108:111], v[184:187], v[4:7]
	v_mfma_f32_16x16x32_bf16 v[4:7], v[116:119], v[188:191], v[4:7]
	v_mfma_f32_16x16x32_bf16 v[8:11], v[88:91], v[184:187], v[8:11]
	v_mfma_f32_16x16x32_bf16 v[8:11], v[96:99], v[188:191], v[8:11]
	v_mfma_f32_16x16x32_bf16 v[0:3], v[128:131], v[184:187], v[0:3]
	v_mfma_f32_16x16x32_bf16 v[0:3], v[140:143], v[188:191], v[0:3]
	s_barrier
	s_add_i32 vcc_lo, vcc_lo, 2
	s_add_u32 s81, s81, 0x100
	s_addc_u32 s96, s96, 0
	s_mov_b64 s[78:79], s[82:83]
.LBB0_1290:
	s_add_u32 s82, s78, 0x100
	s_addc_u32 s83, s79, 0
	s_add_i32 s94, 0, 0x10000
	s_cmpk_eq_i32 vcc_lo, 0x54
	s_cselect_b32 s87, s75, s83
	s_cselect_b32 s86, s74, s82
	s_cselect_b32 s85, s77, s96
	s_cselect_b32 s84, s76, s81
	s_add_i32 vcc_hi, 0, 0x14000
	v_add_u32_e32 v96, s94, v238
	v_add_u32_e32 v140, vcc_hi, v238
	ds_read_b128 v[64:67], v96
	ds_read_b128 v[72:75], v96 offset:1024
	ds_read_b128 v[88:91], v96 offset:2048
	ds_read_b128 v[96:99], v96 offset:3072
	ds_read_b128 v[108:111], v140
	ds_read_b128 v[116:119], v140 offset:1024
	ds_read_b128 v[128:131], v140 offset:2048
	ds_read_b128 v[140:143], v140 offset:3072
	s_add_i32 m0, s29, 0xc000
	ds_read_b128 v[152:155], v240
	ds_read_b128 v[156:159], v240 offset:1024
	ds_read_b128 v[160:163], v240 offset:2048
	ds_read_b128 v[164:167], v240 offset:3072
	ds_read_b128 v[168:171], v240 offset:4096
	ds_read_b128 v[180:183], v240 offset:5120
	ds_read_b128 v[184:187], v240 offset:6144
	ds_read_b128 v[188:191], v240 offset:7168
	global_load_lds_dwordx4 v230, s[78:79]
	s_add_i32 m0, s29, 0xe000
	s_nop 0
	global_load_lds_dwordx4 v232, s[78:79]
	s_waitcnt vmcnt(8)
	s_waitcnt lgkmcnt(0)
	s_barrier
	s_waitcnt lgkmcnt(0)
	v_mfma_f32_16x16x32_bf16 v[176:179], v[64:67], v[152:155], v[176:179]
	v_mfma_f32_16x16x32_bf16 v[176:179], v[72:75], v[156:159], v[176:179]
	v_mfma_f32_16x16x32_bf16 v[148:151], v[108:111], v[152:155], v[148:151]
	v_mfma_f32_16x16x32_bf16 v[148:151], v[116:119], v[156:159], v[148:151]
	v_mfma_f32_16x16x32_bf16 v[172:175], v[88:91], v[152:155], v[172:175]
	v_mfma_f32_16x16x32_bf16 v[172:175], v[96:99], v[156:159], v[172:175]
	v_mfma_f32_16x16x32_bf16 v[144:147], v[128:131], v[152:155], v[144:147]
	v_mfma_f32_16x16x32_bf16 v[144:147], v[140:143], v[156:159], v[144:147]
	v_mfma_f32_16x16x32_bf16 v[136:139], v[64:67], v[160:163], v[136:139]
	v_mfma_f32_16x16x32_bf16 v[136:139], v[72:75], v[164:167], v[136:139]
	v_mfma_f32_16x16x32_bf16 v[124:127], v[108:111], v[160:163], v[124:127]
	v_mfma_f32_16x16x32_bf16 v[124:127], v[116:119], v[164:167], v[124:127]
	v_mfma_f32_16x16x32_bf16 v[132:135], v[88:91], v[160:163], v[132:135]
	v_mfma_f32_16x16x32_bf16 v[132:135], v[96:99], v[164:167], v[132:135]
	v_mfma_f32_16x16x32_bf16 v[120:123], v[128:131], v[160:163], v[120:123]
	v_mfma_f32_16x16x32_bf16 v[120:123], v[140:143], v[164:167], v[120:123]
	v_mfma_f32_16x16x32_bf16 v[112:115], v[64:67], v[168:171], v[112:115]
	v_mfma_f32_16x16x32_bf16 v[112:115], v[72:75], v[180:183], v[112:115]
	v_mfma_f32_16x16x32_bf16 v[100:103], v[108:111], v[168:171], v[100:103]
	v_mfma_f32_16x16x32_bf16 v[100:103], v[116:119], v[180:183], v[100:103]
	v_mfma_f32_16x16x32_bf16 v[104:107], v[88:91], v[168:171], v[104:107]
	v_mfma_f32_16x16x32_bf16 v[104:107], v[96:99], v[180:183], v[104:107]
	v_mfma_f32_16x16x32_bf16 v[92:95], v[128:131], v[168:171], v[92:95]
	v_mfma_f32_16x16x32_bf16 v[92:95], v[140:143], v[180:183], v[92:95]
	v_mfma_f32_16x16x32_bf16 v[84:87], v[64:67], v[184:187], v[84:87]
	v_mfma_f32_16x16x32_bf16 v[84:87], v[72:75], v[188:191], v[84:87]
	v_mfma_f32_16x16x32_bf16 v[76:79], v[108:111], v[184:187], v[76:79]
	v_mfma_f32_16x16x32_bf16 v[76:79], v[116:119], v[188:191], v[76:79]
	v_mfma_f32_16x16x32_bf16 v[80:83], v[88:91], v[184:187], v[80:83]
	v_mfma_f32_16x16x32_bf16 v[80:83], v[96:99], v[188:191], v[80:83]
	v_mfma_f32_16x16x32_bf16 v[68:71], v[128:131], v[184:187], v[68:71]
	v_mfma_f32_16x16x32_bf16 v[68:71], v[140:143], v[188:191], v[68:71]
	s_barrier
	s_add_i32 s78, s94, s2
	s_mov_b32 m0, s78
	ds_read_b128 v[152:155], v240 offset:16384
	ds_read_b128 v[156:159], v240 offset:17408
	ds_read_b128 v[160:163], v240 offset:18432
	ds_read_b128 v[164:167], v240 offset:19456
	ds_read_b128 v[168:171], v240 offset:20480
	ds_read_b128 v[180:183], v240 offset:21504
	ds_read_b128 v[184:187], v240 offset:22528
	ds_read_b128 v[188:191], v240 offset:23552
	global_load_lds_dwordx4 v216, s[84:85]
	s_add_i32 m0, s78, 0x2000
	s_add_u32 s78, s84, 0x160000
	s_addc_u32 s79, s85, 0
	s_add_i32 s94, vcc_hi, s2
	global_load_lds_dwordx4 v228, s[84:85]
	s_mov_b32 m0, s94
	s_nop 0
	global_load_lds_dwordx4 v216, s[78:79]
	s_add_i32 m0, s94, 0x2000
	s_nop 0
	global_load_lds_dwordx4 v228, s[78:79]
	s_mov_b32 m0, s29
	s_nop 0
	global_load_lds_dwordx4 v224, s[86:87]
	s_mov_b32 m0, s34
	s_nop 0
	global_load_lds_dwordx4 v226, s[86:87]
	s_waitcnt vmcnt(8)
	s_waitcnt lgkmcnt(0)
	s_barrier
	s_waitcnt lgkmcnt(0)
	v_mfma_f32_16x16x32_bf16 v[60:63], v[64:67], v[152:155], v[60:63]
	v_mfma_f32_16x16x32_bf16 v[60:63], v[72:75], v[156:159], v[60:63]
	v_mfma_f32_16x16x32_bf16 v[52:55], v[108:111], v[152:155], v[52:55]
	v_mfma_f32_16x16x32_bf16 v[52:55], v[116:119], v[156:159], v[52:55]
	v_mfma_f32_16x16x32_bf16 v[56:59], v[88:91], v[152:155], v[56:59]
	v_mfma_f32_16x16x32_bf16 v[56:59], v[96:99], v[156:159], v[56:59]
	v_mfma_f32_16x16x32_bf16 v[48:51], v[128:131], v[152:155], v[48:51]
	v_mfma_f32_16x16x32_bf16 v[48:51], v[140:143], v[156:159], v[48:51]
	v_mfma_f32_16x16x32_bf16 v[44:47], v[64:67], v[160:163], v[44:47]
	v_mfma_f32_16x16x32_bf16 v[44:47], v[72:75], v[164:167], v[44:47]
	v_mfma_f32_16x16x32_bf16 v[36:39], v[108:111], v[160:163], v[36:39]
	v_mfma_f32_16x16x32_bf16 v[36:39], v[116:119], v[164:167], v[36:39]
	v_mfma_f32_16x16x32_bf16 v[40:43], v[88:91], v[160:163], v[40:43]
	v_mfma_f32_16x16x32_bf16 v[40:43], v[96:99], v[164:167], v[40:43]
	v_mfma_f32_16x16x32_bf16 v[32:35], v[128:131], v[160:163], v[32:35]
	v_mfma_f32_16x16x32_bf16 v[32:35], v[140:143], v[164:167], v[32:35]
	v_mfma_f32_16x16x32_bf16 v[28:31], v[64:67], v[168:171], v[28:31]
	v_mfma_f32_16x16x32_bf16 v[28:31], v[72:75], v[180:183], v[28:31]
	v_mfma_f32_16x16x32_bf16 v[20:23], v[108:111], v[168:171], v[20:23]
	v_mfma_f32_16x16x32_bf16 v[20:23], v[116:119], v[180:183], v[20:23]
	v_mfma_f32_16x16x32_bf16 v[24:27], v[88:91], v[168:171], v[24:27]
	v_mfma_f32_16x16x32_bf16 v[24:27], v[96:99], v[180:183], v[24:27]
	v_mfma_f32_16x16x32_bf16 v[16:19], v[128:131], v[168:171], v[16:19]
	v_mfma_f32_16x16x32_bf16 v[16:19], v[140:143], v[180:183], v[16:19]
	v_mfma_f32_16x16x32_bf16 v[12:15], v[64:67], v[184:187], v[12:15]
	v_mfma_f32_16x16x32_bf16 v[12:15], v[72:75], v[188:191], v[12:15]
	v_mfma_f32_16x16x32_bf16 v[4:7], v[108:111], v[184:187], v[4:7]
	v_mfma_f32_16x16x32_bf16 v[4:7], v[116:119], v[188:191], v[4:7]
	v_mfma_f32_16x16x32_bf16 v[8:11], v[88:91], v[184:187], v[8:11]
	v_mfma_f32_16x16x32_bf16 v[8:11], v[96:99], v[188:191], v[8:11]
	v_mfma_f32_16x16x32_bf16 v[0:3], v[128:131], v[184:187], v[0:3]
	v_mfma_f32_16x16x32_bf16 v[0:3], v[140:143], v[188:191], v[0:3]
	s_barrier
	s_add_i32 s94, 0, 0x18000
	s_add_i32 vcc_hi, 0, 0x1c000
	v_add_u32_e32 v96, s94, v238
	v_add_u32_e32 v140, vcc_hi, v238
	ds_read_b128 v[64:67], v96
	ds_read_b128 v[72:75], v96 offset:1024
	ds_read_b128 v[88:91], v96 offset:2048
	ds_read_b128 v[96:99], v96 offset:3072
	ds_read_b128 v[108:111], v140
	ds_read_b128 v[116:119], v140 offset:1024
	ds_read_b128 v[128:131], v140 offset:2048
	ds_read_b128 v[140:143], v140 offset:3072
	s_add_u32 s78, s86, 0x160000
	s_addc_u32 s79, s87, 0
	s_mov_b32 m0, s35
	ds_read_b128 v[152:155], v240 offset:32768
	ds_read_b128 v[156:159], v240 offset:33792
	ds_read_b128 v[160:163], v240 offset:34816
	ds_read_b128 v[164:167], v240 offset:35840
	ds_read_b128 v[168:171], v240 offset:36864
	ds_read_b128 v[180:183], v240 offset:37888
	ds_read_b128 v[184:187], v240 offset:38912
	ds_read_b128 v[188:191], v240 offset:39936
	global_load_lds_dwordx4 v224, s[78:79]
	s_mov_b32 m0, s38
	s_nop 0
	global_load_lds_dwordx4 v226, s[78:79]
	s_waitcnt vmcnt(8)
	s_waitcnt lgkmcnt(0)
	s_barrier
	s_waitcnt lgkmcnt(0)
	v_mfma_f32_16x16x32_bf16 v[176:179], v[64:67], v[152:155], v[176:179]
	v_mfma_f32_16x16x32_bf16 v[176:179], v[72:75], v[156:159], v[176:179]
	v_mfma_f32_16x16x32_bf16 v[148:151], v[108:111], v[152:155], v[148:151]
	v_mfma_f32_16x16x32_bf16 v[148:151], v[116:119], v[156:159], v[148:151]
	v_mfma_f32_16x16x32_bf16 v[172:175], v[88:91], v[152:155], v[172:175]
	v_mfma_f32_16x16x32_bf16 v[172:175], v[96:99], v[156:159], v[172:175]
	v_mfma_f32_16x16x32_bf16 v[144:147], v[128:131], v[152:155], v[144:147]
	v_mfma_f32_16x16x32_bf16 v[144:147], v[140:143], v[156:159], v[144:147]
	v_mfma_f32_16x16x32_bf16 v[136:139], v[64:67], v[160:163], v[136:139]
	v_mfma_f32_16x16x32_bf16 v[136:139], v[72:75], v[164:167], v[136:139]
	v_mfma_f32_16x16x32_bf16 v[124:127], v[108:111], v[160:163], v[124:127]
	v_mfma_f32_16x16x32_bf16 v[124:127], v[116:119], v[164:167], v[124:127]
	v_mfma_f32_16x16x32_bf16 v[132:135], v[88:91], v[160:163], v[132:135]
	v_mfma_f32_16x16x32_bf16 v[132:135], v[96:99], v[164:167], v[132:135]
	v_mfma_f32_16x16x32_bf16 v[120:123], v[128:131], v[160:163], v[120:123]
	v_mfma_f32_16x16x32_bf16 v[120:123], v[140:143], v[164:167], v[120:123]
	v_mfma_f32_16x16x32_bf16 v[112:115], v[64:67], v[168:171], v[112:115]
	v_mfma_f32_16x16x32_bf16 v[112:115], v[72:75], v[180:183], v[112:115]
	v_mfma_f32_16x16x32_bf16 v[100:103], v[108:111], v[168:171], v[100:103]
	v_mfma_f32_16x16x32_bf16 v[100:103], v[116:119], v[180:183], v[100:103]
	v_mfma_f32_16x16x32_bf16 v[104:107], v[88:91], v[168:171], v[104:107]
	v_mfma_f32_16x16x32_bf16 v[104:107], v[96:99], v[180:183], v[104:107]
	v_mfma_f32_16x16x32_bf16 v[92:95], v[128:131], v[168:171], v[92:95]
	v_mfma_f32_16x16x32_bf16 v[92:95], v[140:143], v[180:183], v[92:95]
	v_mfma_f32_16x16x32_bf16 v[84:87], v[64:67], v[184:187], v[84:87]
	v_mfma_f32_16x16x32_bf16 v[84:87], v[72:75], v[188:191], v[84:87]
	v_mfma_f32_16x16x32_bf16 v[76:79], v[108:111], v[184:187], v[76:79]
	v_mfma_f32_16x16x32_bf16 v[76:79], v[116:119], v[188:191], v[76:79]
	v_mfma_f32_16x16x32_bf16 v[80:83], v[88:91], v[184:187], v[80:83]
	v_mfma_f32_16x16x32_bf16 v[80:83], v[96:99], v[188:191], v[80:83]
	v_mfma_f32_16x16x32_bf16 v[68:71], v[128:131], v[184:187], v[68:71]
	v_mfma_f32_16x16x32_bf16 v[68:71], v[140:143], v[188:191], v[68:71]
	s_barrier
	s_add_i32 s78, s94, s2
	s_add_u32 s98, s84, 0x80
	s_addc_u32 s99, s85, 0
	s_mov_b32 m0, s78
	ds_read_b128 v[152:155], v240 offset:49152
	ds_read_b128 v[156:159], v240 offset:50176
	ds_read_b128 v[160:163], v240 offset:51200
	ds_read_b128 v[164:167], v240 offset:52224
	ds_read_b128 v[168:171], v240 offset:53248
	ds_read_b128 v[180:183], v240 offset:54272
	ds_read_b128 v[184:187], v240 offset:55296
	ds_read_b128 v[188:191], v240 offset:56320
	global_load_lds_dwordx4 v216, s[98:99]
	s_add_i32 m0, s78, 0x2000
	s_add_u32 s78, s84, 0x160080
	s_addc_u32 s79, s85, 0
	s_add_i32 s84, vcc_hi, s2
	global_load_lds_dwordx4 v228, s[98:99]
	s_mov_b32 m0, s84
	s_nop 0
	global_load_lds_dwordx4 v216, s[78:79]
	s_add_i32 m0, s84, 0x2000
	s_nop 0
	global_load_lds_dwordx4 v228, s[78:79]
	s_add_u32 s98, s86, 0x80
	s_addc_u32 s99, s87, 0
	s_mov_b32 m0, s60
	s_nop 0
	global_load_lds_dwordx4 v224, s[98:99]
	s_mov_b32 m0, s61
	s_nop 0
	global_load_lds_dwordx4 v226, s[98:99]
	s_waitcnt vmcnt(8)
	s_waitcnt lgkmcnt(0)
	s_barrier
	s_waitcnt lgkmcnt(0)
	v_mfma_f32_16x16x32_bf16 v[60:63], v[64:67], v[152:155], v[60:63]
	v_mfma_f32_16x16x32_bf16 v[60:63], v[72:75], v[156:159], v[60:63]
	v_mfma_f32_16x16x32_bf16 v[52:55], v[108:111], v[152:155], v[52:55]
	v_mfma_f32_16x16x32_bf16 v[52:55], v[116:119], v[156:159], v[52:55]
	v_mfma_f32_16x16x32_bf16 v[56:59], v[88:91], v[152:155], v[56:59]
	v_mfma_f32_16x16x32_bf16 v[56:59], v[96:99], v[156:159], v[56:59]
	v_mfma_f32_16x16x32_bf16 v[48:51], v[128:131], v[152:155], v[48:51]
	v_mfma_f32_16x16x32_bf16 v[48:51], v[140:143], v[156:159], v[48:51]
	v_mfma_f32_16x16x32_bf16 v[44:47], v[64:67], v[160:163], v[44:47]
	v_mfma_f32_16x16x32_bf16 v[44:47], v[72:75], v[164:167], v[44:47]
	v_mfma_f32_16x16x32_bf16 v[36:39], v[108:111], v[160:163], v[36:39]
	v_mfma_f32_16x16x32_bf16 v[36:39], v[116:119], v[164:167], v[36:39]
	v_mfma_f32_16x16x32_bf16 v[40:43], v[88:91], v[160:163], v[40:43]
	v_mfma_f32_16x16x32_bf16 v[40:43], v[96:99], v[164:167], v[40:43]
	v_mfma_f32_16x16x32_bf16 v[32:35], v[128:131], v[160:163], v[32:35]
	v_mfma_f32_16x16x32_bf16 v[32:35], v[140:143], v[164:167], v[32:35]
	v_mfma_f32_16x16x32_bf16 v[28:31], v[64:67], v[168:171], v[28:31]
	v_mfma_f32_16x16x32_bf16 v[28:31], v[72:75], v[180:183], v[28:31]
	v_mfma_f32_16x16x32_bf16 v[20:23], v[108:111], v[168:171], v[20:23]
	v_mfma_f32_16x16x32_bf16 v[20:23], v[116:119], v[180:183], v[20:23]
	v_mfma_f32_16x16x32_bf16 v[24:27], v[88:91], v[168:171], v[24:27]
	v_mfma_f32_16x16x32_bf16 v[24:27], v[96:99], v[180:183], v[24:27]
	v_mfma_f32_16x16x32_bf16 v[16:19], v[128:131], v[168:171], v[16:19]
	v_mfma_f32_16x16x32_bf16 v[16:19], v[140:143], v[180:183], v[16:19]
	v_mfma_f32_16x16x32_bf16 v[12:15], v[64:67], v[184:187], v[12:15]
	v_mfma_f32_16x16x32_bf16 v[12:15], v[72:75], v[188:191], v[12:15]
	v_mfma_f32_16x16x32_bf16 v[4:7], v[108:111], v[184:187], v[4:7]
	v_mfma_f32_16x16x32_bf16 v[4:7], v[116:119], v[188:191], v[4:7]
	v_mfma_f32_16x16x32_bf16 v[8:11], v[88:91], v[184:187], v[8:11]
	v_mfma_f32_16x16x32_bf16 v[8:11], v[96:99], v[188:191], v[8:11]
	v_mfma_f32_16x16x32_bf16 v[0:3], v[128:131], v[184:187], v[0:3]
	v_mfma_f32_16x16x32_bf16 v[0:3], v[140:143], v[188:191], v[0:3]
	s_barrier
	s_add_i32 vcc_lo, vcc_lo, 2
	s_add_u32 s81, s81, 0x100
	s_addc_u32 s96, s96, 0
	s_cmpk_gt_u32 vcc_lo, 0x55
	s_mov_b64 s[78:79], s[82:83]
	s_cbranch_scc0 .LBB0_1290
	s_and_b64 vcc, exec, s[70:71]
	s_cbranch_vccz .LBB0_1293
	s_barrier
